# gelu in EpiIn/EpiUp: abs folded into fma source modifiers, select replaced by max + fma(-|v|,qe,max(v,0)) (6 fewer VALU slots per pair, bit-identical)
# speedup vs baseline: 1.0001x; 1.0001x over previous
; __device__ __forceinline__ f32x4 gelu4(f32x4 v) { f32x2 a = gelu_pk((f32x2){v[0], v[1]}), b = gelu_pk((f32x2){v[2], v[3]}); return (f32x4){a.x, a.y, b.x, b.y}; }
; __device__ __forceinline__ f32x2 gelu_pk(f32x2 v) {
;     const f32x2 av = __builtin_elementwise_abs(v), d = av * 0.2316418882f + 1.0f;
;     f32x2 t; t.x = __builtin_amdgcn_rcpf(d.x); t.y = __builtin_amdgcn_rcpf(d.y);
;     f32x2 q = t * 0.5307027145f + (-0.7265760135f); q = q * t + 0.7107068705f; q = q * t + (-0.142248368f); q = q * t + 0.127414796f; q = q * t;
;     const f32x2 s = (v * v) * (-0.72134752044f);
;     f32x2 e; e.x = __builtin_amdgcn_exp2f(s.x); e.y = __builtin_amdgcn_exp2f(s.y);
;     const f32x2 m = v * (q * e), r = v - m;
;     f32x2 o; o.x = v.x < 0.f ? m.x : r.x; o.y = v.y < 0.f ? m.y : r.y; return o;
;     __device__ __forceinline__ void operator()(f32x4 (&acc)[2][2][4][2], const Unit& u, int wr, int wc, int fr_, int fq_) const {
;     ...
;             for (int m = 0; m < 4; ++m) { const int row = row0 + ai * HALF + m * 16; const float rs = rstd[row]; bf16_t* rowp = base + (size_t)row * ld + col0;
;                 float s1 = 0.f, s2 = 0.f;
; #pragma unroll
;                 for (int bj = 0; bj < 2; ++bj) { f32x4 v0 = acc[ai][bj][m][0] * rs, v1 = acc[ai][bj][m][1] * rs;
;                     if (act) { v0 = gelu4(v0); v1 = gelu4(v1); }
.LBB0_354:
	s_lshl_b32 s6, s6, 8
	s_add_i32 s6, s6, s37
	v_add_u32_e32 v146, s6, v146
	v_readlane_b32 s6, v244, 38
	v_ashrrev_i32_e32 v147, 31, v146
	v_readlane_b32 s7, v244, 39
	v_cndmask_b32_e64 v150, 0, 1, s[14:15]
	s_andn2_b64 vcc, exec, s[14:15]
	v_lshl_add_u64 v[148:149], v[146:147], 2, s[6:7]
	global_load_dword v152, v[148:149], off
	global_load_dword v245, v[148:149], off offset:64
	global_load_dword v246, v[148:149], off offset:128
	global_load_dword v247, v[148:149], off offset:192
	global_load_dword v248, v[148:149], off offset:512
	global_load_dword v249, v[148:149], off offset:576
	global_load_dword v250, v[148:149], off offset:640
	global_load_dword v251, v[148:149], off offset:704
	v_cmp_ne_u32_e64 s[6:7], 1, v150
	s_waitcnt vmcnt(0)
	v_pk_mul_f32 v[126:127], v[126:127], v[152:153] op_sel_hi:[1,0]
	v_pk_mul_f32 v[150:151], v[124:125], v[152:153] op_sel_hi:[1,0]
	v_pk_mul_f32 v[122:123], v[122:123], v[152:153] op_sel_hi:[1,0]
	v_pk_mul_f32 v[124:125], v[120:121], v[152:153] op_sel_hi:[1,0]
	s_cbranch_vccnz .LBB0_356
	v_fma_f32 v120, |v150|, s90, 1.0
	v_fma_f32 v121, |v151|, s90, 1.0
	v_mov_b64_e32 v[154:155], s[94:95]
	v_rcp_f32_e32 v120, v120
	v_rcp_f32_e32 v121, v121
	v_pk_mul_f32 v[166:167], v[150:151], v[150:151]
	v_pk_mul_f32 v[166:167], v[166:167], s[18:19] op_sel_hi:[1,0]
	v_pk_fma_f32 v[164:165], v[120:121], s[92:93], v[154:155] op_sel_hi:[1,0,0]
	v_exp_f32_e32 v166, v166
	v_pk_fma_f32 v[164:165], v[120:121], v[164:165], s[96:97] op_sel_hi:[1,1,0]
	v_exp_f32_e32 v167, v167
	v_pk_fma_f32 v[164:165], v[120:121], v[164:165], s[16:17] op_sel_hi:[1,1,0]
	v_pk_fma_f32 v[164:165], v[120:121], v[164:165], s[84:85] op_sel_hi:[1,1,0]
	v_pk_mul_f32 v[120:121], v[120:121], v[164:165]
	v_pk_mul_f32 v[164:165], v[126:127], v[126:127]
	v_pk_mul_f32 v[120:121], v[166:167], v[120:121]
	v_pk_mul_f32 v[164:165], v[164:165], s[18:19] op_sel_hi:[1,0]
	v_max_f32_e32 v166, 0, v150
	v_max_f32_e32 v167, 0, v151
	v_exp_f32_e32 v164, v164
	v_fma_f32 v150, -|v150|, v120, v166
	v_fma_f32 v151, -|v151|, v121, v167
	v_exp_f32_e32 v165, v165
	v_fma_f32 v120, |v126|, s90, 1.0
	v_fma_f32 v121, |v127|, s90, 1.0
	v_rcp_f32_e32 v120, v120
	v_rcp_f32_e32 v121, v121
	s_nop 0
	v_pk_fma_f32 v[166:167], v[120:121], s[92:93], v[154:155] op_sel_hi:[1,0,0]
	v_pk_fma_f32 v[166:167], v[120:121], v[166:167], s[96:97] op_sel_hi:[1,1,0]
	v_pk_fma_f32 v[166:167], v[120:121], v[166:167], s[16:17] op_sel_hi:[1,1,0]
	v_pk_fma_f32 v[166:167], v[120:121], v[166:167], s[84:85] op_sel_hi:[1,1,0]
	v_pk_mul_f32 v[120:121], v[120:121], v[166:167]
	v_pk_mul_f32 v[166:167], v[124:125], v[124:125]
	v_pk_mul_f32 v[120:121], v[164:165], v[120:121]
	v_pk_mul_f32 v[166:167], v[166:167], s[18:19] op_sel_hi:[1,0]
	v_max_f32_e32 v164, 0, v126
	v_max_f32_e32 v165, 0, v127
	v_exp_f32_e32 v166, v166
	v_fma_f32 v126, -|v126|, v120, v164
	v_fma_f32 v127, -|v127|, v121, v165
	v_exp_f32_e32 v167, v167
	v_fma_f32 v120, |v124|, s90, 1.0
	v_fma_f32 v121, |v125|, s90, 1.0
	v_rcp_f32_e32 v120, v120
	v_rcp_f32_e32 v121, v121
	s_nop 0
	v_pk_fma_f32 v[164:165], v[120:121], s[92:93], v[154:155] op_sel_hi:[1,0,0]
	v_pk_fma_f32 v[164:165], v[120:121], v[164:165], s[96:97] op_sel_hi:[1,1,0]
	v_pk_fma_f32 v[164:165], v[120:121], v[164:165], s[16:17] op_sel_hi:[1,1,0]
	v_pk_fma_f32 v[164:165], v[120:121], v[164:165], s[84:85] op_sel_hi:[1,1,0]
	v_pk_mul_f32 v[120:121], v[120:121], v[164:165]
	v_pk_mul_f32 v[164:165], v[122:123], v[122:123]
	v_pk_mul_f32 v[120:121], v[166:167], v[120:121]
	v_max_f32_e32 v166, 0, v124
	v_max_f32_e32 v167, 0, v125
	v_fma_f32 v124, -|v124|, v120, v166
	v_fma_f32 v125, -|v125|, v121, v167
	s_nop 0
	v_fma_f32 v120, |v122|, s90, 1.0
	v_fma_f32 v121, |v123|, s90, 1.0
	v_rcp_f32_e32 v120, v120
	v_rcp_f32_e32 v121, v121
	s_nop 0
	v_pk_fma_f32 v[154:155], v[120:121], s[92:93], v[154:155] op_sel_hi:[1,0,0]
	v_pk_fma_f32 v[154:155], v[120:121], v[154:155], s[96:97] op_sel_hi:[1,1,0]
	v_pk_fma_f32 v[154:155], v[120:121], v[154:155], s[16:17] op_sel_hi:[1,1,0]
	v_pk_fma_f32 v[154:155], v[120:121], v[154:155], s[84:85] op_sel_hi:[1,1,0]
	v_pk_mul_f32 v[120:121], v[120:121], v[154:155]
	v_pk_mul_f32 v[154:155], v[164:165], s[18:19] op_sel_hi:[1,0]
	v_exp_f32_e32 v154, v154
	v_exp_f32_e32 v155, v155
	s_nop 0
	v_pk_mul_f32 v[120:121], v[154:155], v[120:121]
	v_max_f32_e32 v154, 0, v122
	v_max_f32_e32 v155, 0, v123
	v_fma_f32 v122, -|v122|, v120, v154
	v_fma_f32 v123, -|v123|, v121, v155
	s_nop 1
; __device__ __forceinline__ u32x4 pack8(f32x4 v0, f32x4 v1) { u32x4 w; w.x = cvt_pk_bf16(v0[0], v0[1]); w.y = cvt_pk_bf16(v0[2], v0[3]); w.z = cvt_pk_bf16(v1[0], v1[1]); w.w = cvt_pk_bf16(v1[2], v1[3]); return w; }
; __device__ __forceinline__ f32x4 gelu4(f32x4 v) { f32x2 a = gelu_pk((f32x2){v[0], v[1]}), b = gelu_pk((f32x2){v[2], v[3]}); return (f32x4){a.x, a.y, b.x, b.y}; }
; __device__ __forceinline__ f32x2 gelu_pk(f32x2 v) {
;     const f32x2 av = __builtin_elementwise_abs(v), d = av * 0.2316418882f + 1.0f;
;     f32x2 t; t.x = __builtin_amdgcn_rcpf(d.x); t.y = __builtin_amdgcn_rcpf(d.y);
;     f32x2 q = t * 0.5307027145f + (-0.7265760135f); q = q * t + 0.7107068705f; q = q * t + (-0.142248368f); q = q * t + 0.127414796f; q = q * t;
;     const f32x2 s = (v * v) * (-0.72134752044f);
;     f32x2 e; e.x = __builtin_amdgcn_exp2f(s.x); e.y = __builtin_amdgcn_exp2f(s.y);
;     const f32x2 m = v * (q * e), r = v - m;
;     f32x2 o; o.x = v.x < 0.f ? m.x : r.x; o.y = v.y < 0.f ? m.y : r.y; return o;
;     __device__ __forceinline__ void operator()(f32x4 (&acc)[2][2][4][2], const Unit& u, int wr, int wc, int fr_, int fq_) const {
;     ...
;             for (int m = 0; m < 4; ++m) { const int row = row0 + ai * HALF + m * 16; const float rs = rstd[row]; bf16_t* rowp = base + (size_t)row * ld + col0;
;                 float s1 = 0.f, s2 = 0.f;
; #pragma unroll
;                 for (int bj = 0; bj < 2; ++bj) { f32x4 v0 = acc[ai][bj][m][0] * rs, v1 = acc[ai][bj][m][1] * rs;
;                     if (act) { v0 = gelu4(v0); v1 = gelu4(v1); }
;                     s1 += ((v0[0] + v0[1]) + (v0[2] + v0[3])) + ((v1[0] + v1[1]) + (v1[2] + v1[3]));
;                     s2 += ((v0[0] * v0[0] + v0[1] * v0[1]) + (v0[2] * v0[2] + v0[3] * v0[3])) + ((v1[0] * v1[0] + v1[1] * v1[1]) + (v1[2] * v1[2] + v1[3] * v1[3]));
;                     *(u32x4*)(rowp + bj * HALF) = pack8(v0, v1); }
.LBB0_356:
	s_lshl_b32 s9, s9, 8
	s_or_b32 s9, s9, s38
	v_lshl_add_u32 v120, v163, 3, s9
	v_ashrrev_i32_e32 v121, 31, v120
	v_lshl_add_u64 v[120:121], v[120:121], 1, s[10:11]
	v_mul_lo_u32 v164, s87, v146
	v_mul_lo_u32 v165, s86, v147
	v_mad_u64_u32 v[154:155], s[10:11], s86, v146, 0
	v_add3_u32 v155, v155, v165, v164
	v_lshl_add_u64 v[154:155], v[154:155], 1, v[120:121]
	v_cvt_pk_bf16_f32 v164, v150, v151
	v_cvt_pk_bf16_f32 v165, v126, v127
	v_cvt_pk_bf16_f32 v166, v124, v125
	v_cvt_pk_bf16_f32 v167, v122, v123
	v_mov_b32_e32 v153, v152
	global_store_dwordx4 v[154:155], v[164:167], off
	v_pk_mul_f32 v[116:117], v[116:117], v[152:153]
	s_and_b64 vcc, exec, s[6:7]
	v_mov_b32_e32 v164, v152
	v_mov_b32_e32 v165, v152
	v_pk_mul_f32 v[118:119], v[118:119], v[164:165]
	v_pk_mul_f32 v[114:115], v[114:115], v[164:165]
	v_pk_mul_f32 v[112:113], v[112:113], v[152:153]
	s_cbranch_vccnz .LBB0_358
	v_fma_f32 v152, |v116|, s90, 1.0
	v_fma_f32 v153, |v117|, s90, 1.0
	v_mov_b64_e32 v[164:165], s[94:95]
	v_rcp_f32_e32 v152, v152
	v_rcp_f32_e32 v153, v153
	v_pk_mul_f32 v[168:169], v[116:117], v[116:117]
	v_pk_mul_f32 v[168:169], v[168:169], s[18:19] op_sel_hi:[1,0]
	v_pk_fma_f32 v[166:167], v[152:153], s[92:93], v[164:165] op_sel_hi:[1,0,0]
	v_exp_f32_e32 v168, v168
	v_pk_fma_f32 v[166:167], v[152:153], v[166:167], s[96:97] op_sel_hi:[1,1,0]
	v_exp_f32_e32 v169, v169
	v_pk_fma_f32 v[166:167], v[152:153], v[166:167], s[16:17] op_sel_hi:[1,1,0]
	v_pk_fma_f32 v[166:167], v[152:153], v[166:167], s[84:85] op_sel_hi:[1,1,0]
	v_pk_mul_f32 v[152:153], v[152:153], v[166:167]
	v_pk_mul_f32 v[166:167], v[118:119], v[118:119]
	v_pk_mul_f32 v[152:153], v[168:169], v[152:153]
	v_pk_mul_f32 v[166:167], v[166:167], s[18:19] op_sel_hi:[1,0]
	v_max_f32_e32 v168, 0, v116
	v_max_f32_e32 v169, 0, v117
	v_exp_f32_e32 v166, v166
	v_fma_f32 v116, -|v116|, v152, v168
	v_fma_f32 v117, -|v117|, v153, v169
	v_exp_f32_e32 v167, v167
	v_fma_f32 v152, |v118|, s90, 1.0
	v_fma_f32 v153, |v119|, s90, 1.0
	v_rcp_f32_e32 v152, v152
	v_rcp_f32_e32 v153, v153
	s_nop 0
	v_pk_fma_f32 v[168:169], v[152:153], s[92:93], v[164:165] op_sel_hi:[1,0,0]
	v_pk_fma_f32 v[168:169], v[152:153], v[168:169], s[96:97] op_sel_hi:[1,1,0]
	v_pk_fma_f32 v[168:169], v[152:153], v[168:169], s[16:17] op_sel_hi:[1,1,0]
	v_pk_fma_f32 v[168:169], v[152:153], v[168:169], s[84:85] op_sel_hi:[1,1,0]
	v_pk_mul_f32 v[152:153], v[152:153], v[168:169]
	v_pk_mul_f32 v[168:169], v[112:113], v[112:113]
	v_pk_mul_f32 v[152:153], v[166:167], v[152:153]
	v_pk_mul_f32 v[168:169], v[168:169], s[18:19] op_sel_hi:[1,0]
	v_max_f32_e32 v166, 0, v118
	v_max_f32_e32 v167, 0, v119
	v_exp_f32_e32 v168, v168
	v_fma_f32 v118, -|v118|, v152, v166
	v_fma_f32 v119, -|v119|, v153, v167
	v_exp_f32_e32 v169, v169
	v_fma_f32 v152, |v112|, s90, 1.0
	v_fma_f32 v153, |v113|, s90, 1.0
	v_rcp_f32_e32 v152, v152
	v_rcp_f32_e32 v153, v153
	s_nop 0
	v_pk_fma_f32 v[166:167], v[152:153], s[92:93], v[164:165] op_sel_hi:[1,0,0]
	v_pk_fma_f32 v[166:167], v[152:153], v[166:167], s[96:97] op_sel_hi:[1,1,0]
	v_pk_fma_f32 v[166:167], v[152:153], v[166:167], s[16:17] op_sel_hi:[1,1,0]
	v_pk_fma_f32 v[166:167], v[152:153], v[166:167], s[84:85] op_sel_hi:[1,1,0]
	v_pk_mul_f32 v[152:153], v[152:153], v[166:167]
	v_pk_mul_f32 v[166:167], v[114:115], v[114:115]
	v_pk_mul_f32 v[152:153], v[168:169], v[152:153]
	v_max_f32_e32 v168, 0, v112
	v_max_f32_e32 v169, 0, v113
	v_fma_f32 v112, -|v112|, v152, v168
	v_fma_f32 v113, -|v113|, v153, v169
	s_nop 0
	v_fma_f32 v152, |v114|, s90, 1.0
	v_fma_f32 v153, |v115|, s90, 1.0
	v_rcp_f32_e32 v152, v152
	v_rcp_f32_e32 v153, v153
	s_nop 0
	v_pk_fma_f32 v[164:165], v[152:153], s[92:93], v[164:165] op_sel_hi:[1,0,0]
	v_pk_fma_f32 v[164:165], v[152:153], v[164:165], s[96:97] op_sel_hi:[1,1,0]
	v_pk_fma_f32 v[164:165], v[152:153], v[164:165], s[16:17] op_sel_hi:[1,1,0]
	v_pk_fma_f32 v[164:165], v[152:153], v[164:165], s[84:85] op_sel_hi:[1,1,0]
	v_pk_mul_f32 v[152:153], v[152:153], v[164:165]
	v_pk_mul_f32 v[164:165], v[166:167], s[18:19] op_sel_hi:[1,0]
	v_exp_f32_e32 v164, v164
	v_exp_f32_e32 v165, v165
	s_nop 0
	v_pk_mul_f32 v[152:153], v[164:165], v[152:153]
	v_max_f32_e32 v164, 0, v114
	v_max_f32_e32 v165, 0, v115
	v_fma_f32 v114, -|v114|, v152, v164
	v_fma_f32 v115, -|v115|, v153, v165
	s_nop 1

; __device__ __forceinline__ f32x4 gelu4(f32x4 v) { f32x2 a = gelu_pk((f32x2){v[0], v[1]}), b = gelu_pk((f32x2){v[2], v[3]}); return (f32x4){a.x, a.y, b.x, b.y}; }
; __device__ __forceinline__ f32x2 gelu_pk(f32x2 v) {
;     const f32x2 av = __builtin_elementwise_abs(v), d = av * 0.2316418882f + 1.0f;
;     f32x2 t; t.x = __builtin_amdgcn_rcpf(d.x); t.y = __builtin_amdgcn_rcpf(d.y);
;     f32x2 q = t * 0.5307027145f + (-0.7265760135f); q = q * t + 0.7107068705f; q = q * t + (-0.142248368f); q = q * t + 0.127414796f; q = q * t;
;     const f32x2 s = (v * v) * (-0.72134752044f);
;     f32x2 e; e.x = __builtin_amdgcn_exp2f(s.x); e.y = __builtin_amdgcn_exp2f(s.y);
;     const f32x2 m = v * (q * e), r = v - m;
;     f32x2 o; o.x = v.x < 0.f ? m.x : r.x; o.y = v.y < 0.f ? m.y : r.y; return o;
;     __device__ __forceinline__ void operator()(f32x4 (&acc)[2][2][4][2], const Unit& u, int wr, int wc, int fr_, int fq_) const {
;     ...
;             for (int m = 0; m < 4; ++m) { const int row = row0 + ai * HALF + m * 16; const float rs = rstd[row]; bf16_t* rowp = base + (size_t)row * ld + col0;
;                 float s1 = 0.f, s2 = 0.f;
; #pragma unroll
;                 for (int bj = 0; bj < 2; ++bj) { f32x4 v0 = acc[ai][bj][m][0] * rs, v1 = acc[ai][bj][m][1] * rs;
;                     if (act) { v0 = gelu4(v0); v1 = gelu4(v1); }
.LBB0_362:
	v_mov_b32_e32 v114, v245
	s_and_b64 vcc, exec, s[6:7]
	s_waitcnt lgkmcnt(0)
	v_pk_mul_f32 v[110:111], v[110:111], v[114:115] op_sel_hi:[1,0]
	v_pk_mul_f32 v[108:109], v[108:109], v[114:115] op_sel_hi:[1,0]
	v_pk_mul_f32 v[106:107], v[106:107], v[114:115] op_sel_hi:[1,0]
	v_pk_mul_f32 v[104:105], v[104:105], v[114:115] op_sel_hi:[1,0]
	s_cbranch_vccnz .LBB0_364
	v_fma_f32 v112, |v108|, s90, 1.0
	v_fma_f32 v113, |v109|, s90, 1.0
	v_mov_b64_e32 v[116:117], s[94:95]
	v_rcp_f32_e32 v112, v112
	v_rcp_f32_e32 v113, v113
	v_pk_mul_f32 v[122:123], v[108:109], v[108:109]
	v_pk_mul_f32 v[122:123], v[122:123], s[18:19] op_sel_hi:[1,0]
	v_pk_fma_f32 v[118:119], v[112:113], s[92:93], v[116:117] op_sel_hi:[1,0,0]
	v_exp_f32_e32 v122, v122
	v_pk_fma_f32 v[118:119], v[112:113], v[118:119], s[96:97] op_sel_hi:[1,1,0]
	v_exp_f32_e32 v123, v123
	v_pk_fma_f32 v[118:119], v[112:113], v[118:119], s[16:17] op_sel_hi:[1,1,0]
	v_pk_fma_f32 v[118:119], v[112:113], v[118:119], s[84:85] op_sel_hi:[1,1,0]
	v_pk_mul_f32 v[112:113], v[112:113], v[118:119]
	v_pk_mul_f32 v[118:119], v[110:111], v[110:111]
	v_pk_mul_f32 v[112:113], v[122:123], v[112:113]
	v_pk_mul_f32 v[118:119], v[118:119], s[18:19] op_sel_hi:[1,0]
	v_max_f32_e32 v122, 0, v108
	v_max_f32_e32 v123, 0, v109
	v_exp_f32_e32 v118, v118
	v_fma_f32 v108, -|v108|, v112, v122
	v_fma_f32 v109, -|v109|, v113, v123
	v_exp_f32_e32 v119, v119
	v_fma_f32 v112, |v110|, s90, 1.0
	v_fma_f32 v113, |v111|, s90, 1.0
	v_rcp_f32_e32 v112, v112
	v_rcp_f32_e32 v113, v113
	s_nop 0
	v_pk_fma_f32 v[122:123], v[112:113], s[92:93], v[116:117] op_sel_hi:[1,0,0]
	v_pk_fma_f32 v[122:123], v[112:113], v[122:123], s[96:97] op_sel_hi:[1,1,0]
	v_pk_fma_f32 v[122:123], v[112:113], v[122:123], s[16:17] op_sel_hi:[1,1,0]
	v_pk_fma_f32 v[122:123], v[112:113], v[122:123], s[84:85] op_sel_hi:[1,1,0]
	v_pk_mul_f32 v[112:113], v[112:113], v[122:123]
	v_pk_mul_f32 v[122:123], v[104:105], v[104:105]
	v_pk_mul_f32 v[112:113], v[118:119], v[112:113]
	v_pk_mul_f32 v[122:123], v[122:123], s[18:19] op_sel_hi:[1,0]
	v_max_f32_e32 v118, 0, v110
	v_max_f32_e32 v119, 0, v111
	v_exp_f32_e32 v122, v122
	v_fma_f32 v110, -|v110|, v112, v118
	v_fma_f32 v111, -|v111|, v113, v119
	v_exp_f32_e32 v123, v123
	v_fma_f32 v112, |v104|, s90, 1.0
	v_fma_f32 v113, |v105|, s90, 1.0
	v_rcp_f32_e32 v112, v112
	v_rcp_f32_e32 v113, v113
	s_nop 0
	v_pk_fma_f32 v[118:119], v[112:113], s[92:93], v[116:117] op_sel_hi:[1,0,0]
	v_pk_fma_f32 v[118:119], v[112:113], v[118:119], s[96:97] op_sel_hi:[1,1,0]
	v_pk_fma_f32 v[118:119], v[112:113], v[118:119], s[16:17] op_sel_hi:[1,1,0]
	v_pk_fma_f32 v[118:119], v[112:113], v[118:119], s[84:85] op_sel_hi:[1,1,0]
	v_pk_mul_f32 v[112:113], v[112:113], v[118:119]
	v_pk_mul_f32 v[118:119], v[106:107], v[106:107]
	v_pk_mul_f32 v[112:113], v[122:123], v[112:113]
	v_max_f32_e32 v122, 0, v104
	v_max_f32_e32 v123, 0, v105
	v_fma_f32 v104, -|v104|, v112, v122
	v_fma_f32 v105, -|v105|, v113, v123
	s_nop 0
	v_fma_f32 v112, |v106|, s90, 1.0
	v_fma_f32 v113, |v107|, s90, 1.0
	v_rcp_f32_e32 v112, v112
	v_rcp_f32_e32 v113, v113
	s_nop 0
	v_pk_fma_f32 v[116:117], v[112:113], s[92:93], v[116:117] op_sel_hi:[1,0,0]
	v_pk_fma_f32 v[116:117], v[112:113], v[116:117], s[96:97] op_sel_hi:[1,1,0]
	v_pk_fma_f32 v[116:117], v[112:113], v[116:117], s[16:17] op_sel_hi:[1,1,0]
	v_pk_fma_f32 v[116:117], v[112:113], v[116:117], s[84:85] op_sel_hi:[1,1,0]
	v_pk_mul_f32 v[112:113], v[112:113], v[116:117]
	v_pk_mul_f32 v[116:117], v[118:119], s[18:19] op_sel_hi:[1,0]
	v_exp_f32_e32 v116, v116
	v_exp_f32_e32 v117, v117
	s_nop 0
	v_pk_mul_f32 v[112:113], v[116:117], v[112:113]
	v_max_f32_e32 v116, 0, v106
	v_max_f32_e32 v117, 0, v107
	v_fma_f32 v106, -|v106|, v112, v116
	v_fma_f32 v107, -|v107|, v113, v117
	s_nop 1
; __device__ __forceinline__ u32x4 pack8(f32x4 v0, f32x4 v1) { u32x4 w; w.x = cvt_pk_bf16(v0[0], v0[1]); w.y = cvt_pk_bf16(v0[2], v0[3]); w.z = cvt_pk_bf16(v1[0], v1[1]); w.w = cvt_pk_bf16(v1[2], v1[3]); return w; }
; __device__ __forceinline__ f32x4 gelu4(f32x4 v) { f32x2 a = gelu_pk((f32x2){v[0], v[1]}), b = gelu_pk((f32x2){v[2], v[3]}); return (f32x4){a.x, a.y, b.x, b.y}; }
; __device__ __forceinline__ f32x2 gelu_pk(f32x2 v) {
;     const f32x2 av = __builtin_elementwise_abs(v), d = av * 0.2316418882f + 1.0f;
;     f32x2 t; t.x = __builtin_amdgcn_rcpf(d.x); t.y = __builtin_amdgcn_rcpf(d.y);
;     f32x2 q = t * 0.5307027145f + (-0.7265760135f); q = q * t + 0.7107068705f; q = q * t + (-0.142248368f); q = q * t + 0.127414796f; q = q * t;
;     const f32x2 s = (v * v) * (-0.72134752044f);
;     f32x2 e; e.x = __builtin_amdgcn_exp2f(s.x); e.y = __builtin_amdgcn_exp2f(s.y);
;     const f32x2 m = v * (q * e), r = v - m;
;     f32x2 o; o.x = v.x < 0.f ? m.x : r.x; o.y = v.y < 0.f ? m.y : r.y; return o;
;     __device__ __forceinline__ void operator()(f32x4 (&acc)[2][2][4][2], const Unit& u, int wr, int wc, int fr_, int fq_) const {
;     ...
;             for (int m = 0; m < 4; ++m) { const int row = row0 + ai * HALF + m * 16; const float rs = rstd[row]; bf16_t* rowp = base + (size_t)row * ld + col0;
;                 float s1 = 0.f, s2 = 0.f;
; #pragma unroll
;                 for (int bj = 0; bj < 2; ++bj) { f32x4 v0 = acc[ai][bj][m][0] * rs, v1 = acc[ai][bj][m][1] * rs;
;                     if (act) { v0 = gelu4(v0); v1 = gelu4(v1); }
;                     s1 += ((v0[0] + v0[1]) + (v0[2] + v0[3])) + ((v1[0] + v1[1]) + (v1[2] + v1[3]));
;                     s2 += ((v0[0] * v0[0] + v0[1] * v0[1]) + (v0[2] * v0[2] + v0[3] * v0[3])) + ((v1[0] * v1[0] + v1[1] * v1[1]) + (v1[2] * v1[2] + v1[3] * v1[3]));
;                     *(u32x4*)(rowp + bj * HALF) = pack8(v0, v1); }
.LBB0_364:
	v_add_u32_e32 v112, 16, v146
	v_ashrrev_i32_e32 v113, 31, v112
	v_mul_lo_u32 v118, s86, v113
	v_mul_lo_u32 v119, s87, v112
	v_mad_u64_u32 v[116:117], s[10:11], s86, v112, 0
	v_mov_b32_e32 v115, v114
	v_add3_u32 v117, v117, v118, v119
	v_mov_b32_e32 v118, v114
	v_mov_b32_e32 v119, v114
	v_lshl_add_u64 v[116:117], v[116:117], 1, v[120:121]
	v_cvt_pk_bf16_f32 v122, v108, v109
	v_cvt_pk_bf16_f32 v123, v110, v111
	v_cvt_pk_bf16_f32 v124, v104, v105
	v_cvt_pk_bf16_f32 v125, v106, v107
	v_pk_mul_f32 v[102:103], v[102:103], v[118:119]
	v_pk_mul_f32 v[100:101], v[100:101], v[114:115]
	v_pk_mul_f32 v[98:99], v[98:99], v[118:119]
	s_and_b64 vcc, exec, s[6:7]
	v_pk_mul_f32 v[96:97], v[96:97], v[114:115]
	global_store_dwordx4 v[116:117], v[122:125], off
	s_cbranch_vccnz .LBB0_366
	v_fma_f32 v114, |v100|, s90, 1.0
	v_fma_f32 v115, |v101|, s90, 1.0
	v_mov_b64_e32 v[118:119], s[94:95]
	v_rcp_f32_e32 v114, v114
	v_rcp_f32_e32 v115, v115
	v_pk_mul_f32 v[124:125], v[100:101], v[100:101]
	v_pk_mul_f32 v[124:125], v[124:125], s[18:19] op_sel_hi:[1,0]
	v_pk_fma_f32 v[122:123], v[114:115], s[92:93], v[118:119] op_sel_hi:[1,0,0]
	v_exp_f32_e32 v124, v124
	v_pk_fma_f32 v[122:123], v[114:115], v[122:123], s[96:97] op_sel_hi:[1,1,0]
	v_exp_f32_e32 v125, v125
	v_pk_fma_f32 v[122:123], v[114:115], v[122:123], s[16:17] op_sel_hi:[1,1,0]
	v_pk_fma_f32 v[122:123], v[114:115], v[122:123], s[84:85] op_sel_hi:[1,1,0]
	v_pk_mul_f32 v[114:115], v[114:115], v[122:123]
	v_pk_mul_f32 v[122:123], v[102:103], v[102:103]
	v_pk_mul_f32 v[114:115], v[124:125], v[114:115]
	v_pk_mul_f32 v[122:123], v[122:123], s[18:19] op_sel_hi:[1,0]
	v_max_f32_e32 v124, 0, v100
	v_max_f32_e32 v125, 0, v101
	v_exp_f32_e32 v122, v122
	v_fma_f32 v100, -|v100|, v114, v124
	v_fma_f32 v101, -|v101|, v115, v125
	v_exp_f32_e32 v123, v123
	v_fma_f32 v114, |v102|, s90, 1.0
	v_fma_f32 v115, |v103|, s90, 1.0
	v_rcp_f32_e32 v114, v114
	v_rcp_f32_e32 v115, v115
	s_nop 0
	v_pk_fma_f32 v[124:125], v[114:115], s[92:93], v[118:119] op_sel_hi:[1,0,0]
	v_pk_fma_f32 v[124:125], v[114:115], v[124:125], s[96:97] op_sel_hi:[1,1,0]
	v_pk_fma_f32 v[124:125], v[114:115], v[124:125], s[16:17] op_sel_hi:[1,1,0]
	v_pk_fma_f32 v[124:125], v[114:115], v[124:125], s[84:85] op_sel_hi:[1,1,0]
	v_pk_mul_f32 v[114:115], v[114:115], v[124:125]
	v_pk_mul_f32 v[124:125], v[96:97], v[96:97]
	v_pk_mul_f32 v[114:115], v[122:123], v[114:115]
	v_pk_mul_f32 v[124:125], v[124:125], s[18:19] op_sel_hi:[1,0]
	v_max_f32_e32 v122, 0, v102
	v_max_f32_e32 v123, 0, v103
	v_exp_f32_e32 v124, v124
	v_fma_f32 v102, -|v102|, v114, v122
	v_fma_f32 v103, -|v103|, v115, v123
	v_exp_f32_e32 v125, v125
	v_fma_f32 v114, |v96|, s90, 1.0
	v_fma_f32 v115, |v97|, s90, 1.0
	v_rcp_f32_e32 v114, v114
	v_rcp_f32_e32 v115, v115
	s_nop 0
	v_pk_fma_f32 v[122:123], v[114:115], s[92:93], v[118:119] op_sel_hi:[1,0,0]
	v_pk_fma_f32 v[122:123], v[114:115], v[122:123], s[96:97] op_sel_hi:[1,1,0]
	v_pk_fma_f32 v[122:123], v[114:115], v[122:123], s[16:17] op_sel_hi:[1,1,0]
	v_pk_fma_f32 v[122:123], v[114:115], v[122:123], s[84:85] op_sel_hi:[1,1,0]
	v_pk_mul_f32 v[114:115], v[114:115], v[122:123]
	v_pk_mul_f32 v[122:123], v[98:99], v[98:99]
	v_pk_mul_f32 v[114:115], v[124:125], v[114:115]
	v_max_f32_e32 v124, 0, v96
	v_max_f32_e32 v125, 0, v97
	v_fma_f32 v96, -|v96|, v114, v124
	v_fma_f32 v97, -|v97|, v115, v125
	s_nop 0
	v_fma_f32 v114, |v98|, s90, 1.0
	v_fma_f32 v115, |v99|, s90, 1.0
	v_rcp_f32_e32 v114, v114
	v_rcp_f32_e32 v115, v115
	s_nop 0
	v_pk_fma_f32 v[118:119], v[114:115], s[92:93], v[118:119] op_sel_hi:[1,0,0]
	v_pk_fma_f32 v[118:119], v[114:115], v[118:119], s[96:97] op_sel_hi:[1,1,0]
	v_pk_fma_f32 v[118:119], v[114:115], v[118:119], s[16:17] op_sel_hi:[1,1,0]
	v_pk_fma_f32 v[118:119], v[114:115], v[118:119], s[84:85] op_sel_hi:[1,1,0]
	v_pk_mul_f32 v[114:115], v[114:115], v[118:119]
	v_pk_mul_f32 v[118:119], v[122:123], s[18:19] op_sel_hi:[1,0]
	v_exp_f32_e32 v118, v118
	v_exp_f32_e32 v119, v119
	s_nop 0
	v_pk_mul_f32 v[114:115], v[118:119], v[114:115]
	v_max_f32_e32 v118, 0, v98
	v_max_f32_e32 v119, 0, v99
	v_fma_f32 v98, -|v98|, v114, v118
	v_fma_f32 v99, -|v99|, v115, v119
	s_nop 1

; __device__ __forceinline__ f32x4 gelu4(f32x4 v) { f32x2 a = gelu_pk((f32x2){v[0], v[1]}), b = gelu_pk((f32x2){v[2], v[3]}); return (f32x4){a.x, a.y, b.x, b.y}; }
; __device__ __forceinline__ f32x2 gelu_pk(f32x2 v) {
;     const f32x2 av = __builtin_elementwise_abs(v), d = av * 0.2316418882f + 1.0f;
;     f32x2 t; t.x = __builtin_amdgcn_rcpf(d.x); t.y = __builtin_amdgcn_rcpf(d.y);
;     f32x2 q = t * 0.5307027145f + (-0.7265760135f); q = q * t + 0.7107068705f; q = q * t + (-0.142248368f); q = q * t + 0.127414796f; q = q * t;
;     const f32x2 s = (v * v) * (-0.72134752044f);
;     f32x2 e; e.x = __builtin_amdgcn_exp2f(s.x); e.y = __builtin_amdgcn_exp2f(s.y);
;     const f32x2 m = v * (q * e), r = v - m;
;     f32x2 o; o.x = v.x < 0.f ? m.x : r.x; o.y = v.y < 0.f ? m.y : r.y; return o;
;     __device__ __forceinline__ void operator()(f32x4 (&acc)[2][2][4][2], const Unit& u, int wr, int wc, int fr_, int fq_) const {
;     ...
;             for (int m = 0; m < 4; ++m) { const int row = row0 + ai * HALF + m * 16; const float rs = rstd[row]; bf16_t* rowp = base + (size_t)row * ld + col0;
;                 float s1 = 0.f, s2 = 0.f;
; #pragma unroll
;                 for (int bj = 0; bj < 2; ++bj) { f32x4 v0 = acc[ai][bj][m][0] * rs, v1 = acc[ai][bj][m][1] * rs;
;                     if (act) { v0 = gelu4(v0); v1 = gelu4(v1); }
.LBB0_370:
	v_mov_b32_e32 v98, v246
	s_and_b64 vcc, exec, s[6:7]
	s_waitcnt lgkmcnt(0)
	v_pk_mul_f32 v[94:95], v[94:95], v[98:99] op_sel_hi:[1,0]
	v_pk_mul_f32 v[92:93], v[92:93], v[98:99] op_sel_hi:[1,0]
	v_pk_mul_f32 v[90:91], v[90:91], v[98:99] op_sel_hi:[1,0]
	v_pk_mul_f32 v[88:89], v[88:89], v[98:99] op_sel_hi:[1,0]
	s_cbranch_vccnz .LBB0_372
	v_fma_f32 v96, |v92|, s90, 1.0
	v_fma_f32 v97, |v93|, s90, 1.0
	v_mov_b64_e32 v[100:101], s[94:95]
	v_rcp_f32_e32 v96, v96
	v_rcp_f32_e32 v97, v97
	v_pk_mul_f32 v[104:105], v[92:93], v[92:93]
	v_pk_mul_f32 v[104:105], v[104:105], s[18:19] op_sel_hi:[1,0]
	v_pk_fma_f32 v[102:103], v[96:97], s[92:93], v[100:101] op_sel_hi:[1,0,0]
	v_exp_f32_e32 v104, v104
	v_pk_fma_f32 v[102:103], v[96:97], v[102:103], s[96:97] op_sel_hi:[1,1,0]
	v_exp_f32_e32 v105, v105
	v_pk_fma_f32 v[102:103], v[96:97], v[102:103], s[16:17] op_sel_hi:[1,1,0]
	v_pk_fma_f32 v[102:103], v[96:97], v[102:103], s[84:85] op_sel_hi:[1,1,0]
	v_pk_mul_f32 v[96:97], v[96:97], v[102:103]
	v_pk_mul_f32 v[102:103], v[94:95], v[94:95]
	v_pk_mul_f32 v[96:97], v[104:105], v[96:97]
	v_pk_mul_f32 v[102:103], v[102:103], s[18:19] op_sel_hi:[1,0]
	v_max_f32_e32 v104, 0, v92
	v_max_f32_e32 v105, 0, v93
	v_exp_f32_e32 v102, v102
	v_fma_f32 v92, -|v92|, v96, v104
	v_fma_f32 v93, -|v93|, v97, v105
	v_exp_f32_e32 v103, v103
	v_fma_f32 v96, |v94|, s90, 1.0
	v_fma_f32 v97, |v95|, s90, 1.0
	v_rcp_f32_e32 v96, v96
	v_rcp_f32_e32 v97, v97
	s_nop 0
	v_pk_fma_f32 v[104:105], v[96:97], s[92:93], v[100:101] op_sel_hi:[1,0,0]
	v_pk_fma_f32 v[104:105], v[96:97], v[104:105], s[96:97] op_sel_hi:[1,1,0]
	v_pk_fma_f32 v[104:105], v[96:97], v[104:105], s[16:17] op_sel_hi:[1,1,0]
	v_pk_fma_f32 v[104:105], v[96:97], v[104:105], s[84:85] op_sel_hi:[1,1,0]
	v_pk_mul_f32 v[96:97], v[96:97], v[104:105]
	v_pk_mul_f32 v[104:105], v[88:89], v[88:89]
	v_pk_mul_f32 v[96:97], v[102:103], v[96:97]
	v_pk_mul_f32 v[104:105], v[104:105], s[18:19] op_sel_hi:[1,0]
	v_max_f32_e32 v102, 0, v94
	v_max_f32_e32 v103, 0, v95
	v_exp_f32_e32 v104, v104
	v_fma_f32 v94, -|v94|, v96, v102
	v_fma_f32 v95, -|v95|, v97, v103
	v_exp_f32_e32 v105, v105
	v_fma_f32 v96, |v88|, s90, 1.0
	v_fma_f32 v97, |v89|, s90, 1.0
	v_rcp_f32_e32 v96, v96
	v_rcp_f32_e32 v97, v97
	s_nop 0
	v_pk_fma_f32 v[102:103], v[96:97], s[92:93], v[100:101] op_sel_hi:[1,0,0]
	v_pk_fma_f32 v[102:103], v[96:97], v[102:103], s[96:97] op_sel_hi:[1,1,0]
	v_pk_fma_f32 v[102:103], v[96:97], v[102:103], s[16:17] op_sel_hi:[1,1,0]
	v_pk_fma_f32 v[102:103], v[96:97], v[102:103], s[84:85] op_sel_hi:[1,1,0]
	v_pk_mul_f32 v[96:97], v[96:97], v[102:103]
	v_pk_mul_f32 v[102:103], v[90:91], v[90:91]
	v_pk_mul_f32 v[96:97], v[104:105], v[96:97]
	v_max_f32_e32 v104, 0, v88
	v_max_f32_e32 v105, 0, v89
	v_fma_f32 v88, -|v88|, v96, v104
	v_fma_f32 v89, -|v89|, v97, v105
	s_nop 0
	v_fma_f32 v96, |v90|, s90, 1.0
	v_fma_f32 v97, |v91|, s90, 1.0
	v_rcp_f32_e32 v96, v96
	v_rcp_f32_e32 v97, v97
	s_nop 0
	v_pk_fma_f32 v[100:101], v[96:97], s[92:93], v[100:101] op_sel_hi:[1,0,0]
	v_pk_fma_f32 v[100:101], v[96:97], v[100:101], s[96:97] op_sel_hi:[1,1,0]
	v_pk_fma_f32 v[100:101], v[96:97], v[100:101], s[16:17] op_sel_hi:[1,1,0]
	v_pk_fma_f32 v[100:101], v[96:97], v[100:101], s[84:85] op_sel_hi:[1,1,0]
	v_pk_mul_f32 v[96:97], v[96:97], v[100:101]
	v_pk_mul_f32 v[100:101], v[102:103], s[18:19] op_sel_hi:[1,0]
	v_exp_f32_e32 v100, v100
	v_exp_f32_e32 v101, v101
	s_nop 0
	v_pk_mul_f32 v[96:97], v[100:101], v[96:97]
	v_max_f32_e32 v100, 0, v90
	v_max_f32_e32 v101, 0, v91
	v_fma_f32 v90, -|v90|, v96, v100
	v_fma_f32 v91, -|v91|, v97, v101
	s_nop 1
; __device__ __forceinline__ u32x4 pack8(f32x4 v0, f32x4 v1) { u32x4 w; w.x = cvt_pk_bf16(v0[0], v0[1]); w.y = cvt_pk_bf16(v0[2], v0[3]); w.z = cvt_pk_bf16(v1[0], v1[1]); w.w = cvt_pk_bf16(v1[2], v1[3]); return w; }
; __device__ __forceinline__ f32x4 gelu4(f32x4 v) { f32x2 a = gelu_pk((f32x2){v[0], v[1]}), b = gelu_pk((f32x2){v[2], v[3]}); return (f32x4){a.x, a.y, b.x, b.y}; }
; __device__ __forceinline__ f32x2 gelu_pk(f32x2 v) {
;     const f32x2 av = __builtin_elementwise_abs(v), d = av * 0.2316418882f + 1.0f;
;     f32x2 t; t.x = __builtin_amdgcn_rcpf(d.x); t.y = __builtin_amdgcn_rcpf(d.y);
;     f32x2 q = t * 0.5307027145f + (-0.7265760135f); q = q * t + 0.7107068705f; q = q * t + (-0.142248368f); q = q * t + 0.127414796f; q = q * t;
;     const f32x2 s = (v * v) * (-0.72134752044f);
;     f32x2 e; e.x = __builtin_amdgcn_exp2f(s.x); e.y = __builtin_amdgcn_exp2f(s.y);
;     const f32x2 m = v * (q * e), r = v - m;
;     f32x2 o; o.x = v.x < 0.f ? m.x : r.x; o.y = v.y < 0.f ? m.y : r.y; return o;
;     __device__ __forceinline__ void operator()(f32x4 (&acc)[2][2][4][2], const Unit& u, int wr, int wc, int fr_, int fq_) const {
;     ...
;             for (int m = 0; m < 4; ++m) { const int row = row0 + ai * HALF + m * 16; const float rs = rstd[row]; bf16_t* rowp = base + (size_t)row * ld + col0;
;                 float s1 = 0.f, s2 = 0.f;
; #pragma unroll
;                 for (int bj = 0; bj < 2; ++bj) { f32x4 v0 = acc[ai][bj][m][0] * rs, v1 = acc[ai][bj][m][1] * rs;
;                     if (act) { v0 = gelu4(v0); v1 = gelu4(v1); }
;                     s1 += ((v0[0] + v0[1]) + (v0[2] + v0[3])) + ((v1[0] + v1[1]) + (v1[2] + v1[3]));
;                     s2 += ((v0[0] * v0[0] + v0[1] * v0[1]) + (v0[2] * v0[2] + v0[3] * v0[3])) + ((v1[0] * v1[0] + v1[1] * v1[1]) + (v1[2] * v1[2] + v1[3] * v1[3]));
;                     *(u32x4*)(rowp + bj * HALF) = pack8(v0, v1); }
.LBB0_372:
	v_add_u32_e32 v96, 32, v146
	v_ashrrev_i32_e32 v97, 31, v96
	v_mul_lo_u32 v102, s86, v97
	v_mul_lo_u32 v103, s87, v96
	v_mad_u64_u32 v[100:101], s[14:15], s86, v96, 0
	v_add3_u32 v101, v101, v102, v103
	v_lshl_add_u64 v[100:101], v[100:101], 1, v[120:121]
	v_cvt_pk_bf16_f32 v102, v92, v93
	v_cvt_pk_bf16_f32 v103, v94, v95
	v_cvt_pk_bf16_f32 v104, v88, v89
	v_cvt_pk_bf16_f32 v105, v90, v91
	v_mov_b32_e32 v99, v98
	global_store_dwordx4 v[100:101], v[102:105], off
	v_pk_mul_f32 v[84:85], v[84:85], v[98:99]
	s_and_b64 vcc, exec, s[6:7]
	v_mov_b32_e32 v102, v98
	v_mov_b32_e32 v103, v98
	v_pk_mul_f32 v[86:87], v[86:87], v[102:103]
	v_pk_mul_f32 v[82:83], v[82:83], v[102:103]
	v_pk_mul_f32 v[80:81], v[80:81], v[98:99]
	s_cbranch_vccnz .LBB0_374
	v_fma_f32 v98, |v84|, s90, 1.0
	v_fma_f32 v99, |v85|, s90, 1.0
	v_mov_b64_e32 v[102:103], s[94:95]
	v_rcp_f32_e32 v98, v98
	v_rcp_f32_e32 v99, v99
	v_pk_mul_f32 v[106:107], v[84:85], v[84:85]
	v_pk_mul_f32 v[106:107], v[106:107], s[18:19] op_sel_hi:[1,0]
	v_pk_fma_f32 v[104:105], v[98:99], s[92:93], v[102:103] op_sel_hi:[1,0,0]
	v_exp_f32_e32 v106, v106
	v_pk_fma_f32 v[104:105], v[98:99], v[104:105], s[96:97] op_sel_hi:[1,1,0]
	v_exp_f32_e32 v107, v107
	v_pk_fma_f32 v[104:105], v[98:99], v[104:105], s[16:17] op_sel_hi:[1,1,0]
	v_pk_fma_f32 v[104:105], v[98:99], v[104:105], s[84:85] op_sel_hi:[1,1,0]
	v_pk_mul_f32 v[98:99], v[98:99], v[104:105]
	v_pk_mul_f32 v[104:105], v[86:87], v[86:87]
	v_pk_mul_f32 v[98:99], v[106:107], v[98:99]
	v_pk_mul_f32 v[104:105], v[104:105], s[18:19] op_sel_hi:[1,0]
	v_max_f32_e32 v106, 0, v84
	v_max_f32_e32 v107, 0, v85
	v_exp_f32_e32 v104, v104
	v_fma_f32 v84, -|v84|, v98, v106
	v_fma_f32 v85, -|v85|, v99, v107
	v_exp_f32_e32 v105, v105
	v_fma_f32 v98, |v86|, s90, 1.0
	v_fma_f32 v99, |v87|, s90, 1.0
	v_rcp_f32_e32 v98, v98
	v_rcp_f32_e32 v99, v99
	s_nop 0
	v_pk_fma_f32 v[106:107], v[98:99], s[92:93], v[102:103] op_sel_hi:[1,0,0]
	v_pk_fma_f32 v[106:107], v[98:99], v[106:107], s[96:97] op_sel_hi:[1,1,0]
	v_pk_fma_f32 v[106:107], v[98:99], v[106:107], s[16:17] op_sel_hi:[1,1,0]
	v_pk_fma_f32 v[106:107], v[98:99], v[106:107], s[84:85] op_sel_hi:[1,1,0]
	v_pk_mul_f32 v[98:99], v[98:99], v[106:107]
	v_pk_mul_f32 v[106:107], v[80:81], v[80:81]
	v_pk_mul_f32 v[98:99], v[104:105], v[98:99]
	v_pk_mul_f32 v[106:107], v[106:107], s[18:19] op_sel_hi:[1,0]
	v_max_f32_e32 v104, 0, v86
	v_max_f32_e32 v105, 0, v87
	v_exp_f32_e32 v106, v106
	v_fma_f32 v86, -|v86|, v98, v104
	v_fma_f32 v87, -|v87|, v99, v105
	v_exp_f32_e32 v107, v107
	v_fma_f32 v98, |v80|, s90, 1.0
	v_fma_f32 v99, |v81|, s90, 1.0
	v_rcp_f32_e32 v98, v98
	v_rcp_f32_e32 v99, v99
	s_nop 0
	v_pk_fma_f32 v[104:105], v[98:99], s[92:93], v[102:103] op_sel_hi:[1,0,0]
	v_pk_fma_f32 v[104:105], v[98:99], v[104:105], s[96:97] op_sel_hi:[1,1,0]
	v_pk_fma_f32 v[104:105], v[98:99], v[104:105], s[16:17] op_sel_hi:[1,1,0]
	v_pk_fma_f32 v[104:105], v[98:99], v[104:105], s[84:85] op_sel_hi:[1,1,0]
	v_pk_mul_f32 v[98:99], v[98:99], v[104:105]
	v_pk_mul_f32 v[104:105], v[82:83], v[82:83]
	v_pk_mul_f32 v[98:99], v[106:107], v[98:99]
	v_max_f32_e32 v106, 0, v80
	v_max_f32_e32 v107, 0, v81
	v_fma_f32 v80, -|v80|, v98, v106
	v_fma_f32 v81, -|v81|, v99, v107
	s_nop 0
	v_fma_f32 v98, |v82|, s90, 1.0
	v_fma_f32 v99, |v83|, s90, 1.0
	v_rcp_f32_e32 v98, v98
	v_rcp_f32_e32 v99, v99
	s_nop 0
	v_pk_fma_f32 v[102:103], v[98:99], s[92:93], v[102:103] op_sel_hi:[1,0,0]
	v_pk_fma_f32 v[102:103], v[98:99], v[102:103], s[96:97] op_sel_hi:[1,1,0]
	v_pk_fma_f32 v[102:103], v[98:99], v[102:103], s[16:17] op_sel_hi:[1,1,0]
	v_pk_fma_f32 v[102:103], v[98:99], v[102:103], s[84:85] op_sel_hi:[1,1,0]
	v_pk_mul_f32 v[98:99], v[98:99], v[102:103]
	v_pk_mul_f32 v[102:103], v[104:105], s[18:19] op_sel_hi:[1,0]
	v_exp_f32_e32 v102, v102
	v_exp_f32_e32 v103, v103
	s_nop 0
	v_pk_mul_f32 v[98:99], v[102:103], v[98:99]
	v_max_f32_e32 v102, 0, v82
	v_max_f32_e32 v103, 0, v83
	v_fma_f32 v82, -|v82|, v98, v102
	v_fma_f32 v83, -|v83|, v99, v103
	s_nop 1

; __device__ __forceinline__ f32x4 gelu4(f32x4 v) { f32x2 a = gelu_pk((f32x2){v[0], v[1]}), b = gelu_pk((f32x2){v[2], v[3]}); return (f32x4){a.x, a.y, b.x, b.y}; }
; __device__ __forceinline__ f32x2 gelu_pk(f32x2 v) {
;     const f32x2 av = __builtin_elementwise_abs(v), d = av * 0.2316418882f + 1.0f;
;     f32x2 t; t.x = __builtin_amdgcn_rcpf(d.x); t.y = __builtin_amdgcn_rcpf(d.y);
;     f32x2 q = t * 0.5307027145f + (-0.7265760135f); q = q * t + 0.7107068705f; q = q * t + (-0.142248368f); q = q * t + 0.127414796f; q = q * t;
;     const f32x2 s = (v * v) * (-0.72134752044f);
;     f32x2 e; e.x = __builtin_amdgcn_exp2f(s.x); e.y = __builtin_amdgcn_exp2f(s.y);
;     const f32x2 m = v * (q * e), r = v - m;
;     f32x2 o; o.x = v.x < 0.f ? m.x : r.x; o.y = v.y < 0.f ? m.y : r.y; return o;
;     __device__ __forceinline__ void operator()(f32x4 (&acc)[2][2][4][2], const Unit& u, int wr, int wc, int fr_, int fq_) const {
;     ...
;             for (int m = 0; m < 4; ++m) { const int row = row0 + ai * HALF + m * 16; const float rs = rstd[row]; bf16_t* rowp = base + (size_t)row * ld + col0;
;                 float s1 = 0.f, s2 = 0.f;
; #pragma unroll
;                 for (int bj = 0; bj < 2; ++bj) { f32x4 v0 = acc[ai][bj][m][0] * rs, v1 = acc[ai][bj][m][1] * rs;
;                     if (act) { v0 = gelu4(v0); v1 = gelu4(v1); }
.LBB0_378:
	v_mov_b32_e32 v82, v247
	s_and_b64 vcc, exec, s[6:7]
	s_waitcnt lgkmcnt(0)
	v_pk_mul_f32 v[78:79], v[78:79], v[82:83] op_sel_hi:[1,0]
	v_pk_mul_f32 v[76:77], v[76:77], v[82:83] op_sel_hi:[1,0]
	v_pk_mul_f32 v[74:75], v[74:75], v[82:83] op_sel_hi:[1,0]
	v_pk_mul_f32 v[72:73], v[72:73], v[82:83] op_sel_hi:[1,0]
	s_cbranch_vccnz .LBB0_380
	v_fma_f32 v80, |v76|, s90, 1.0
	v_fma_f32 v81, |v77|, s90, 1.0
	v_mov_b64_e32 v[84:85], s[94:95]
	v_rcp_f32_e32 v80, v80
	v_rcp_f32_e32 v81, v81
	v_pk_mul_f32 v[88:89], v[76:77], v[76:77]
	v_pk_mul_f32 v[88:89], v[88:89], s[18:19] op_sel_hi:[1,0]
	v_pk_fma_f32 v[86:87], v[80:81], s[92:93], v[84:85] op_sel_hi:[1,0,0]
	v_exp_f32_e32 v88, v88
	v_pk_fma_f32 v[86:87], v[80:81], v[86:87], s[96:97] op_sel_hi:[1,1,0]
	v_exp_f32_e32 v89, v89
	v_pk_fma_f32 v[86:87], v[80:81], v[86:87], s[16:17] op_sel_hi:[1,1,0]
	v_pk_fma_f32 v[86:87], v[80:81], v[86:87], s[84:85] op_sel_hi:[1,1,0]
	v_pk_mul_f32 v[80:81], v[80:81], v[86:87]
	v_pk_mul_f32 v[86:87], v[78:79], v[78:79]
	v_pk_mul_f32 v[80:81], v[88:89], v[80:81]
	v_pk_mul_f32 v[86:87], v[86:87], s[18:19] op_sel_hi:[1,0]
	v_max_f32_e32 v88, 0, v76
	v_max_f32_e32 v89, 0, v77
	v_exp_f32_e32 v86, v86
	v_fma_f32 v76, -|v76|, v80, v88
	v_fma_f32 v77, -|v77|, v81, v89
	v_exp_f32_e32 v87, v87
	v_fma_f32 v80, |v78|, s90, 1.0
	v_fma_f32 v81, |v79|, s90, 1.0
	v_rcp_f32_e32 v80, v80
	v_rcp_f32_e32 v81, v81
	s_nop 0
	v_pk_fma_f32 v[88:89], v[80:81], s[92:93], v[84:85] op_sel_hi:[1,0,0]
	v_pk_fma_f32 v[88:89], v[80:81], v[88:89], s[96:97] op_sel_hi:[1,1,0]
	v_pk_fma_f32 v[88:89], v[80:81], v[88:89], s[16:17] op_sel_hi:[1,1,0]
	v_pk_fma_f32 v[88:89], v[80:81], v[88:89], s[84:85] op_sel_hi:[1,1,0]
	v_pk_mul_f32 v[80:81], v[80:81], v[88:89]
	v_pk_mul_f32 v[88:89], v[72:73], v[72:73]
	v_pk_mul_f32 v[80:81], v[86:87], v[80:81]
	v_pk_mul_f32 v[88:89], v[88:89], s[18:19] op_sel_hi:[1,0]
	v_max_f32_e32 v86, 0, v78
	v_max_f32_e32 v87, 0, v79
	v_exp_f32_e32 v88, v88
	v_fma_f32 v78, -|v78|, v80, v86
	v_fma_f32 v79, -|v79|, v81, v87
	v_exp_f32_e32 v89, v89
	v_fma_f32 v80, |v72|, s90, 1.0
	v_fma_f32 v81, |v73|, s90, 1.0
	v_rcp_f32_e32 v80, v80
	v_rcp_f32_e32 v81, v81
	s_nop 0
	v_pk_fma_f32 v[86:87], v[80:81], s[92:93], v[84:85] op_sel_hi:[1,0,0]
	v_pk_fma_f32 v[86:87], v[80:81], v[86:87], s[96:97] op_sel_hi:[1,1,0]
	v_pk_fma_f32 v[86:87], v[80:81], v[86:87], s[16:17] op_sel_hi:[1,1,0]
	v_pk_fma_f32 v[86:87], v[80:81], v[86:87], s[84:85] op_sel_hi:[1,1,0]
	v_pk_mul_f32 v[80:81], v[80:81], v[86:87]
	v_pk_mul_f32 v[86:87], v[74:75], v[74:75]
	v_pk_mul_f32 v[80:81], v[88:89], v[80:81]
	v_max_f32_e32 v88, 0, v72
	v_max_f32_e32 v89, 0, v73
	v_fma_f32 v72, -|v72|, v80, v88
	v_fma_f32 v73, -|v73|, v81, v89
	s_nop 0
	v_fma_f32 v80, |v74|, s90, 1.0
	v_fma_f32 v81, |v75|, s90, 1.0
	v_rcp_f32_e32 v80, v80
	v_rcp_f32_e32 v81, v81
	s_nop 0
	v_pk_fma_f32 v[84:85], v[80:81], s[92:93], v[84:85] op_sel_hi:[1,0,0]
	v_pk_fma_f32 v[84:85], v[80:81], v[84:85], s[96:97] op_sel_hi:[1,1,0]
	v_pk_fma_f32 v[84:85], v[80:81], v[84:85], s[16:17] op_sel_hi:[1,1,0]
	v_pk_fma_f32 v[84:85], v[80:81], v[84:85], s[84:85] op_sel_hi:[1,1,0]
	v_pk_mul_f32 v[80:81], v[80:81], v[84:85]
	v_pk_mul_f32 v[84:85], v[86:87], s[18:19] op_sel_hi:[1,0]
	v_exp_f32_e32 v84, v84
	v_exp_f32_e32 v85, v85
	s_nop 0
	v_pk_mul_f32 v[80:81], v[84:85], v[80:81]
	v_max_f32_e32 v84, 0, v74
	v_max_f32_e32 v85, 0, v75
	v_fma_f32 v74, -|v74|, v80, v84
	v_fma_f32 v75, -|v75|, v81, v85
	s_nop 1
; __device__ __forceinline__ u32x4 pack8(f32x4 v0, f32x4 v1) { u32x4 w; w.x = cvt_pk_bf16(v0[0], v0[1]); w.y = cvt_pk_bf16(v0[2], v0[3]); w.z = cvt_pk_bf16(v1[0], v1[1]); w.w = cvt_pk_bf16(v1[2], v1[3]); return w; }
; __device__ __forceinline__ f32x4 gelu4(f32x4 v) { f32x2 a = gelu_pk((f32x2){v[0], v[1]}), b = gelu_pk((f32x2){v[2], v[3]}); return (f32x4){a.x, a.y, b.x, b.y}; }
; __device__ __forceinline__ f32x2 gelu_pk(f32x2 v) {
;     const f32x2 av = __builtin_elementwise_abs(v), d = av * 0.2316418882f + 1.0f;
;     f32x2 t; t.x = __builtin_amdgcn_rcpf(d.x); t.y = __builtin_amdgcn_rcpf(d.y);
;     f32x2 q = t * 0.5307027145f + (-0.7265760135f); q = q * t + 0.7107068705f; q = q * t + (-0.142248368f); q = q * t + 0.127414796f; q = q * t;
;     const f32x2 s = (v * v) * (-0.72134752044f);
;     f32x2 e; e.x = __builtin_amdgcn_exp2f(s.x); e.y = __builtin_amdgcn_exp2f(s.y);
;     const f32x2 m = v * (q * e), r = v - m;
;     f32x2 o; o.x = v.x < 0.f ? m.x : r.x; o.y = v.y < 0.f ? m.y : r.y; return o;
;     __device__ __forceinline__ void operator()(f32x4 (&acc)[2][2][4][2], const Unit& u, int wr, int wc, int fr_, int fq_) const {
;     ...
;             for (int m = 0; m < 4; ++m) { const int row = row0 + ai * HALF + m * 16; const float rs = rstd[row]; bf16_t* rowp = base + (size_t)row * ld + col0;
;                 float s1 = 0.f, s2 = 0.f;
; #pragma unroll
;                 for (int bj = 0; bj < 2; ++bj) { f32x4 v0 = acc[ai][bj][m][0] * rs, v1 = acc[ai][bj][m][1] * rs;
;                     if (act) { v0 = gelu4(v0); v1 = gelu4(v1); }
;                     s1 += ((v0[0] + v0[1]) + (v0[2] + v0[3])) + ((v1[0] + v1[1]) + (v1[2] + v1[3]));
;                     s2 += ((v0[0] * v0[0] + v0[1] * v0[1]) + (v0[2] * v0[2] + v0[3] * v0[3])) + ((v1[0] * v1[0] + v1[1] * v1[1]) + (v1[2] * v1[2] + v1[3] * v1[3]));
;                     *(u32x4*)(rowp + bj * HALF) = pack8(v0, v1); }
.LBB0_380:
	v_add_u32_e32 v80, 48, v146
	v_ashrrev_i32_e32 v81, 31, v80
	v_mul_lo_u32 v86, s86, v81
	v_mul_lo_u32 v87, s87, v80
	v_mad_u64_u32 v[84:85], s[14:15], s86, v80, 0
	v_add3_u32 v85, v85, v86, v87
	v_lshl_add_u64 v[84:85], v[84:85], 1, v[120:121]
	v_cvt_pk_bf16_f32 v86, v76, v77
	v_cvt_pk_bf16_f32 v87, v78, v79
	v_cvt_pk_bf16_f32 v88, v72, v73
	v_cvt_pk_bf16_f32 v89, v74, v75
	v_mov_b32_e32 v83, v82
	global_store_dwordx4 v[84:85], v[86:89], off
	v_pk_mul_f32 v[68:69], v[68:69], v[82:83]
	s_and_b64 vcc, exec, s[6:7]
	v_mov_b32_e32 v86, v82
	v_mov_b32_e32 v87, v82
	v_pk_mul_f32 v[70:71], v[70:71], v[86:87]
	v_pk_mul_f32 v[66:67], v[66:67], v[86:87]
	v_pk_mul_f32 v[64:65], v[64:65], v[82:83]
	s_cbranch_vccnz .LBB0_382
	v_fma_f32 v82, |v68|, s90, 1.0
	v_fma_f32 v83, |v69|, s90, 1.0
	v_mov_b64_e32 v[86:87], s[94:95]
	v_rcp_f32_e32 v82, v82
	v_rcp_f32_e32 v83, v83
	v_pk_mul_f32 v[90:91], v[68:69], v[68:69]
	v_pk_mul_f32 v[90:91], v[90:91], s[18:19] op_sel_hi:[1,0]
	v_pk_fma_f32 v[88:89], v[82:83], s[92:93], v[86:87] op_sel_hi:[1,0,0]
	v_exp_f32_e32 v90, v90
	v_pk_fma_f32 v[88:89], v[82:83], v[88:89], s[96:97] op_sel_hi:[1,1,0]
	v_exp_f32_e32 v91, v91
	v_pk_fma_f32 v[88:89], v[82:83], v[88:89], s[16:17] op_sel_hi:[1,1,0]
	v_pk_fma_f32 v[88:89], v[82:83], v[88:89], s[84:85] op_sel_hi:[1,1,0]
	v_pk_mul_f32 v[82:83], v[82:83], v[88:89]
	v_pk_mul_f32 v[88:89], v[70:71], v[70:71]
	v_pk_mul_f32 v[82:83], v[90:91], v[82:83]
	v_pk_mul_f32 v[88:89], v[88:89], s[18:19] op_sel_hi:[1,0]
	v_max_f32_e32 v90, 0, v68
	v_max_f32_e32 v91, 0, v69
	v_exp_f32_e32 v88, v88
	v_fma_f32 v68, -|v68|, v82, v90
	v_fma_f32 v69, -|v69|, v83, v91
	v_exp_f32_e32 v89, v89
	v_fma_f32 v82, |v70|, s90, 1.0
	v_fma_f32 v83, |v71|, s90, 1.0
	v_rcp_f32_e32 v82, v82
	v_rcp_f32_e32 v83, v83
	s_nop 0
	v_pk_fma_f32 v[90:91], v[82:83], s[92:93], v[86:87] op_sel_hi:[1,0,0]
	v_pk_fma_f32 v[90:91], v[82:83], v[90:91], s[96:97] op_sel_hi:[1,1,0]
	v_pk_fma_f32 v[90:91], v[82:83], v[90:91], s[16:17] op_sel_hi:[1,1,0]
	v_pk_fma_f32 v[90:91], v[82:83], v[90:91], s[84:85] op_sel_hi:[1,1,0]
	v_pk_mul_f32 v[82:83], v[82:83], v[90:91]
	v_pk_mul_f32 v[90:91], v[64:65], v[64:65]
	v_pk_mul_f32 v[82:83], v[88:89], v[82:83]
	v_pk_mul_f32 v[90:91], v[90:91], s[18:19] op_sel_hi:[1,0]
	v_max_f32_e32 v88, 0, v70
	v_max_f32_e32 v89, 0, v71
	v_exp_f32_e32 v90, v90
	v_fma_f32 v70, -|v70|, v82, v88
	v_fma_f32 v71, -|v71|, v83, v89
	v_exp_f32_e32 v91, v91
	v_fma_f32 v82, |v64|, s90, 1.0
	v_fma_f32 v83, |v65|, s90, 1.0
	v_rcp_f32_e32 v82, v82
	v_rcp_f32_e32 v83, v83
	s_nop 0
	v_pk_fma_f32 v[88:89], v[82:83], s[92:93], v[86:87] op_sel_hi:[1,0,0]
	v_pk_fma_f32 v[88:89], v[82:83], v[88:89], s[96:97] op_sel_hi:[1,1,0]
	v_pk_fma_f32 v[88:89], v[82:83], v[88:89], s[16:17] op_sel_hi:[1,1,0]
	v_pk_fma_f32 v[88:89], v[82:83], v[88:89], s[84:85] op_sel_hi:[1,1,0]
	v_pk_mul_f32 v[82:83], v[82:83], v[88:89]
	v_pk_mul_f32 v[88:89], v[66:67], v[66:67]
	v_pk_mul_f32 v[82:83], v[90:91], v[82:83]
	v_max_f32_e32 v90, 0, v64
	v_max_f32_e32 v91, 0, v65
	v_fma_f32 v64, -|v64|, v82, v90
	v_fma_f32 v65, -|v65|, v83, v91
	s_nop 0
	v_fma_f32 v82, |v66|, s90, 1.0
	v_fma_f32 v83, |v67|, s90, 1.0
	v_rcp_f32_e32 v82, v82
	v_rcp_f32_e32 v83, v83
	s_nop 0
	v_pk_fma_f32 v[86:87], v[82:83], s[92:93], v[86:87] op_sel_hi:[1,0,0]
	v_pk_fma_f32 v[86:87], v[82:83], v[86:87], s[96:97] op_sel_hi:[1,1,0]
	v_pk_fma_f32 v[86:87], v[82:83], v[86:87], s[16:17] op_sel_hi:[1,1,0]
	v_pk_fma_f32 v[86:87], v[82:83], v[86:87], s[84:85] op_sel_hi:[1,1,0]
	v_pk_mul_f32 v[82:83], v[82:83], v[86:87]
	v_pk_mul_f32 v[86:87], v[88:89], s[18:19] op_sel_hi:[1,0]
	v_exp_f32_e32 v86, v86
	v_exp_f32_e32 v87, v87
	s_nop 0
	v_pk_mul_f32 v[82:83], v[86:87], v[82:83]
	v_max_f32_e32 v86, 0, v66
	v_max_f32_e32 v87, 0, v67
	v_fma_f32 v66, -|v66|, v82, v86
	v_fma_f32 v67, -|v67|, v83, v87
	s_nop 1

; __device__ __forceinline__ u32x4 pack8(f32x4 v0, f32x4 v1) { u32x4 w; w.x = cvt_pk_bf16(v0[0], v0[1]); w.y = cvt_pk_bf16(v0[2], v0[3]); w.z = cvt_pk_bf16(v1[0], v1[1]); w.w = cvt_pk_bf16(v1[2], v1[3]); return w; }
; __device__ __forceinline__ f32x4 gelu4(f32x4 v) { f32x2 a = gelu_pk((f32x2){v[0], v[1]}), b = gelu_pk((f32x2){v[2], v[3]}); return (f32x4){a.x, a.y, b.x, b.y}; }
; __device__ __forceinline__ f32x2 gelu_pk(f32x2 v) {
;     const f32x2 av = __builtin_elementwise_abs(v), d = av * 0.2316418882f + 1.0f;
;     f32x2 t; t.x = __builtin_amdgcn_rcpf(d.x); t.y = __builtin_amdgcn_rcpf(d.y);
;     f32x2 q = t * 0.5307027145f + (-0.7265760135f); q = q * t + 0.7107068705f; q = q * t + (-0.142248368f); q = q * t + 0.127414796f; q = q * t;
;     const f32x2 s = (v * v) * (-0.72134752044f);
;     f32x2 e; e.x = __builtin_amdgcn_exp2f(s.x); e.y = __builtin_amdgcn_exp2f(s.y);
;     const f32x2 m = v * (q * e), r = v - m;
;     f32x2 o; o.x = v.x < 0.f ? m.x : r.x; o.y = v.y < 0.f ? m.y : r.y; return o;
;     __device__ __forceinline__ void operator()(f32x4 (&acc)[2][2][4][2], const Unit& u, int wr, int wc, int fr_, int fq_) const {
;     ...
;             for (int m = 0; m < 4; ++m) { const int row = row0 + ai * HALF + m * 16; const float rs = rstd[row]; bf16_t* rowp = base + (size_t)row * ld + col0;
;                 float s1 = 0.f, s2 = 0.f;
; #pragma unroll
;                 for (int bj = 0; bj < 2; ++bj) { f32x4 v0 = acc[ai][bj][m][0] * rs, v1 = acc[ai][bj][m][1] * rs;
;                     if (act) { v0 = gelu4(v0); v1 = gelu4(v1); }
;                     s1 += ((v0[0] + v0[1]) + (v0[2] + v0[3])) + ((v1[0] + v1[1]) + (v1[2] + v1[3]));
;                     s2 += ((v0[0] * v0[0] + v0[1] * v0[1]) + (v0[2] * v0[2] + v0[3] * v0[3])) + ((v1[0] * v1[0] + v1[1] * v1[1]) + (v1[2] * v1[2] + v1[3] * v1[3]));
;                     *(u32x4*)(rowp + bj * HALF) = pack8(v0, v1); }
.LBB0_386:
	v_mov_b32_e32 v66, v248
	s_and_b64 vcc, exec, s[6:7]
	s_waitcnt lgkmcnt(0)
	v_pk_mul_f32 v[62:63], v[62:63], v[66:67] op_sel_hi:[1,0]
	v_pk_mul_f32 v[60:61], v[60:61], v[66:67] op_sel_hi:[1,0]
	v_pk_mul_f32 v[58:59], v[58:59], v[66:67] op_sel_hi:[1,0]
	v_pk_mul_f32 v[56:57], v[56:57], v[66:67] op_sel_hi:[1,0]
	s_cbranch_vccnz .LBB0_388
	v_fma_f32 v64, |v60|, s90, 1.0
	v_fma_f32 v65, |v61|, s90, 1.0
	v_mov_b64_e32 v[68:69], s[94:95]
	v_rcp_f32_e32 v64, v64
	v_rcp_f32_e32 v65, v65
	v_pk_mul_f32 v[72:73], v[60:61], v[60:61]
	v_pk_mul_f32 v[72:73], v[72:73], s[18:19] op_sel_hi:[1,0]
	v_pk_fma_f32 v[70:71], v[64:65], s[92:93], v[68:69] op_sel_hi:[1,0,0]
	v_exp_f32_e32 v72, v72
	v_pk_fma_f32 v[70:71], v[64:65], v[70:71], s[96:97] op_sel_hi:[1,1,0]
	v_exp_f32_e32 v73, v73
	v_pk_fma_f32 v[70:71], v[64:65], v[70:71], s[16:17] op_sel_hi:[1,1,0]
	v_pk_fma_f32 v[70:71], v[64:65], v[70:71], s[84:85] op_sel_hi:[1,1,0]
	v_pk_mul_f32 v[64:65], v[64:65], v[70:71]
	v_pk_mul_f32 v[70:71], v[62:63], v[62:63]
	v_pk_mul_f32 v[64:65], v[72:73], v[64:65]
	v_pk_mul_f32 v[70:71], v[70:71], s[18:19] op_sel_hi:[1,0]
	v_max_f32_e32 v72, 0, v60
	v_max_f32_e32 v73, 0, v61
	v_exp_f32_e32 v70, v70
	v_fma_f32 v60, -|v60|, v64, v72
	v_fma_f32 v61, -|v61|, v65, v73
	v_exp_f32_e32 v71, v71
	v_fma_f32 v64, |v62|, s90, 1.0
	v_fma_f32 v65, |v63|, s90, 1.0
	v_rcp_f32_e32 v64, v64
	v_rcp_f32_e32 v65, v65
	s_nop 0
	v_pk_fma_f32 v[72:73], v[64:65], s[92:93], v[68:69] op_sel_hi:[1,0,0]
	v_pk_fma_f32 v[72:73], v[64:65], v[72:73], s[96:97] op_sel_hi:[1,1,0]
	v_pk_fma_f32 v[72:73], v[64:65], v[72:73], s[16:17] op_sel_hi:[1,1,0]
	v_pk_fma_f32 v[72:73], v[64:65], v[72:73], s[84:85] op_sel_hi:[1,1,0]
	v_pk_mul_f32 v[64:65], v[64:65], v[72:73]
	v_pk_mul_f32 v[72:73], v[56:57], v[56:57]
	v_pk_mul_f32 v[64:65], v[70:71], v[64:65]
	v_pk_mul_f32 v[72:73], v[72:73], s[18:19] op_sel_hi:[1,0]
	v_max_f32_e32 v70, 0, v62
	v_max_f32_e32 v71, 0, v63
	v_exp_f32_e32 v72, v72
	v_fma_f32 v62, -|v62|, v64, v70
	v_fma_f32 v63, -|v63|, v65, v71
	v_exp_f32_e32 v73, v73
	v_fma_f32 v64, |v56|, s90, 1.0
	v_fma_f32 v65, |v57|, s90, 1.0
	v_rcp_f32_e32 v64, v64
	v_rcp_f32_e32 v65, v65
	s_nop 0
	v_pk_fma_f32 v[70:71], v[64:65], s[92:93], v[68:69] op_sel_hi:[1,0,0]
	v_pk_fma_f32 v[70:71], v[64:65], v[70:71], s[96:97] op_sel_hi:[1,1,0]
	v_pk_fma_f32 v[70:71], v[64:65], v[70:71], s[16:17] op_sel_hi:[1,1,0]
	v_pk_fma_f32 v[70:71], v[64:65], v[70:71], s[84:85] op_sel_hi:[1,1,0]
	v_pk_mul_f32 v[64:65], v[64:65], v[70:71]
	v_pk_mul_f32 v[70:71], v[58:59], v[58:59]
	v_pk_mul_f32 v[64:65], v[72:73], v[64:65]
	v_max_f32_e32 v72, 0, v56
	v_max_f32_e32 v73, 0, v57
	v_fma_f32 v56, -|v56|, v64, v72
	v_fma_f32 v57, -|v57|, v65, v73
	s_nop 0
	v_fma_f32 v64, |v58|, s90, 1.0
	v_fma_f32 v65, |v59|, s90, 1.0
	v_rcp_f32_e32 v64, v64
	v_rcp_f32_e32 v65, v65
	s_nop 0
	v_pk_fma_f32 v[68:69], v[64:65], s[92:93], v[68:69] op_sel_hi:[1,0,0]
	v_pk_fma_f32 v[68:69], v[64:65], v[68:69], s[96:97] op_sel_hi:[1,1,0]
	v_pk_fma_f32 v[68:69], v[64:65], v[68:69], s[16:17] op_sel_hi:[1,1,0]
	v_pk_fma_f32 v[68:69], v[64:65], v[68:69], s[84:85] op_sel_hi:[1,1,0]
	v_pk_mul_f32 v[64:65], v[64:65], v[68:69]
	v_pk_mul_f32 v[68:69], v[70:71], s[18:19] op_sel_hi:[1,0]
	v_exp_f32_e32 v68, v68
	v_exp_f32_e32 v69, v69
	s_nop 0
	v_pk_mul_f32 v[64:65], v[68:69], v[64:65]
	v_max_f32_e32 v68, 0, v58
	v_max_f32_e32 v69, 0, v59
	v_fma_f32 v58, -|v58|, v64, v68
	v_fma_f32 v59, -|v59|, v65, v69
	s_nop 1
; __device__ __forceinline__ u32x4 pack8(f32x4 v0, f32x4 v1) { u32x4 w; w.x = cvt_pk_bf16(v0[0], v0[1]); w.y = cvt_pk_bf16(v0[2], v0[3]); w.z = cvt_pk_bf16(v1[0], v1[1]); w.w = cvt_pk_bf16(v1[2], v1[3]); return w; }
; __device__ __forceinline__ f32x4 gelu4(f32x4 v) { f32x2 a = gelu_pk((f32x2){v[0], v[1]}), b = gelu_pk((f32x2){v[2], v[3]}); return (f32x4){a.x, a.y, b.x, b.y}; }
; __device__ __forceinline__ f32x2 gelu_pk(f32x2 v) {
;     const f32x2 av = __builtin_elementwise_abs(v), d = av * 0.2316418882f + 1.0f;
;     f32x2 t; t.x = __builtin_amdgcn_rcpf(d.x); t.y = __builtin_amdgcn_rcpf(d.y);
;     f32x2 q = t * 0.5307027145f + (-0.7265760135f); q = q * t + 0.7107068705f; q = q * t + (-0.142248368f); q = q * t + 0.127414796f; q = q * t;
;     const f32x2 s = (v * v) * (-0.72134752044f);
;     f32x2 e; e.x = __builtin_amdgcn_exp2f(s.x); e.y = __builtin_amdgcn_exp2f(s.y);
;     const f32x2 m = v * (q * e), r = v - m;
;     f32x2 o; o.x = v.x < 0.f ? m.x : r.x; o.y = v.y < 0.f ? m.y : r.y; return o;
;     __device__ __forceinline__ void operator()(f32x4 (&acc)[2][2][4][2], const Unit& u, int wr, int wc, int fr_, int fq_) const {
;     ...
;             for (int m = 0; m < 4; ++m) { const int row = row0 + ai * HALF + m * 16; const float rs = rstd[row]; bf16_t* rowp = base + (size_t)row * ld + col0;
;                 float s1 = 0.f, s2 = 0.f;
; #pragma unroll
;                 for (int bj = 0; bj < 2; ++bj) { f32x4 v0 = acc[ai][bj][m][0] * rs, v1 = acc[ai][bj][m][1] * rs;
;                     if (act) { v0 = gelu4(v0); v1 = gelu4(v1); }
;                     s1 += ((v0[0] + v0[1]) + (v0[2] + v0[3])) + ((v1[0] + v1[1]) + (v1[2] + v1[3]));
;                     s2 += ((v0[0] * v0[0] + v0[1] * v0[1]) + (v0[2] * v0[2] + v0[3] * v0[3])) + ((v1[0] * v1[0] + v1[1] * v1[1]) + (v1[2] * v1[2] + v1[3] * v1[3]));
;                     *(u32x4*)(rowp + bj * HALF) = pack8(v0, v1); }
.LBB0_388:
	v_add_u32_e32 v64, 0x80, v146
	v_ashrrev_i32_e32 v65, 31, v64
	v_mul_lo_u32 v70, s86, v65
	v_mul_lo_u32 v71, s87, v64
	v_mad_u64_u32 v[68:69], s[14:15], s86, v64, 0
	v_add3_u32 v69, v69, v70, v71
	v_lshl_add_u64 v[68:69], v[68:69], 1, v[120:121]
	v_cvt_pk_bf16_f32 v70, v60, v61
	v_cvt_pk_bf16_f32 v71, v62, v63
	v_cvt_pk_bf16_f32 v72, v56, v57
	v_cvt_pk_bf16_f32 v73, v58, v59
	v_mov_b32_e32 v67, v66
	global_store_dwordx4 v[68:69], v[70:73], off
	v_pk_mul_f32 v[52:53], v[52:53], v[66:67]
	s_and_b64 vcc, exec, s[6:7]
	v_mov_b32_e32 v70, v66
	v_mov_b32_e32 v71, v66
	v_pk_mul_f32 v[54:55], v[54:55], v[70:71]
	v_pk_mul_f32 v[50:51], v[50:51], v[70:71]
	v_pk_mul_f32 v[48:49], v[48:49], v[66:67]
	s_cbranch_vccnz .LBB0_390
	v_fma_f32 v66, |v52|, s90, 1.0
	v_fma_f32 v67, |v53|, s90, 1.0
	v_mov_b64_e32 v[70:71], s[94:95]
	v_rcp_f32_e32 v66, v66
	v_rcp_f32_e32 v67, v67
	v_pk_mul_f32 v[74:75], v[52:53], v[52:53]
	v_pk_mul_f32 v[74:75], v[74:75], s[18:19] op_sel_hi:[1,0]
	v_pk_fma_f32 v[72:73], v[66:67], s[92:93], v[70:71] op_sel_hi:[1,0,0]
	v_exp_f32_e32 v74, v74
	v_pk_fma_f32 v[72:73], v[66:67], v[72:73], s[96:97] op_sel_hi:[1,1,0]
	v_exp_f32_e32 v75, v75
	v_pk_fma_f32 v[72:73], v[66:67], v[72:73], s[16:17] op_sel_hi:[1,1,0]
	v_pk_fma_f32 v[72:73], v[66:67], v[72:73], s[84:85] op_sel_hi:[1,1,0]
	v_pk_mul_f32 v[66:67], v[66:67], v[72:73]
	v_pk_mul_f32 v[72:73], v[54:55], v[54:55]
	v_pk_mul_f32 v[66:67], v[74:75], v[66:67]
	v_pk_mul_f32 v[72:73], v[72:73], s[18:19] op_sel_hi:[1,0]
	v_max_f32_e32 v74, 0, v52
	v_max_f32_e32 v75, 0, v53
	v_exp_f32_e32 v72, v72
	v_fma_f32 v52, -|v52|, v66, v74
	v_fma_f32 v53, -|v53|, v67, v75
	v_exp_f32_e32 v73, v73
	v_fma_f32 v66, |v54|, s90, 1.0
	v_fma_f32 v67, |v55|, s90, 1.0
	v_rcp_f32_e32 v66, v66
	v_rcp_f32_e32 v67, v67
	s_nop 0
	v_pk_fma_f32 v[74:75], v[66:67], s[92:93], v[70:71] op_sel_hi:[1,0,0]
	v_pk_fma_f32 v[74:75], v[66:67], v[74:75], s[96:97] op_sel_hi:[1,1,0]
	v_pk_fma_f32 v[74:75], v[66:67], v[74:75], s[16:17] op_sel_hi:[1,1,0]
	v_pk_fma_f32 v[74:75], v[66:67], v[74:75], s[84:85] op_sel_hi:[1,1,0]
	v_pk_mul_f32 v[66:67], v[66:67], v[74:75]
	v_pk_mul_f32 v[74:75], v[48:49], v[48:49]
	v_pk_mul_f32 v[66:67], v[72:73], v[66:67]
	v_pk_mul_f32 v[74:75], v[74:75], s[18:19] op_sel_hi:[1,0]
	v_max_f32_e32 v72, 0, v54
	v_max_f32_e32 v73, 0, v55
	v_exp_f32_e32 v74, v74
	v_fma_f32 v54, -|v54|, v66, v72
	v_fma_f32 v55, -|v55|, v67, v73
	v_exp_f32_e32 v75, v75
	v_fma_f32 v66, |v48|, s90, 1.0
	v_fma_f32 v67, |v49|, s90, 1.0
	v_rcp_f32_e32 v66, v66
	v_rcp_f32_e32 v67, v67
	s_nop 0
	v_pk_fma_f32 v[72:73], v[66:67], s[92:93], v[70:71] op_sel_hi:[1,0,0]
	v_pk_fma_f32 v[72:73], v[66:67], v[72:73], s[96:97] op_sel_hi:[1,1,0]
	v_pk_fma_f32 v[72:73], v[66:67], v[72:73], s[16:17] op_sel_hi:[1,1,0]
	v_pk_fma_f32 v[72:73], v[66:67], v[72:73], s[84:85] op_sel_hi:[1,1,0]
	v_pk_mul_f32 v[66:67], v[66:67], v[72:73]
	v_pk_mul_f32 v[72:73], v[50:51], v[50:51]
	v_pk_mul_f32 v[66:67], v[74:75], v[66:67]
	v_max_f32_e32 v74, 0, v48
	v_max_f32_e32 v75, 0, v49
	v_fma_f32 v48, -|v48|, v66, v74
	v_fma_f32 v49, -|v49|, v67, v75
	s_nop 0
	v_fma_f32 v66, |v50|, s90, 1.0
	v_fma_f32 v67, |v51|, s90, 1.0
	v_rcp_f32_e32 v66, v66
	v_rcp_f32_e32 v67, v67
	s_nop 0
	v_pk_fma_f32 v[70:71], v[66:67], s[92:93], v[70:71] op_sel_hi:[1,0,0]
	v_pk_fma_f32 v[70:71], v[66:67], v[70:71], s[96:97] op_sel_hi:[1,1,0]
	v_pk_fma_f32 v[70:71], v[66:67], v[70:71], s[16:17] op_sel_hi:[1,1,0]
	v_pk_fma_f32 v[70:71], v[66:67], v[70:71], s[84:85] op_sel_hi:[1,1,0]
	v_pk_mul_f32 v[66:67], v[66:67], v[70:71]
	v_pk_mul_f32 v[70:71], v[72:73], s[18:19] op_sel_hi:[1,0]
	v_exp_f32_e32 v70, v70
	v_exp_f32_e32 v71, v71
	s_nop 0
	v_pk_mul_f32 v[66:67], v[70:71], v[66:67]
	v_max_f32_e32 v70, 0, v50
	v_max_f32_e32 v71, 0, v51
	v_fma_f32 v50, -|v50|, v66, v70
	v_fma_f32 v51, -|v51|, v67, v71
	s_nop 1

; __device__ __forceinline__ u32x4 pack8(f32x4 v0, f32x4 v1) { u32x4 w; w.x = cvt_pk_bf16(v0[0], v0[1]); w.y = cvt_pk_bf16(v0[2], v0[3]); w.z = cvt_pk_bf16(v1[0], v1[1]); w.w = cvt_pk_bf16(v1[2], v1[3]); return w; }
; __device__ __forceinline__ f32x4 gelu4(f32x4 v) { f32x2 a = gelu_pk((f32x2){v[0], v[1]}), b = gelu_pk((f32x2){v[2], v[3]}); return (f32x4){a.x, a.y, b.x, b.y}; }
; __device__ __forceinline__ f32x2 gelu_pk(f32x2 v) {
;     const f32x2 av = __builtin_elementwise_abs(v), d = av * 0.2316418882f + 1.0f;
;     f32x2 t; t.x = __builtin_amdgcn_rcpf(d.x); t.y = __builtin_amdgcn_rcpf(d.y);
;     f32x2 q = t * 0.5307027145f + (-0.7265760135f); q = q * t + 0.7107068705f; q = q * t + (-0.142248368f); q = q * t + 0.127414796f; q = q * t;
;     const f32x2 s = (v * v) * (-0.72134752044f);
;     f32x2 e; e.x = __builtin_amdgcn_exp2f(s.x); e.y = __builtin_amdgcn_exp2f(s.y);
;     const f32x2 m = v * (q * e), r = v - m;
;     f32x2 o; o.x = v.x < 0.f ? m.x : r.x; o.y = v.y < 0.f ? m.y : r.y; return o;
;     __device__ __forceinline__ void operator()(f32x4 (&acc)[2][2][4][2], const Unit& u, int wr, int wc, int fr_, int fq_) const {
;     ...
;             for (int m = 0; m < 4; ++m) { const int row = row0 + ai * HALF + m * 16; const float rs = rstd[row]; bf16_t* rowp = base + (size_t)row * ld + col0;
;                 float s1 = 0.f, s2 = 0.f;
; #pragma unroll
;                 for (int bj = 0; bj < 2; ++bj) { f32x4 v0 = acc[ai][bj][m][0] * rs, v1 = acc[ai][bj][m][1] * rs;
;                     if (act) { v0 = gelu4(v0); v1 = gelu4(v1); }
;                     s1 += ((v0[0] + v0[1]) + (v0[2] + v0[3])) + ((v1[0] + v1[1]) + (v1[2] + v1[3]));
;                     s2 += ((v0[0] * v0[0] + v0[1] * v0[1]) + (v0[2] * v0[2] + v0[3] * v0[3])) + ((v1[0] * v1[0] + v1[1] * v1[1]) + (v1[2] * v1[2] + v1[3] * v1[3]));
;                     *(u32x4*)(rowp + bj * HALF) = pack8(v0, v1); }
.LBB0_394:
	v_mov_b32_e32 v50, v249
	s_and_b64 vcc, exec, s[6:7]
	s_waitcnt lgkmcnt(0)
	v_pk_mul_f32 v[46:47], v[46:47], v[50:51] op_sel_hi:[1,0]
	v_pk_mul_f32 v[44:45], v[44:45], v[50:51] op_sel_hi:[1,0]
	v_pk_mul_f32 v[42:43], v[42:43], v[50:51] op_sel_hi:[1,0]
	v_pk_mul_f32 v[40:41], v[40:41], v[50:51] op_sel_hi:[1,0]
	s_cbranch_vccnz .LBB0_396
	v_fma_f32 v48, |v44|, s90, 1.0
	v_fma_f32 v49, |v45|, s90, 1.0
	v_mov_b64_e32 v[52:53], s[94:95]
	v_rcp_f32_e32 v48, v48
	v_rcp_f32_e32 v49, v49
	v_pk_mul_f32 v[56:57], v[44:45], v[44:45]
	v_pk_mul_f32 v[56:57], v[56:57], s[18:19] op_sel_hi:[1,0]
	v_pk_fma_f32 v[54:55], v[48:49], s[92:93], v[52:53] op_sel_hi:[1,0,0]
	v_exp_f32_e32 v56, v56
	v_pk_fma_f32 v[54:55], v[48:49], v[54:55], s[96:97] op_sel_hi:[1,1,0]
	v_exp_f32_e32 v57, v57
	v_pk_fma_f32 v[54:55], v[48:49], v[54:55], s[16:17] op_sel_hi:[1,1,0]
	v_pk_fma_f32 v[54:55], v[48:49], v[54:55], s[84:85] op_sel_hi:[1,1,0]
	v_pk_mul_f32 v[48:49], v[48:49], v[54:55]
	v_pk_mul_f32 v[54:55], v[46:47], v[46:47]
	v_pk_mul_f32 v[48:49], v[56:57], v[48:49]
	v_pk_mul_f32 v[54:55], v[54:55], s[18:19] op_sel_hi:[1,0]
	v_max_f32_e32 v56, 0, v44
	v_max_f32_e32 v57, 0, v45
	v_exp_f32_e32 v54, v54
	v_fma_f32 v44, -|v44|, v48, v56
	v_fma_f32 v45, -|v45|, v49, v57
	v_exp_f32_e32 v55, v55
	v_fma_f32 v48, |v46|, s90, 1.0
	v_fma_f32 v49, |v47|, s90, 1.0
	v_rcp_f32_e32 v48, v48
	v_rcp_f32_e32 v49, v49
	s_nop 0
	v_pk_fma_f32 v[56:57], v[48:49], s[92:93], v[52:53] op_sel_hi:[1,0,0]
	v_pk_fma_f32 v[56:57], v[48:49], v[56:57], s[96:97] op_sel_hi:[1,1,0]
	v_pk_fma_f32 v[56:57], v[48:49], v[56:57], s[16:17] op_sel_hi:[1,1,0]
	v_pk_fma_f32 v[56:57], v[48:49], v[56:57], s[84:85] op_sel_hi:[1,1,0]
	v_pk_mul_f32 v[48:49], v[48:49], v[56:57]
	v_pk_mul_f32 v[56:57], v[40:41], v[40:41]
	v_pk_mul_f32 v[48:49], v[54:55], v[48:49]
	v_pk_mul_f32 v[56:57], v[56:57], s[18:19] op_sel_hi:[1,0]
	v_max_f32_e32 v54, 0, v46
	v_max_f32_e32 v55, 0, v47
	v_exp_f32_e32 v56, v56
	v_fma_f32 v46, -|v46|, v48, v54
	v_fma_f32 v47, -|v47|, v49, v55
	v_exp_f32_e32 v57, v57
	v_fma_f32 v48, |v40|, s90, 1.0
	v_fma_f32 v49, |v41|, s90, 1.0
	v_rcp_f32_e32 v48, v48
	v_rcp_f32_e32 v49, v49
	s_nop 0
	v_pk_fma_f32 v[54:55], v[48:49], s[92:93], v[52:53] op_sel_hi:[1,0,0]
	v_pk_fma_f32 v[54:55], v[48:49], v[54:55], s[96:97] op_sel_hi:[1,1,0]
	v_pk_fma_f32 v[54:55], v[48:49], v[54:55], s[16:17] op_sel_hi:[1,1,0]
	v_pk_fma_f32 v[54:55], v[48:49], v[54:55], s[84:85] op_sel_hi:[1,1,0]
	v_pk_mul_f32 v[48:49], v[48:49], v[54:55]
	v_pk_mul_f32 v[54:55], v[42:43], v[42:43]
	v_pk_mul_f32 v[48:49], v[56:57], v[48:49]
	v_max_f32_e32 v56, 0, v40
	v_max_f32_e32 v57, 0, v41
	v_fma_f32 v40, -|v40|, v48, v56
	v_fma_f32 v41, -|v41|, v49, v57
	s_nop 0
	v_fma_f32 v48, |v42|, s90, 1.0
	v_fma_f32 v49, |v43|, s90, 1.0
	v_rcp_f32_e32 v48, v48
	v_rcp_f32_e32 v49, v49
	s_nop 0
	v_pk_fma_f32 v[52:53], v[48:49], s[92:93], v[52:53] op_sel_hi:[1,0,0]
	v_pk_fma_f32 v[52:53], v[48:49], v[52:53], s[96:97] op_sel_hi:[1,1,0]
	v_pk_fma_f32 v[52:53], v[48:49], v[52:53], s[16:17] op_sel_hi:[1,1,0]
	v_pk_fma_f32 v[52:53], v[48:49], v[52:53], s[84:85] op_sel_hi:[1,1,0]
	v_pk_mul_f32 v[48:49], v[48:49], v[52:53]
	v_pk_mul_f32 v[52:53], v[54:55], s[18:19] op_sel_hi:[1,0]
	v_exp_f32_e32 v52, v52
	v_exp_f32_e32 v53, v53
	s_nop 0
	v_pk_mul_f32 v[48:49], v[52:53], v[48:49]
	v_max_f32_e32 v52, 0, v42
	v_max_f32_e32 v53, 0, v43
	v_fma_f32 v42, -|v42|, v48, v52
	v_fma_f32 v43, -|v43|, v49, v53
	s_nop 1
; __device__ __forceinline__ u32x4 pack8(f32x4 v0, f32x4 v1) { u32x4 w; w.x = cvt_pk_bf16(v0[0], v0[1]); w.y = cvt_pk_bf16(v0[2], v0[3]); w.z = cvt_pk_bf16(v1[0], v1[1]); w.w = cvt_pk_bf16(v1[2], v1[3]); return w; }
; __device__ __forceinline__ f32x4 gelu4(f32x4 v) { f32x2 a = gelu_pk((f32x2){v[0], v[1]}), b = gelu_pk((f32x2){v[2], v[3]}); return (f32x4){a.x, a.y, b.x, b.y}; }
; __device__ __forceinline__ f32x2 gelu_pk(f32x2 v) {
;     const f32x2 av = __builtin_elementwise_abs(v), d = av * 0.2316418882f + 1.0f;
;     f32x2 t; t.x = __builtin_amdgcn_rcpf(d.x); t.y = __builtin_amdgcn_rcpf(d.y);
;     f32x2 q = t * 0.5307027145f + (-0.7265760135f); q = q * t + 0.7107068705f; q = q * t + (-0.142248368f); q = q * t + 0.127414796f; q = q * t;
;     const f32x2 s = (v * v) * (-0.72134752044f);
;     f32x2 e; e.x = __builtin_amdgcn_exp2f(s.x); e.y = __builtin_amdgcn_exp2f(s.y);
;     const f32x2 m = v * (q * e), r = v - m;
;     f32x2 o; o.x = v.x < 0.f ? m.x : r.x; o.y = v.y < 0.f ? m.y : r.y; return o;
;     __device__ __forceinline__ void operator()(f32x4 (&acc)[2][2][4][2], const Unit& u, int wr, int wc, int fr_, int fq_) const {
;     ...
;             for (int m = 0; m < 4; ++m) { const int row = row0 + ai * HALF + m * 16; const float rs = rstd[row]; bf16_t* rowp = base + (size_t)row * ld + col0;
;                 float s1 = 0.f, s2 = 0.f;
; #pragma unroll
;                 for (int bj = 0; bj < 2; ++bj) { f32x4 v0 = acc[ai][bj][m][0] * rs, v1 = acc[ai][bj][m][1] * rs;
;                     if (act) { v0 = gelu4(v0); v1 = gelu4(v1); }
;                     s1 += ((v0[0] + v0[1]) + (v0[2] + v0[3])) + ((v1[0] + v1[1]) + (v1[2] + v1[3]));
;                     s2 += ((v0[0] * v0[0] + v0[1] * v0[1]) + (v0[2] * v0[2] + v0[3] * v0[3])) + ((v1[0] * v1[0] + v1[1] * v1[1]) + (v1[2] * v1[2] + v1[3] * v1[3]));
;                     *(u32x4*)(rowp + bj * HALF) = pack8(v0, v1); }
.LBB0_396:
	v_add_u32_e32 v48, 0x90, v146
	v_ashrrev_i32_e32 v49, 31, v48
	v_mul_lo_u32 v54, s86, v49
	v_mul_lo_u32 v55, s87, v48
	v_mad_u64_u32 v[52:53], s[14:15], s86, v48, 0
	v_add3_u32 v53, v53, v54, v55
	v_lshl_add_u64 v[52:53], v[52:53], 1, v[120:121]
	v_cvt_pk_bf16_f32 v54, v44, v45
	v_cvt_pk_bf16_f32 v55, v46, v47
	v_cvt_pk_bf16_f32 v56, v40, v41
	v_cvt_pk_bf16_f32 v57, v42, v43
	v_mov_b32_e32 v51, v50
	global_store_dwordx4 v[52:53], v[54:57], off
	v_pk_mul_f32 v[36:37], v[36:37], v[50:51]
	s_and_b64 vcc, exec, s[6:7]
	v_mov_b32_e32 v54, v50
	v_mov_b32_e32 v55, v50
	v_pk_mul_f32 v[38:39], v[38:39], v[54:55]
	v_pk_mul_f32 v[34:35], v[34:35], v[54:55]
	v_pk_mul_f32 v[32:33], v[32:33], v[50:51]
	s_cbranch_vccnz .LBB0_398
	v_fma_f32 v50, |v36|, s90, 1.0
	v_fma_f32 v51, |v37|, s90, 1.0
	v_mov_b64_e32 v[54:55], s[94:95]
	v_rcp_f32_e32 v50, v50
	v_rcp_f32_e32 v51, v51
	v_pk_mul_f32 v[58:59], v[36:37], v[36:37]
	v_pk_mul_f32 v[58:59], v[58:59], s[18:19] op_sel_hi:[1,0]
	v_pk_fma_f32 v[56:57], v[50:51], s[92:93], v[54:55] op_sel_hi:[1,0,0]
	v_exp_f32_e32 v58, v58
	v_pk_fma_f32 v[56:57], v[50:51], v[56:57], s[96:97] op_sel_hi:[1,1,0]
	v_exp_f32_e32 v59, v59
	v_pk_fma_f32 v[56:57], v[50:51], v[56:57], s[16:17] op_sel_hi:[1,1,0]
	v_pk_fma_f32 v[56:57], v[50:51], v[56:57], s[84:85] op_sel_hi:[1,1,0]
	v_pk_mul_f32 v[50:51], v[50:51], v[56:57]
	v_pk_mul_f32 v[56:57], v[38:39], v[38:39]
	v_pk_mul_f32 v[50:51], v[58:59], v[50:51]
	v_pk_mul_f32 v[56:57], v[56:57], s[18:19] op_sel_hi:[1,0]
	v_max_f32_e32 v58, 0, v36
	v_max_f32_e32 v59, 0, v37
	v_exp_f32_e32 v56, v56
	v_fma_f32 v36, -|v36|, v50, v58
	v_fma_f32 v37, -|v37|, v51, v59
	v_exp_f32_e32 v57, v57
	v_fma_f32 v50, |v38|, s90, 1.0
	v_fma_f32 v51, |v39|, s90, 1.0
	v_rcp_f32_e32 v50, v50
	v_rcp_f32_e32 v51, v51
	s_nop 0
	v_pk_fma_f32 v[58:59], v[50:51], s[92:93], v[54:55] op_sel_hi:[1,0,0]
	v_pk_fma_f32 v[58:59], v[50:51], v[58:59], s[96:97] op_sel_hi:[1,1,0]
	v_pk_fma_f32 v[58:59], v[50:51], v[58:59], s[16:17] op_sel_hi:[1,1,0]
	v_pk_fma_f32 v[58:59], v[50:51], v[58:59], s[84:85] op_sel_hi:[1,1,0]
	v_pk_mul_f32 v[50:51], v[50:51], v[58:59]
	v_pk_mul_f32 v[58:59], v[32:33], v[32:33]
	v_pk_mul_f32 v[50:51], v[56:57], v[50:51]
	v_pk_mul_f32 v[58:59], v[58:59], s[18:19] op_sel_hi:[1,0]
	v_max_f32_e32 v56, 0, v38
	v_max_f32_e32 v57, 0, v39
	v_exp_f32_e32 v58, v58
	v_fma_f32 v38, -|v38|, v50, v56
	v_fma_f32 v39, -|v39|, v51, v57
	v_exp_f32_e32 v59, v59
	v_fma_f32 v50, |v32|, s90, 1.0
	v_fma_f32 v51, |v33|, s90, 1.0
	v_rcp_f32_e32 v50, v50
	v_rcp_f32_e32 v51, v51
	s_nop 0
	v_pk_fma_f32 v[56:57], v[50:51], s[92:93], v[54:55] op_sel_hi:[1,0,0]
	v_pk_fma_f32 v[56:57], v[50:51], v[56:57], s[96:97] op_sel_hi:[1,1,0]
	v_pk_fma_f32 v[56:57], v[50:51], v[56:57], s[16:17] op_sel_hi:[1,1,0]
	v_pk_fma_f32 v[56:57], v[50:51], v[56:57], s[84:85] op_sel_hi:[1,1,0]
	v_pk_mul_f32 v[50:51], v[50:51], v[56:57]
	v_pk_mul_f32 v[56:57], v[34:35], v[34:35]
	v_pk_mul_f32 v[50:51], v[58:59], v[50:51]
	v_max_f32_e32 v58, 0, v32
	v_max_f32_e32 v59, 0, v33
	v_fma_f32 v32, -|v32|, v50, v58
	v_fma_f32 v33, -|v33|, v51, v59
	s_nop 0
	v_fma_f32 v50, |v34|, s90, 1.0
	v_fma_f32 v51, |v35|, s90, 1.0
	v_rcp_f32_e32 v50, v50
	v_rcp_f32_e32 v51, v51
	s_nop 0
	v_pk_fma_f32 v[54:55], v[50:51], s[92:93], v[54:55] op_sel_hi:[1,0,0]
	v_pk_fma_f32 v[54:55], v[50:51], v[54:55], s[96:97] op_sel_hi:[1,1,0]
	v_pk_fma_f32 v[54:55], v[50:51], v[54:55], s[16:17] op_sel_hi:[1,1,0]
	v_pk_fma_f32 v[54:55], v[50:51], v[54:55], s[84:85] op_sel_hi:[1,1,0]
	v_pk_mul_f32 v[50:51], v[50:51], v[54:55]
	v_pk_mul_f32 v[54:55], v[56:57], s[18:19] op_sel_hi:[1,0]
	v_exp_f32_e32 v54, v54
	v_exp_f32_e32 v55, v55
	s_nop 0
	v_pk_mul_f32 v[50:51], v[54:55], v[50:51]
	v_max_f32_e32 v54, 0, v34
	v_max_f32_e32 v55, 0, v35
	v_fma_f32 v34, -|v34|, v50, v54
	v_fma_f32 v35, -|v35|, v51, v55
	s_nop 1

; __device__ __forceinline__ u32x4 pack8(f32x4 v0, f32x4 v1) { u32x4 w; w.x = cvt_pk_bf16(v0[0], v0[1]); w.y = cvt_pk_bf16(v0[2], v0[3]); w.z = cvt_pk_bf16(v1[0], v1[1]); w.w = cvt_pk_bf16(v1[2], v1[3]); return w; }
; __device__ __forceinline__ f32x4 gelu4(f32x4 v) { f32x2 a = gelu_pk((f32x2){v[0], v[1]}), b = gelu_pk((f32x2){v[2], v[3]}); return (f32x4){a.x, a.y, b.x, b.y}; }
; __device__ __forceinline__ f32x2 gelu_pk(f32x2 v) {
;     const f32x2 av = __builtin_elementwise_abs(v), d = av * 0.2316418882f + 1.0f;
;     f32x2 t; t.x = __builtin_amdgcn_rcpf(d.x); t.y = __builtin_amdgcn_rcpf(d.y);
;     f32x2 q = t * 0.5307027145f + (-0.7265760135f); q = q * t + 0.7107068705f; q = q * t + (-0.142248368f); q = q * t + 0.127414796f; q = q * t;
;     const f32x2 s = (v * v) * (-0.72134752044f);
;     f32x2 e; e.x = __builtin_amdgcn_exp2f(s.x); e.y = __builtin_amdgcn_exp2f(s.y);
;     const f32x2 m = v * (q * e), r = v - m;
;     f32x2 o; o.x = v.x < 0.f ? m.x : r.x; o.y = v.y < 0.f ? m.y : r.y; return o;
;     __device__ __forceinline__ void operator()(f32x4 (&acc)[2][2][4][2], const Unit& u, int wr, int wc, int fr_, int fq_) const {
;     ...
;             for (int m = 0; m < 4; ++m) { const int row = row0 + ai * HALF + m * 16; const float rs = rstd[row]; bf16_t* rowp = base + (size_t)row * ld + col0;
;                 float s1 = 0.f, s2 = 0.f;
; #pragma unroll
;                 for (int bj = 0; bj < 2; ++bj) { f32x4 v0 = acc[ai][bj][m][0] * rs, v1 = acc[ai][bj][m][1] * rs;
;                     if (act) { v0 = gelu4(v0); v1 = gelu4(v1); }
;                     s1 += ((v0[0] + v0[1]) + (v0[2] + v0[3])) + ((v1[0] + v1[1]) + (v1[2] + v1[3]));
;                     s2 += ((v0[0] * v0[0] + v0[1] * v0[1]) + (v0[2] * v0[2] + v0[3] * v0[3])) + ((v1[0] * v1[0] + v1[1] * v1[1]) + (v1[2] * v1[2] + v1[3] * v1[3]));
;                     *(u32x4*)(rowp + bj * HALF) = pack8(v0, v1); }
.LBB0_402:
	v_mov_b32_e32 v34, v250
	s_and_b64 vcc, exec, s[6:7]
	s_waitcnt lgkmcnt(0)
	v_pk_mul_f32 v[30:31], v[30:31], v[34:35] op_sel_hi:[1,0]
	v_pk_mul_f32 v[28:29], v[28:29], v[34:35] op_sel_hi:[1,0]
	v_pk_mul_f32 v[26:27], v[26:27], v[34:35] op_sel_hi:[1,0]
	v_pk_mul_f32 v[24:25], v[24:25], v[34:35] op_sel_hi:[1,0]
	s_cbranch_vccnz .LBB0_404
	v_fma_f32 v32, |v28|, s90, 1.0
	v_fma_f32 v33, |v29|, s90, 1.0
	v_mov_b64_e32 v[36:37], s[94:95]
	v_rcp_f32_e32 v32, v32
	v_rcp_f32_e32 v33, v33
	v_pk_mul_f32 v[40:41], v[28:29], v[28:29]
	v_pk_mul_f32 v[40:41], v[40:41], s[18:19] op_sel_hi:[1,0]
	v_pk_fma_f32 v[38:39], v[32:33], s[92:93], v[36:37] op_sel_hi:[1,0,0]
	v_exp_f32_e32 v40, v40
	v_pk_fma_f32 v[38:39], v[32:33], v[38:39], s[96:97] op_sel_hi:[1,1,0]
	v_exp_f32_e32 v41, v41
	v_pk_fma_f32 v[38:39], v[32:33], v[38:39], s[16:17] op_sel_hi:[1,1,0]
	v_pk_fma_f32 v[38:39], v[32:33], v[38:39], s[84:85] op_sel_hi:[1,1,0]
	v_pk_mul_f32 v[32:33], v[32:33], v[38:39]
	v_pk_mul_f32 v[38:39], v[30:31], v[30:31]
	v_pk_mul_f32 v[32:33], v[40:41], v[32:33]
	v_pk_mul_f32 v[38:39], v[38:39], s[18:19] op_sel_hi:[1,0]
	v_max_f32_e32 v40, 0, v28
	v_max_f32_e32 v41, 0, v29
	v_exp_f32_e32 v38, v38
	v_fma_f32 v28, -|v28|, v32, v40
	v_fma_f32 v29, -|v29|, v33, v41
	v_exp_f32_e32 v39, v39
	v_fma_f32 v32, |v30|, s90, 1.0
	v_fma_f32 v33, |v31|, s90, 1.0
	v_rcp_f32_e32 v32, v32
	v_rcp_f32_e32 v33, v33
	s_nop 0
	v_pk_fma_f32 v[40:41], v[32:33], s[92:93], v[36:37] op_sel_hi:[1,0,0]
	v_pk_fma_f32 v[40:41], v[32:33], v[40:41], s[96:97] op_sel_hi:[1,1,0]
	v_pk_fma_f32 v[40:41], v[32:33], v[40:41], s[16:17] op_sel_hi:[1,1,0]
	v_pk_fma_f32 v[40:41], v[32:33], v[40:41], s[84:85] op_sel_hi:[1,1,0]
	v_pk_mul_f32 v[32:33], v[32:33], v[40:41]
	v_pk_mul_f32 v[40:41], v[24:25], v[24:25]
	v_pk_mul_f32 v[32:33], v[38:39], v[32:33]
	v_pk_mul_f32 v[40:41], v[40:41], s[18:19] op_sel_hi:[1,0]
	v_max_f32_e32 v38, 0, v30
	v_max_f32_e32 v39, 0, v31
	v_exp_f32_e32 v40, v40
	v_fma_f32 v30, -|v30|, v32, v38
	v_fma_f32 v31, -|v31|, v33, v39
	v_exp_f32_e32 v41, v41
	v_fma_f32 v32, |v24|, s90, 1.0
	v_fma_f32 v33, |v25|, s90, 1.0
	v_rcp_f32_e32 v32, v32
	v_rcp_f32_e32 v33, v33
	s_nop 0
	v_pk_fma_f32 v[38:39], v[32:33], s[92:93], v[36:37] op_sel_hi:[1,0,0]
	v_pk_fma_f32 v[38:39], v[32:33], v[38:39], s[96:97] op_sel_hi:[1,1,0]
	v_pk_fma_f32 v[38:39], v[32:33], v[38:39], s[16:17] op_sel_hi:[1,1,0]
	v_pk_fma_f32 v[38:39], v[32:33], v[38:39], s[84:85] op_sel_hi:[1,1,0]
	v_pk_mul_f32 v[32:33], v[32:33], v[38:39]
	v_pk_mul_f32 v[38:39], v[26:27], v[26:27]
	v_pk_mul_f32 v[32:33], v[40:41], v[32:33]
	v_max_f32_e32 v40, 0, v24
	v_max_f32_e32 v41, 0, v25
	v_fma_f32 v24, -|v24|, v32, v40
	v_fma_f32 v25, -|v25|, v33, v41
	s_nop 0
	v_fma_f32 v32, |v26|, s90, 1.0
	v_fma_f32 v33, |v27|, s90, 1.0
	v_rcp_f32_e32 v32, v32
	v_rcp_f32_e32 v33, v33
	s_nop 0
	v_pk_fma_f32 v[36:37], v[32:33], s[92:93], v[36:37] op_sel_hi:[1,0,0]
	v_pk_fma_f32 v[36:37], v[32:33], v[36:37], s[96:97] op_sel_hi:[1,1,0]
	v_pk_fma_f32 v[36:37], v[32:33], v[36:37], s[16:17] op_sel_hi:[1,1,0]
	v_pk_fma_f32 v[36:37], v[32:33], v[36:37], s[84:85] op_sel_hi:[1,1,0]
	v_pk_mul_f32 v[32:33], v[32:33], v[36:37]
	v_pk_mul_f32 v[36:37], v[38:39], s[18:19] op_sel_hi:[1,0]
	v_exp_f32_e32 v36, v36
	v_exp_f32_e32 v37, v37
	s_nop 0
	v_pk_mul_f32 v[32:33], v[36:37], v[32:33]
	v_max_f32_e32 v36, 0, v26
	v_max_f32_e32 v37, 0, v27
	v_fma_f32 v26, -|v26|, v32, v36
	v_fma_f32 v27, -|v27|, v33, v37
	s_nop 1
; __device__ __forceinline__ u32x4 pack8(f32x4 v0, f32x4 v1) { u32x4 w; w.x = cvt_pk_bf16(v0[0], v0[1]); w.y = cvt_pk_bf16(v0[2], v0[3]); w.z = cvt_pk_bf16(v1[0], v1[1]); w.w = cvt_pk_bf16(v1[2], v1[3]); return w; }
; __device__ __forceinline__ f32x4 gelu4(f32x4 v) { f32x2 a = gelu_pk((f32x2){v[0], v[1]}), b = gelu_pk((f32x2){v[2], v[3]}); return (f32x4){a.x, a.y, b.x, b.y}; }
; __device__ __forceinline__ f32x2 gelu_pk(f32x2 v) {
;     const f32x2 av = __builtin_elementwise_abs(v), d = av * 0.2316418882f + 1.0f;
;     f32x2 t; t.x = __builtin_amdgcn_rcpf(d.x); t.y = __builtin_amdgcn_rcpf(d.y);
;     f32x2 q = t * 0.5307027145f + (-0.7265760135f); q = q * t + 0.7107068705f; q = q * t + (-0.142248368f); q = q * t + 0.127414796f; q = q * t;
;     const f32x2 s = (v * v) * (-0.72134752044f);
;     f32x2 e; e.x = __builtin_amdgcn_exp2f(s.x); e.y = __builtin_amdgcn_exp2f(s.y);
;     const f32x2 m = v * (q * e), r = v - m;
;     f32x2 o; o.x = v.x < 0.f ? m.x : r.x; o.y = v.y < 0.f ? m.y : r.y; return o;
;     __device__ __forceinline__ void operator()(f32x4 (&acc)[2][2][4][2], const Unit& u, int wr, int wc, int fr_, int fq_) const {
;     ...
;             for (int m = 0; m < 4; ++m) { const int row = row0 + ai * HALF + m * 16; const float rs = rstd[row]; bf16_t* rowp = base + (size_t)row * ld + col0;
;                 float s1 = 0.f, s2 = 0.f;
; #pragma unroll
;                 for (int bj = 0; bj < 2; ++bj) { f32x4 v0 = acc[ai][bj][m][0] * rs, v1 = acc[ai][bj][m][1] * rs;
;                     if (act) { v0 = gelu4(v0); v1 = gelu4(v1); }
;                     s1 += ((v0[0] + v0[1]) + (v0[2] + v0[3])) + ((v1[0] + v1[1]) + (v1[2] + v1[3]));
;                     s2 += ((v0[0] * v0[0] + v0[1] * v0[1]) + (v0[2] * v0[2] + v0[3] * v0[3])) + ((v1[0] * v1[0] + v1[1] * v1[1]) + (v1[2] * v1[2] + v1[3] * v1[3]));
;                     *(u32x4*)(rowp + bj * HALF) = pack8(v0, v1); }
.LBB0_404:
	v_add_u32_e32 v32, 0xa0, v146
	v_ashrrev_i32_e32 v33, 31, v32
	v_mul_lo_u32 v38, s86, v33
	v_mul_lo_u32 v39, s87, v32
	v_mad_u64_u32 v[36:37], s[14:15], s86, v32, 0
	v_add3_u32 v37, v37, v38, v39
	v_lshl_add_u64 v[36:37], v[36:37], 1, v[120:121]
	v_cvt_pk_bf16_f32 v38, v28, v29
	v_cvt_pk_bf16_f32 v39, v30, v31
	v_cvt_pk_bf16_f32 v40, v24, v25
	v_cvt_pk_bf16_f32 v41, v26, v27
	v_mov_b32_e32 v35, v34
	global_store_dwordx4 v[36:37], v[38:41], off
	v_pk_mul_f32 v[20:21], v[20:21], v[34:35]
	s_and_b64 vcc, exec, s[6:7]
	v_mov_b32_e32 v38, v34
	v_mov_b32_e32 v39, v34
	v_pk_mul_f32 v[22:23], v[22:23], v[38:39]
	v_pk_mul_f32 v[18:19], v[18:19], v[38:39]
	v_pk_mul_f32 v[16:17], v[16:17], v[34:35]
	s_cbranch_vccnz .LBB0_406
	v_fma_f32 v34, |v20|, s90, 1.0
	v_fma_f32 v35, |v21|, s90, 1.0
	v_mov_b64_e32 v[38:39], s[94:95]
	v_rcp_f32_e32 v34, v34
	v_rcp_f32_e32 v35, v35
	v_pk_mul_f32 v[42:43], v[20:21], v[20:21]
	v_pk_mul_f32 v[42:43], v[42:43], s[18:19] op_sel_hi:[1,0]
	v_pk_fma_f32 v[40:41], v[34:35], s[92:93], v[38:39] op_sel_hi:[1,0,0]
	v_exp_f32_e32 v42, v42
	v_pk_fma_f32 v[40:41], v[34:35], v[40:41], s[96:97] op_sel_hi:[1,1,0]
	v_exp_f32_e32 v43, v43
	v_pk_fma_f32 v[40:41], v[34:35], v[40:41], s[16:17] op_sel_hi:[1,1,0]
	v_pk_fma_f32 v[40:41], v[34:35], v[40:41], s[84:85] op_sel_hi:[1,1,0]
	v_pk_mul_f32 v[34:35], v[34:35], v[40:41]
	v_pk_mul_f32 v[40:41], v[22:23], v[22:23]
	v_pk_mul_f32 v[34:35], v[42:43], v[34:35]
	v_pk_mul_f32 v[40:41], v[40:41], s[18:19] op_sel_hi:[1,0]
	v_max_f32_e32 v42, 0, v20
	v_max_f32_e32 v43, 0, v21
	v_exp_f32_e32 v40, v40
	v_fma_f32 v20, -|v20|, v34, v42
	v_fma_f32 v21, -|v21|, v35, v43
	v_exp_f32_e32 v41, v41
	v_fma_f32 v34, |v22|, s90, 1.0
	v_fma_f32 v35, |v23|, s90, 1.0
	v_rcp_f32_e32 v34, v34
	v_rcp_f32_e32 v35, v35
	s_nop 0
	v_pk_fma_f32 v[42:43], v[34:35], s[92:93], v[38:39] op_sel_hi:[1,0,0]
	v_pk_fma_f32 v[42:43], v[34:35], v[42:43], s[96:97] op_sel_hi:[1,1,0]
	v_pk_fma_f32 v[42:43], v[34:35], v[42:43], s[16:17] op_sel_hi:[1,1,0]
	v_pk_fma_f32 v[42:43], v[34:35], v[42:43], s[84:85] op_sel_hi:[1,1,0]
	v_pk_mul_f32 v[34:35], v[34:35], v[42:43]
	v_pk_mul_f32 v[42:43], v[16:17], v[16:17]
	v_pk_mul_f32 v[34:35], v[40:41], v[34:35]
	v_pk_mul_f32 v[42:43], v[42:43], s[18:19] op_sel_hi:[1,0]
	v_max_f32_e32 v40, 0, v22
	v_max_f32_e32 v41, 0, v23
	v_exp_f32_e32 v42, v42
	v_fma_f32 v22, -|v22|, v34, v40
	v_fma_f32 v23, -|v23|, v35, v41
	v_exp_f32_e32 v43, v43
	v_fma_f32 v34, |v16|, s90, 1.0
	v_fma_f32 v35, |v17|, s90, 1.0
	v_rcp_f32_e32 v34, v34
	v_rcp_f32_e32 v35, v35
	s_nop 0
	v_pk_fma_f32 v[40:41], v[34:35], s[92:93], v[38:39] op_sel_hi:[1,0,0]
	v_pk_fma_f32 v[40:41], v[34:35], v[40:41], s[96:97] op_sel_hi:[1,1,0]
	v_pk_fma_f32 v[40:41], v[34:35], v[40:41], s[16:17] op_sel_hi:[1,1,0]
	v_pk_fma_f32 v[40:41], v[34:35], v[40:41], s[84:85] op_sel_hi:[1,1,0]
	v_pk_mul_f32 v[34:35], v[34:35], v[40:41]
	v_pk_mul_f32 v[40:41], v[18:19], v[18:19]
	v_pk_mul_f32 v[34:35], v[42:43], v[34:35]
	v_max_f32_e32 v42, 0, v16
	v_max_f32_e32 v43, 0, v17
	v_fma_f32 v16, -|v16|, v34, v42
	v_fma_f32 v17, -|v17|, v35, v43
	s_nop 0
	v_fma_f32 v34, |v18|, s90, 1.0
	v_fma_f32 v35, |v19|, s90, 1.0
	v_rcp_f32_e32 v34, v34
	v_rcp_f32_e32 v35, v35
	s_nop 0
	v_pk_fma_f32 v[38:39], v[34:35], s[92:93], v[38:39] op_sel_hi:[1,0,0]
	v_pk_fma_f32 v[38:39], v[34:35], v[38:39], s[96:97] op_sel_hi:[1,1,0]
	v_pk_fma_f32 v[38:39], v[34:35], v[38:39], s[16:17] op_sel_hi:[1,1,0]
	v_pk_fma_f32 v[38:39], v[34:35], v[38:39], s[84:85] op_sel_hi:[1,1,0]
	v_pk_mul_f32 v[34:35], v[34:35], v[38:39]
	v_pk_mul_f32 v[38:39], v[40:41], s[18:19] op_sel_hi:[1,0]
	v_exp_f32_e32 v38, v38
	v_exp_f32_e32 v39, v39
	s_nop 0
	v_pk_mul_f32 v[34:35], v[38:39], v[34:35]
	v_max_f32_e32 v38, 0, v18
	v_max_f32_e32 v39, 0, v19
	v_fma_f32 v18, -|v18|, v34, v38
	v_fma_f32 v19, -|v19|, v35, v39
	s_nop 1

; __device__ __forceinline__ u32x4 pack8(f32x4 v0, f32x4 v1) { u32x4 w; w.x = cvt_pk_bf16(v0[0], v0[1]); w.y = cvt_pk_bf16(v0[2], v0[3]); w.z = cvt_pk_bf16(v1[0], v1[1]); w.w = cvt_pk_bf16(v1[2], v1[3]); return w; }
; __device__ __forceinline__ f32x4 gelu4(f32x4 v) { f32x2 a = gelu_pk((f32x2){v[0], v[1]}), b = gelu_pk((f32x2){v[2], v[3]}); return (f32x4){a.x, a.y, b.x, b.y}; }
; __device__ __forceinline__ f32x2 gelu_pk(f32x2 v) {
;     const f32x2 av = __builtin_elementwise_abs(v), d = av * 0.2316418882f + 1.0f;
;     f32x2 t; t.x = __builtin_amdgcn_rcpf(d.x); t.y = __builtin_amdgcn_rcpf(d.y);
;     f32x2 q = t * 0.5307027145f + (-0.7265760135f); q = q * t + 0.7107068705f; q = q * t + (-0.142248368f); q = q * t + 0.127414796f; q = q * t;
;     const f32x2 s = (v * v) * (-0.72134752044f);
;     f32x2 e; e.x = __builtin_amdgcn_exp2f(s.x); e.y = __builtin_amdgcn_exp2f(s.y);
;     const f32x2 m = v * (q * e), r = v - m;
;     f32x2 o; o.x = v.x < 0.f ? m.x : r.x; o.y = v.y < 0.f ? m.y : r.y; return o;
;     __device__ __forceinline__ void operator()(f32x4 (&acc)[2][2][4][2], const Unit& u, int wr, int wc, int fr_, int fq_) const {
;     ...
;             for (int m = 0; m < 4; ++m) { const int row = row0 + ai * HALF + m * 16; const float rs = rstd[row]; bf16_t* rowp = base + (size_t)row * ld + col0;
;                 float s1 = 0.f, s2 = 0.f;
; #pragma unroll
;                 for (int bj = 0; bj < 2; ++bj) { f32x4 v0 = acc[ai][bj][m][0] * rs, v1 = acc[ai][bj][m][1] * rs;
;                     if (act) { v0 = gelu4(v0); v1 = gelu4(v1); }
;                     s1 += ((v0[0] + v0[1]) + (v0[2] + v0[3])) + ((v1[0] + v1[1]) + (v1[2] + v1[3]));
;                     s2 += ((v0[0] * v0[0] + v0[1] * v0[1]) + (v0[2] * v0[2] + v0[3] * v0[3])) + ((v1[0] * v1[0] + v1[1] * v1[1]) + (v1[2] * v1[2] + v1[3] * v1[3]));
;                     *(u32x4*)(rowp + bj * HALF) = pack8(v0, v1); }
.LBB0_410:
	v_mov_b32_e32 v18, v251
	s_and_b64 vcc, exec, s[6:7]
	s_waitcnt lgkmcnt(0)
	v_pk_mul_f32 v[14:15], v[14:15], v[18:19] op_sel_hi:[1,0]
	v_pk_mul_f32 v[12:13], v[12:13], v[18:19] op_sel_hi:[1,0]
	v_pk_mul_f32 v[10:11], v[10:11], v[18:19] op_sel_hi:[1,0]
	v_pk_mul_f32 v[8:9], v[8:9], v[18:19] op_sel_hi:[1,0]
	s_cbranch_vccnz .LBB0_412
	v_fma_f32 v16, |v12|, s90, 1.0
	v_fma_f32 v17, |v13|, s90, 1.0
	v_mov_b64_e32 v[20:21], s[94:95]
	v_rcp_f32_e32 v16, v16
	v_rcp_f32_e32 v17, v17
	v_pk_mul_f32 v[24:25], v[12:13], v[12:13]
	v_pk_mul_f32 v[24:25], v[24:25], s[18:19] op_sel_hi:[1,0]
	v_pk_fma_f32 v[22:23], v[16:17], s[92:93], v[20:21] op_sel_hi:[1,0,0]
	v_exp_f32_e32 v24, v24
	v_pk_fma_f32 v[22:23], v[16:17], v[22:23], s[96:97] op_sel_hi:[1,1,0]
	v_exp_f32_e32 v25, v25
	v_pk_fma_f32 v[22:23], v[16:17], v[22:23], s[16:17] op_sel_hi:[1,1,0]
	v_pk_fma_f32 v[22:23], v[16:17], v[22:23], s[84:85] op_sel_hi:[1,1,0]
	v_pk_mul_f32 v[16:17], v[16:17], v[22:23]
	v_pk_mul_f32 v[22:23], v[14:15], v[14:15]
	v_pk_mul_f32 v[16:17], v[24:25], v[16:17]
	v_pk_mul_f32 v[22:23], v[22:23], s[18:19] op_sel_hi:[1,0]
	v_max_f32_e32 v24, 0, v12
	v_max_f32_e32 v25, 0, v13
	v_exp_f32_e32 v22, v22
	v_fma_f32 v12, -|v12|, v16, v24
	v_fma_f32 v13, -|v13|, v17, v25
	v_exp_f32_e32 v23, v23
	v_fma_f32 v16, |v14|, s90, 1.0
	v_fma_f32 v17, |v15|, s90, 1.0
	v_rcp_f32_e32 v16, v16
	v_rcp_f32_e32 v17, v17
	s_nop 0
	v_pk_fma_f32 v[24:25], v[16:17], s[92:93], v[20:21] op_sel_hi:[1,0,0]
	v_pk_fma_f32 v[24:25], v[16:17], v[24:25], s[96:97] op_sel_hi:[1,1,0]
	v_pk_fma_f32 v[24:25], v[16:17], v[24:25], s[16:17] op_sel_hi:[1,1,0]
	v_pk_fma_f32 v[24:25], v[16:17], v[24:25], s[84:85] op_sel_hi:[1,1,0]
	v_pk_mul_f32 v[16:17], v[16:17], v[24:25]
	v_pk_mul_f32 v[24:25], v[8:9], v[8:9]
	v_pk_mul_f32 v[16:17], v[22:23], v[16:17]
	v_pk_mul_f32 v[24:25], v[24:25], s[18:19] op_sel_hi:[1,0]
	v_max_f32_e32 v22, 0, v14
	v_max_f32_e32 v23, 0, v15
	v_exp_f32_e32 v24, v24
	v_fma_f32 v14, -|v14|, v16, v22
	v_fma_f32 v15, -|v15|, v17, v23
	v_exp_f32_e32 v25, v25
	v_fma_f32 v16, |v8|, s90, 1.0
	v_fma_f32 v17, |v9|, s90, 1.0
	v_rcp_f32_e32 v16, v16
	v_rcp_f32_e32 v17, v17
	s_nop 0
	v_pk_fma_f32 v[22:23], v[16:17], s[92:93], v[20:21] op_sel_hi:[1,0,0]
	v_pk_fma_f32 v[22:23], v[16:17], v[22:23], s[96:97] op_sel_hi:[1,1,0]
	v_pk_fma_f32 v[22:23], v[16:17], v[22:23], s[16:17] op_sel_hi:[1,1,0]
	v_pk_fma_f32 v[22:23], v[16:17], v[22:23], s[84:85] op_sel_hi:[1,1,0]
	v_pk_mul_f32 v[16:17], v[16:17], v[22:23]
	v_pk_mul_f32 v[22:23], v[10:11], v[10:11]
	v_pk_mul_f32 v[16:17], v[24:25], v[16:17]
	v_max_f32_e32 v24, 0, v8
	v_max_f32_e32 v25, 0, v9
	v_fma_f32 v8, -|v8|, v16, v24
	v_fma_f32 v9, -|v9|, v17, v25
	s_nop 0
	v_fma_f32 v16, |v10|, s90, 1.0
	v_fma_f32 v17, |v11|, s90, 1.0
	v_rcp_f32_e32 v16, v16
	v_rcp_f32_e32 v17, v17
	s_nop 0
	v_pk_fma_f32 v[20:21], v[16:17], s[92:93], v[20:21] op_sel_hi:[1,0,0]
	v_pk_fma_f32 v[20:21], v[16:17], v[20:21], s[96:97] op_sel_hi:[1,1,0]
	v_pk_fma_f32 v[20:21], v[16:17], v[20:21], s[16:17] op_sel_hi:[1,1,0]
	v_pk_fma_f32 v[20:21], v[16:17], v[20:21], s[84:85] op_sel_hi:[1,1,0]
	v_pk_mul_f32 v[16:17], v[16:17], v[20:21]
	v_pk_mul_f32 v[20:21], v[22:23], s[18:19] op_sel_hi:[1,0]
	v_exp_f32_e32 v20, v20
	v_exp_f32_e32 v21, v21
	s_nop 0
	v_pk_mul_f32 v[16:17], v[20:21], v[16:17]
	v_max_f32_e32 v20, 0, v10
	v_max_f32_e32 v21, 0, v11
	v_fma_f32 v10, -|v10|, v16, v20
	v_fma_f32 v11, -|v11|, v17, v21
	s_nop 1
; __device__ __forceinline__ u32x4 pack8(f32x4 v0, f32x4 v1) { u32x4 w; w.x = cvt_pk_bf16(v0[0], v0[1]); w.y = cvt_pk_bf16(v0[2], v0[3]); w.z = cvt_pk_bf16(v1[0], v1[1]); w.w = cvt_pk_bf16(v1[2], v1[3]); return w; }
; __device__ __forceinline__ f32x4 gelu4(f32x4 v) { f32x2 a = gelu_pk((f32x2){v[0], v[1]}), b = gelu_pk((f32x2){v[2], v[3]}); return (f32x4){a.x, a.y, b.x, b.y}; }
; __device__ __forceinline__ f32x2 gelu_pk(f32x2 v) {
;     const f32x2 av = __builtin_elementwise_abs(v), d = av * 0.2316418882f + 1.0f;
;     f32x2 t; t.x = __builtin_amdgcn_rcpf(d.x); t.y = __builtin_amdgcn_rcpf(d.y);
;     f32x2 q = t * 0.5307027145f + (-0.7265760135f); q = q * t + 0.7107068705f; q = q * t + (-0.142248368f); q = q * t + 0.127414796f; q = q * t;
;     const f32x2 s = (v * v) * (-0.72134752044f);
;     f32x2 e; e.x = __builtin_amdgcn_exp2f(s.x); e.y = __builtin_amdgcn_exp2f(s.y);
;     const f32x2 m = v * (q * e), r = v - m;
;     f32x2 o; o.x = v.x < 0.f ? m.x : r.x; o.y = v.y < 0.f ? m.y : r.y; return o;
;     __device__ __forceinline__ void operator()(f32x4 (&acc)[2][2][4][2], const Unit& u, int wr, int wc, int fr_, int fq_) const {
;     ...
;             for (int m = 0; m < 4; ++m) { const int row = row0 + ai * HALF + m * 16; const float rs = rstd[row]; bf16_t* rowp = base + (size_t)row * ld + col0;
;                 float s1 = 0.f, s2 = 0.f;
; #pragma unroll
;                 for (int bj = 0; bj < 2; ++bj) { f32x4 v0 = acc[ai][bj][m][0] * rs, v1 = acc[ai][bj][m][1] * rs;
;                     if (act) { v0 = gelu4(v0); v1 = gelu4(v1); }
;                     s1 += ((v0[0] + v0[1]) + (v0[2] + v0[3])) + ((v1[0] + v1[1]) + (v1[2] + v1[3]));
;                     s2 += ((v0[0] * v0[0] + v0[1] * v0[1]) + (v0[2] * v0[2] + v0[3] * v0[3])) + ((v1[0] * v1[0] + v1[1] * v1[1]) + (v1[2] * v1[2] + v1[3] * v1[3]));
;                     *(u32x4*)(rowp + bj * HALF) = pack8(v0, v1); }
.LBB0_412:
	v_add_u32_e32 v16, 0xb0, v146
	v_ashrrev_i32_e32 v17, 31, v16
	v_mul_lo_u32 v22, s86, v17
	v_mul_lo_u32 v23, s87, v16
	v_mad_u64_u32 v[20:21], s[14:15], s86, v16, 0
	v_add3_u32 v21, v21, v22, v23
	v_lshl_add_u64 v[20:21], v[20:21], 1, v[120:121]
	v_cvt_pk_bf16_f32 v22, v12, v13
	v_cvt_pk_bf16_f32 v23, v14, v15
	v_cvt_pk_bf16_f32 v24, v8, v9
	v_cvt_pk_bf16_f32 v25, v10, v11
	v_mov_b32_e32 v19, v18
	global_store_dwordx4 v[20:21], v[22:25], off
	v_pk_mul_f32 v[4:5], v[4:5], v[18:19]
	s_and_b64 vcc, exec, s[6:7]
	v_mov_b32_e32 v22, v18
	v_mov_b32_e32 v23, v18
	v_pk_mul_f32 v[6:7], v[6:7], v[22:23]
	v_pk_mul_f32 v[2:3], v[2:3], v[22:23]
	v_pk_mul_f32 v[0:1], v[0:1], v[18:19]
	s_cbranch_vccnz .LBB0_414
	v_fma_f32 v18, |v4|, s90, 1.0
	v_fma_f32 v19, |v5|, s90, 1.0
	v_mov_b64_e32 v[22:23], s[94:95]
	v_rcp_f32_e32 v18, v18
	v_rcp_f32_e32 v19, v19
	v_pk_mul_f32 v[26:27], v[4:5], v[4:5]
	v_pk_mul_f32 v[26:27], v[26:27], s[18:19] op_sel_hi:[1,0]
	v_pk_fma_f32 v[24:25], v[18:19], s[92:93], v[22:23] op_sel_hi:[1,0,0]
	v_exp_f32_e32 v26, v26
	v_pk_fma_f32 v[24:25], v[18:19], v[24:25], s[96:97] op_sel_hi:[1,1,0]
	v_exp_f32_e32 v27, v27
	v_pk_fma_f32 v[24:25], v[18:19], v[24:25], s[16:17] op_sel_hi:[1,1,0]
	v_pk_fma_f32 v[24:25], v[18:19], v[24:25], s[84:85] op_sel_hi:[1,1,0]
	v_pk_mul_f32 v[18:19], v[18:19], v[24:25]
	v_pk_mul_f32 v[24:25], v[6:7], v[6:7]
	v_pk_mul_f32 v[18:19], v[26:27], v[18:19]
	v_pk_mul_f32 v[24:25], v[24:25], s[18:19] op_sel_hi:[1,0]
	v_max_f32_e32 v26, 0, v4
	v_max_f32_e32 v27, 0, v5
	v_exp_f32_e32 v24, v24
	v_fma_f32 v4, -|v4|, v18, v26
	v_fma_f32 v5, -|v5|, v19, v27
	v_exp_f32_e32 v25, v25
	v_fma_f32 v18, |v6|, s90, 1.0
	v_fma_f32 v19, |v7|, s90, 1.0
	v_rcp_f32_e32 v18, v18
	v_rcp_f32_e32 v19, v19
	s_nop 0
	v_pk_fma_f32 v[26:27], v[18:19], s[92:93], v[22:23] op_sel_hi:[1,0,0]
	v_pk_fma_f32 v[26:27], v[18:19], v[26:27], s[96:97] op_sel_hi:[1,1,0]
	v_pk_fma_f32 v[26:27], v[18:19], v[26:27], s[16:17] op_sel_hi:[1,1,0]
	v_pk_fma_f32 v[26:27], v[18:19], v[26:27], s[84:85] op_sel_hi:[1,1,0]
	v_pk_mul_f32 v[18:19], v[18:19], v[26:27]
	v_pk_mul_f32 v[26:27], v[0:1], v[0:1]
	v_pk_mul_f32 v[18:19], v[24:25], v[18:19]
	v_pk_mul_f32 v[26:27], v[26:27], s[18:19] op_sel_hi:[1,0]
	v_max_f32_e32 v24, 0, v6
	v_max_f32_e32 v25, 0, v7
	v_exp_f32_e32 v26, v26
	v_fma_f32 v6, -|v6|, v18, v24
	v_fma_f32 v7, -|v7|, v19, v25
	v_exp_f32_e32 v27, v27
	v_fma_f32 v18, |v0|, s90, 1.0
	v_fma_f32 v19, |v1|, s90, 1.0
	v_rcp_f32_e32 v18, v18
	v_rcp_f32_e32 v19, v19
	s_nop 0
	v_pk_fma_f32 v[24:25], v[18:19], s[92:93], v[22:23] op_sel_hi:[1,0,0]
	v_pk_fma_f32 v[24:25], v[18:19], v[24:25], s[96:97] op_sel_hi:[1,1,0]
	v_pk_fma_f32 v[24:25], v[18:19], v[24:25], s[16:17] op_sel_hi:[1,1,0]
	v_pk_fma_f32 v[24:25], v[18:19], v[24:25], s[84:85] op_sel_hi:[1,1,0]
	v_pk_mul_f32 v[18:19], v[18:19], v[24:25]
	v_pk_mul_f32 v[24:25], v[2:3], v[2:3]
	v_pk_mul_f32 v[18:19], v[26:27], v[18:19]
	v_max_f32_e32 v26, 0, v0
	v_max_f32_e32 v27, 0, v1
	v_fma_f32 v0, -|v0|, v18, v26
	v_fma_f32 v1, -|v1|, v19, v27
	s_nop 0
	v_fma_f32 v18, |v2|, s90, 1.0
	v_fma_f32 v19, |v3|, s90, 1.0
	v_rcp_f32_e32 v18, v18
	v_rcp_f32_e32 v19, v19
	s_nop 0
	v_pk_fma_f32 v[22:23], v[18:19], s[92:93], v[22:23] op_sel_hi:[1,0,0]
	v_pk_fma_f32 v[22:23], v[18:19], v[22:23], s[96:97] op_sel_hi:[1,1,0]
	v_pk_fma_f32 v[22:23], v[18:19], v[22:23], s[16:17] op_sel_hi:[1,1,0]
	v_pk_fma_f32 v[22:23], v[18:19], v[22:23], s[84:85] op_sel_hi:[1,1,0]
	v_pk_mul_f32 v[18:19], v[18:19], v[22:23]
	v_pk_mul_f32 v[22:23], v[24:25], s[18:19] op_sel_hi:[1,0]
	v_exp_f32_e32 v22, v22
	v_exp_f32_e32 v23, v23
	s_nop 0
	v_pk_mul_f32 v[18:19], v[22:23], v[18:19]
	v_max_f32_e32 v22, 0, v2
	v_max_f32_e32 v23, 0, v3
	v_fma_f32 v2, -|v2|, v18, v22
	v_fma_f32 v3, -|v3|, v19, v23
	s_nop 1

; __device__ __forceinline__ u32x4 pack8(f32x4 v0, f32x4 v1) { u32x4 w; w.x = cvt_pk_bf16(v0[0], v0[1]); w.y = cvt_pk_bf16(v0[2], v0[3]); w.z = cvt_pk_bf16(v1[0], v1[1]); w.w = cvt_pk_bf16(v1[2], v1[3]); return w; }
; __device__ __forceinline__ f32x4 gelu4(f32x4 v) { f32x2 a = gelu_pk((f32x2){v[0], v[1]}), b = gelu_pk((f32x2){v[2], v[3]}); return (f32x4){a.x, a.y, b.x, b.y}; }
; __device__ __forceinline__ f32x2 gelu_pk(f32x2 v) {
;     const f32x2 av = __builtin_elementwise_abs(v), d = av * 0.2316418882f + 1.0f;
;     f32x2 t; t.x = __builtin_amdgcn_rcpf(d.x); t.y = __builtin_amdgcn_rcpf(d.y);
;     f32x2 q = t * 0.5307027145f + (-0.7265760135f); q = q * t + 0.7107068705f; q = q * t + (-0.142248368f); q = q * t + 0.127414796f; q = q * t;
;     const f32x2 s = (v * v) * (-0.72134752044f);
;     f32x2 e; e.x = __builtin_amdgcn_exp2f(s.x); e.y = __builtin_amdgcn_exp2f(s.y);
;     const f32x2 m = v * (q * e), r = v - m;
;     f32x2 o; o.x = v.x < 0.f ? m.x : r.x; o.y = v.y < 0.f ? m.y : r.y; return o;
;     __device__ __forceinline__ void operator()(f32x4 (&acc)[2][2][4][2], const Unit& u, int wr, int wc, int fr_, int fq_) const {
;     ...
;             for (int m = 0; m < 4; ++m) { const int row = u.pm * BM + blk * 64 + m * 16 + fr;
;                 const f32x4 g0 = gelu4(acc[ai][0][m][0]), g1 = gelu4(acc[ai][0][m][1]);
;                 *(u32x4*)(ACT + (size_t)row * 5632 + jcol) = pack8(g0 * acc[ai][1][m][0], g1 * acc[ai][1][m][1]); asm volatile("" ::: "memory"); __builtin_amdgcn_sched_barrier(0); }
.LBB0_1727:
	s_or_b64 exec, exec, s[12:13]
	v_fma_f32 v128, |v124|, s58, 1.0
	v_fma_f32 v129, |v125|, s58, 1.0
	v_lshl_add_u32 v178, s90, 8, v178
	v_rcp_f32_e32 v182, v128
	v_rcp_f32_e32 v183, v129
	v_readlane_b32 s0, v244, 55
	v_pk_mul_f32 v[186:187], v[124:125], v[124:125]
	s_nop 0
	v_add_u32_e32 v179, s0, v178
	s_mov_b32 s0, 0xbf3a00e3
	v_mov_b64_e32 v[128:129], s[0:1]
	v_pk_fma_f32 v[184:185], v[182:183], s[60:61], v[128:129] op_sel_hi:[1,0,0]
	v_pk_mul_f32 v[186:187], v[186:187], s[50:51] op_sel_hi:[1,0]
	v_pk_fma_f32 v[184:185], v[182:183], v[184:185], s[62:63] op_sel_hi:[1,1,0]
	v_exp_f32_e32 v186, v186
	v_exp_f32_e32 v187, v187
	v_pk_fma_f32 v[184:185], v[182:183], v[184:185], s[64:65] op_sel_hi:[1,1,0]
	v_lshl_add_u64 v[138:139], v[164:165], 0, s[54:55]
	v_pk_fma_f32 v[184:185], v[182:183], v[184:185], s[66:67] op_sel_hi:[1,1,0]
	v_lshl_add_u64 v[140:141], v[168:169], 0, s[54:55]
	v_pk_mul_f32 v[182:183], v[182:183], v[184:185]
	v_pk_mul_f32 v[184:185], v[126:127], v[126:127]
	v_pk_mul_f32 v[182:183], v[186:187], v[182:183]
	v_pk_mul_f32 v[184:185], v[184:185], s[50:51] op_sel_hi:[1,0]
	v_max_f32_e32 v186, 0, v124
	v_max_f32_e32 v187, 0, v125
	v_exp_f32_e32 v184, v184
	v_fma_f32 v124, -|v124|, v182, v186
	v_fma_f32 v125, -|v125|, v183, v187
	v_exp_f32_e32 v185, v185
	v_fma_f32 v182, |v126|, s58, 1.0
	v_fma_f32 v183, |v127|, s58, 1.0
	v_rcp_f32_e32 v182, v182
	v_rcp_f32_e32 v183, v183
	v_pk_mul_f32 v[100:101], v[124:125], v[100:101]
	v_lshl_add_u64 v[142:143], v[170:171], 0, s[54:55]
	v_cvt_pk_bf16_f32 v100, v100, v101
	v_pk_fma_f32 v[186:187], v[182:183], s[60:61], v[128:129] op_sel_hi:[1,0,0]
	v_lshl_add_u64 v[176:177], v[166:167], 0, s[54:55]
	v_pk_fma_f32 v[186:187], v[182:183], v[186:187], s[62:63] op_sel_hi:[1,1,0]
	v_lshl_add_u64 v[130:131], v[164:165], 0, s[56:57]
	v_pk_fma_f32 v[186:187], v[182:183], v[186:187], s[64:65] op_sel_hi:[1,1,0]
	v_lshl_add_u64 v[132:133], v[168:169], 0, s[56:57]
	v_pk_fma_f32 v[186:187], v[182:183], v[186:187], s[66:67] op_sel_hi:[1,1,0]
	v_lshl_add_u64 v[134:135], v[170:171], 0, s[56:57]
	v_pk_mul_f32 v[182:183], v[182:183], v[186:187]
	v_pk_mul_f32 v[186:187], v[116:117], v[116:117]
	v_pk_mul_f32 v[182:183], v[184:185], v[182:183]
	v_pk_mul_f32 v[186:187], v[186:187], s[50:51] op_sel_hi:[1,0]
	v_max_f32_e32 v184, 0, v126
	v_max_f32_e32 v185, 0, v127
	v_exp_f32_e32 v186, v186
	v_fma_f32 v126, -|v126|, v182, v184
	v_fma_f32 v127, -|v127|, v183, v185
	v_exp_f32_e32 v187, v187
	v_fma_f32 v182, |v116|, s58, 1.0
	v_fma_f32 v183, |v117|, s58, 1.0
	v_rcp_f32_e32 v182, v182
	v_rcp_f32_e32 v183, v183
	v_pk_mul_f32 v[102:103], v[126:127], v[102:103]
	v_lshl_add_u64 v[136:137], v[166:167], 0, s[56:57]
	v_cvt_pk_bf16_f32 v101, v102, v103
	v_pk_fma_f32 v[184:185], v[182:183], s[60:61], v[128:129] op_sel_hi:[1,0,0]
	v_pk_fma_f32 v[184:185], v[182:183], v[184:185], s[62:63] op_sel_hi:[1,1,0]
	v_pk_fma_f32 v[184:185], v[182:183], v[184:185], s[64:65] op_sel_hi:[1,1,0]
	v_pk_fma_f32 v[184:185], v[182:183], v[184:185], s[66:67] op_sel_hi:[1,1,0]
	v_pk_mul_f32 v[182:183], v[182:183], v[184:185]
	v_pk_mul_f32 v[184:185], v[118:119], v[118:119]
	v_pk_mul_f32 v[182:183], v[186:187], v[182:183]
	v_pk_mul_f32 v[184:185], v[184:185], s[50:51] op_sel_hi:[1,0]
	v_max_f32_e32 v186, 0, v116
	v_max_f32_e32 v187, 0, v117
	v_exp_f32_e32 v184, v184
	v_fma_f32 v116, -|v116|, v182, v186
	v_fma_f32 v117, -|v117|, v183, v187
	v_exp_f32_e32 v185, v185
	v_fma_f32 v182, |v118|, s58, 1.0
	v_fma_f32 v183, |v119|, s58, 1.0
	v_rcp_f32_e32 v182, v182
	v_rcp_f32_e32 v183, v183
	v_pk_mul_f32 v[76:77], v[116:117], v[76:77]
	v_pk_fma_f32 v[186:187], v[182:183], s[60:61], v[128:129] op_sel_hi:[1,0,0]
	v_pk_fma_f32 v[186:187], v[182:183], v[186:187], s[62:63] op_sel_hi:[1,1,0]
	v_cvt_pk_bf16_f32 v102, v76, v77
	v_pk_fma_f32 v[186:187], v[182:183], v[186:187], s[64:65] op_sel_hi:[1,1,0]
	v_mov_b64_e32 v[76:77], s[22:23]
	v_pk_fma_f32 v[186:187], v[182:183], v[186:187], s[66:67] op_sel_hi:[1,1,0]
	v_mad_i64_i32 v[116:117], s[0:1], v179, s93, v[76:77]
	v_pk_mul_f32 v[182:183], v[182:183], v[186:187]
	s_nop 0
	v_pk_mul_f32 v[182:183], v[184:185], v[182:183]
	s_nop 0
	v_max_f32_e32 v184, 0, v118
	v_max_f32_e32 v185, 0, v119
	v_fma_f32 v118, -|v118|, v182, v184
	v_fma_f32 v119, -|v119|, v183, v185
	s_nop 1
	v_pk_mul_f32 v[78:79], v[118:119], v[78:79]
	s_nop 0
	v_cvt_pk_bf16_f32 v103, v78, v79
	v_lshlrev_b64 v[78:79], 1, v[180:181]
	v_lshl_add_u64 v[116:117], v[116:117], 0, v[78:79]
	global_store_dwordx4 v[116:117], v[100:103], off
	s_nop 1
	v_fma_f32 v100, |v120|, s58, 1.0
	v_fma_f32 v101, |v121|, s58, 1.0
	v_pk_mul_f32 v[116:117], v[120:121], v[120:121]
	v_rcp_f32_e32 v100, v100
	v_rcp_f32_e32 v101, v101
	v_pk_mul_f32 v[116:117], v[116:117], s[50:51] op_sel_hi:[1,0]
	v_exp_f32_e32 v116, v116
	v_pk_fma_f32 v[102:103], v[100:101], s[60:61], v[128:129] op_sel_hi:[1,0,0]
	v_exp_f32_e32 v117, v117
	v_pk_fma_f32 v[102:103], v[100:101], v[102:103], s[62:63] op_sel_hi:[1,1,0]
	v_add_u32_e32 v124, 16, v179
	v_pk_fma_f32 v[102:103], v[100:101], v[102:103], s[64:65] op_sel_hi:[1,1,0]
	v_pk_fma_f32 v[102:103], v[100:101], v[102:103], s[66:67] op_sel_hi:[1,1,0]
	v_pk_mul_f32 v[100:101], v[100:101], v[102:103]
	v_pk_mul_f32 v[102:103], v[122:123], v[122:123]
	v_pk_mul_f32 v[100:101], v[116:117], v[100:101]
	v_pk_mul_f32 v[102:103], v[102:103], s[50:51] op_sel_hi:[1,0]
	v_max_f32_e32 v116, 0, v120
	v_max_f32_e32 v117, 0, v121
	v_exp_f32_e32 v102, v102
	v_fma_f32 v100, -|v120|, v100, v116
	v_fma_f32 v101, -|v121|, v101, v117
	v_exp_f32_e32 v103, v103
	v_fma_f32 v116, |v122|, s58, 1.0
	v_fma_f32 v117, |v123|, s58, 1.0
	v_rcp_f32_e32 v116, v116
	v_rcp_f32_e32 v117, v117
; __device__ __forceinline__ u32x4 pack8(f32x4 v0, f32x4 v1) { u32x4 w; w.x = cvt_pk_bf16(v0[0], v0[1]); w.y = cvt_pk_bf16(v0[2], v0[3]); w.z = cvt_pk_bf16(v1[0], v1[1]); w.w = cvt_pk_bf16(v1[2], v1[3]); return w; }
; __device__ __forceinline__ f32x4 gelu4(f32x4 v) { f32x2 a = gelu_pk((f32x2){v[0], v[1]}), b = gelu_pk((f32x2){v[2], v[3]}); return (f32x4){a.x, a.y, b.x, b.y}; }
; __device__ __forceinline__ f32x2 gelu_pk(f32x2 v) {
;     const f32x2 av = __builtin_elementwise_abs(v), d = av * 0.2316418882f + 1.0f;
;     f32x2 t; t.x = __builtin_amdgcn_rcpf(d.x); t.y = __builtin_amdgcn_rcpf(d.y);
;     f32x2 q = t * 0.5307027145f + (-0.7265760135f); q = q * t + 0.7107068705f; q = q * t + (-0.142248368f); q = q * t + 0.127414796f; q = q * t;
;     const f32x2 s = (v * v) * (-0.72134752044f);
;     f32x2 e; e.x = __builtin_amdgcn_exp2f(s.x); e.y = __builtin_amdgcn_exp2f(s.y);
;     const f32x2 m = v * (q * e), r = v - m;
;     f32x2 o; o.x = v.x < 0.f ? m.x : r.x; o.y = v.y < 0.f ? m.y : r.y; return o;
;     __device__ __forceinline__ void operator()(f32x4 (&acc)[2][2][4][2], const Unit& u, int wr, int wc, int fr_, int fq_) const {
;     ...
;             for (int m = 0; m < 4; ++m) { const int row = u.pm * BM + blk * 64 + m * 16 + fr;
;                 const f32x4 g0 = gelu4(acc[ai][0][m][0]), g1 = gelu4(acc[ai][0][m][1]);
;                 *(u32x4*)(ACT + (size_t)row * 5632 + jcol) = pack8(g0 * acc[ai][1][m][0], g1 * acc[ai][1][m][1]); asm volatile("" ::: "memory"); __builtin_amdgcn_sched_barrier(0); }
	v_pk_mul_f32 v[120:121], v[112:113], v[112:113]
	v_pk_mul_f32 v[96:97], v[100:101], v[96:97]
	v_pk_mul_f32 v[120:121], v[120:121], s[50:51] op_sel_hi:[1,0]
	v_pk_fma_f32 v[118:119], v[116:117], s[60:61], v[128:129] op_sel_hi:[1,0,0]
	v_exp_f32_e32 v120, v120
	v_pk_fma_f32 v[118:119], v[116:117], v[118:119], s[62:63] op_sel_hi:[1,1,0]
	v_exp_f32_e32 v121, v121
	v_pk_fma_f32 v[118:119], v[116:117], v[118:119], s[64:65] op_sel_hi:[1,1,0]
	v_pk_fma_f32 v[118:119], v[116:117], v[118:119], s[66:67] op_sel_hi:[1,1,0]
	v_pk_mul_f32 v[116:117], v[116:117], v[118:119]
	v_pk_mul_f32 v[102:103], v[102:103], v[116:117]
	v_max_f32_e32 v116, 0, v122
	v_max_f32_e32 v117, 0, v123
	v_fma_f32 v102, -|v122|, v102, v116
	v_fma_f32 v103, -|v123|, v103, v117
	s_nop 0
	v_fma_f32 v116, |v112|, s58, 1.0
	v_fma_f32 v117, |v113|, s58, 1.0
	v_rcp_f32_e32 v116, v116
	v_rcp_f32_e32 v117, v117
	v_pk_mul_f32 v[98:99], v[102:103], v[98:99]
	v_pk_fma_f32 v[118:119], v[116:117], s[60:61], v[128:129] op_sel_hi:[1,0,0]
	v_pk_fma_f32 v[118:119], v[116:117], v[118:119], s[62:63] op_sel_hi:[1,1,0]
	v_pk_fma_f32 v[118:119], v[116:117], v[118:119], s[64:65] op_sel_hi:[1,1,0]
	v_pk_fma_f32 v[118:119], v[116:117], v[118:119], s[66:67] op_sel_hi:[1,1,0]
	v_pk_mul_f32 v[116:117], v[116:117], v[118:119]
	v_pk_mul_f32 v[118:119], v[114:115], v[114:115]
	v_pk_mul_f32 v[116:117], v[120:121], v[116:117]
	v_pk_mul_f32 v[118:119], v[118:119], s[50:51] op_sel_hi:[1,0]
	v_max_f32_e32 v120, 0, v112
	v_max_f32_e32 v121, 0, v113
	v_exp_f32_e32 v118, v118
	v_fma_f32 v112, -|v112|, v116, v120
	v_fma_f32 v113, -|v113|, v117, v121
	v_exp_f32_e32 v119, v119
	v_fma_f32 v116, |v114|, s58, 1.0
	v_fma_f32 v117, |v115|, s58, 1.0
	v_rcp_f32_e32 v116, v116
	v_rcp_f32_e32 v117, v117
	s_nop 0
	v_pk_fma_f32 v[120:121], v[116:117], s[60:61], v[128:129] op_sel_hi:[1,0,0]
	v_pk_fma_f32 v[120:121], v[116:117], v[120:121], s[62:63] op_sel_hi:[1,1,0]
	v_pk_fma_f32 v[120:121], v[116:117], v[120:121], s[64:65] op_sel_hi:[1,1,0]
	v_pk_fma_f32 v[120:121], v[116:117], v[120:121], s[66:67] op_sel_hi:[1,1,0]
	v_pk_mul_f32 v[116:117], v[116:117], v[120:121]
	v_pk_mul_f32 v[116:117], v[118:119], v[116:117]
	v_max_f32_e32 v118, 0, v114
	v_max_f32_e32 v119, 0, v115
	v_fma_f32 v114, -|v114|, v116, v118
	v_fma_f32 v115, -|v115|, v117, v119
	s_nop 1
	v_pk_mul_f32 v[100:101], v[114:115], v[74:75]
	v_pk_mul_f32 v[74:75], v[112:113], v[72:73]
	v_cvt_pk_bf16_f32 v72, v96, v97
	v_mad_i64_i32 v[96:97], s[0:1], v124, s93, v[76:77]
	v_cvt_pk_bf16_f32 v73, v98, v99
	v_cvt_pk_bf16_f32 v74, v74, v75
	v_cvt_pk_bf16_f32 v75, v100, v101
	v_lshl_add_u64 v[96:97], v[96:97], 0, v[78:79]
	global_store_dwordx4 v[96:97], v[72:75], off
	s_nop 1
	v_fma_f32 v72, |v104|, s58, 1.0
	v_fma_f32 v73, |v105|, s58, 1.0
	v_pk_mul_f32 v[96:97], v[104:105], v[104:105]
	v_rcp_f32_e32 v72, v72
	v_rcp_f32_e32 v73, v73
	v_pk_mul_f32 v[96:97], v[96:97], s[50:51] op_sel_hi:[1,0]
	v_exp_f32_e32 v96, v96
	v_pk_fma_f32 v[74:75], v[72:73], s[60:61], v[128:129] op_sel_hi:[1,0,0]
	v_exp_f32_e32 v97, v97
	v_pk_fma_f32 v[74:75], v[72:73], v[74:75], s[62:63] op_sel_hi:[1,1,0]
	v_pk_mul_f32 v[100:101], v[108:109], v[108:109]
	v_pk_fma_f32 v[74:75], v[72:73], v[74:75], s[64:65] op_sel_hi:[1,1,0]
	v_pk_mul_f32 v[100:101], v[100:101], s[50:51] op_sel_hi:[1,0]
	v_pk_fma_f32 v[74:75], v[72:73], v[74:75], s[66:67] op_sel_hi:[1,1,0]
	v_exp_f32_e32 v100, v100
	v_pk_mul_f32 v[72:73], v[72:73], v[74:75]
	v_pk_mul_f32 v[74:75], v[106:107], v[106:107]
	v_pk_mul_f32 v[72:73], v[96:97], v[72:73]
	v_pk_mul_f32 v[74:75], v[74:75], s[50:51] op_sel_hi:[1,0]
	v_max_f32_e32 v96, 0, v104
	v_max_f32_e32 v97, 0, v105
	v_exp_f32_e32 v74, v74
	v_fma_f32 v72, -|v104|, v72, v96
	v_fma_f32 v73, -|v105|, v73, v97
	v_exp_f32_e32 v75, v75
	v_fma_f32 v96, |v106|, s58, 1.0
	v_fma_f32 v97, |v107|, s58, 1.0
	v_rcp_f32_e32 v96, v96
	v_rcp_f32_e32 v97, v97
	v_exp_f32_e32 v101, v101
	v_add_u32_e32 v112, 32, v179
	v_pk_mul_f32 v[72:73], v[72:73], v[88:89]
	v_pk_fma_f32 v[98:99], v[96:97], s[60:61], v[128:129] op_sel_hi:[1,0,0]
	v_pk_fma_f32 v[98:99], v[96:97], v[98:99], s[62:63] op_sel_hi:[1,1,0]
	v_pk_fma_f32 v[98:99], v[96:97], v[98:99], s[64:65] op_sel_hi:[1,1,0]
	v_pk_fma_f32 v[98:99], v[96:97], v[98:99], s[66:67] op_sel_hi:[1,1,0]
	v_pk_mul_f32 v[96:97], v[96:97], v[98:99]
	v_pk_mul_f32 v[74:75], v[74:75], v[96:97]
	v_max_f32_e32 v96, 0, v106
	v_max_f32_e32 v97, 0, v107
	v_fma_f32 v74, -|v106|, v74, v96
	v_fma_f32 v75, -|v107|, v75, v97
	s_nop 0
	v_fma_f32 v96, |v108|, s58, 1.0
	v_fma_f32 v97, |v109|, s58, 1.0
	v_rcp_f32_e32 v96, v96
	v_rcp_f32_e32 v97, v97
	v_pk_mul_f32 v[74:75], v[74:75], v[90:91]
	v_pk_fma_f32 v[98:99], v[96:97], s[60:61], v[128:129] op_sel_hi:[1,0,0]
	v_pk_fma_f32 v[98:99], v[96:97], v[98:99], s[62:63] op_sel_hi:[1,1,0]
	v_pk_fma_f32 v[98:99], v[96:97], v[98:99], s[64:65] op_sel_hi:[1,1,0]
	v_pk_fma_f32 v[98:99], v[96:97], v[98:99], s[66:67] op_sel_hi:[1,1,0]
	v_pk_mul_f32 v[96:97], v[96:97], v[98:99]
	v_pk_mul_f32 v[98:99], v[110:111], v[110:111]
	v_pk_mul_f32 v[96:97], v[100:101], v[96:97]
	v_pk_mul_f32 v[98:99], v[98:99], s[50:51] op_sel_hi:[1,0]
	v_max_f32_e32 v100, 0, v108
	v_max_f32_e32 v101, 0, v109
	v_exp_f32_e32 v98, v98
	v_fma_f32 v96, -|v108|, v96, v100
	v_fma_f32 v97, -|v109|, v97, v101
	v_exp_f32_e32 v99, v99
	v_fma_f32 v100, |v110|, s58, 1.0
	v_fma_f32 v101, |v111|, s58, 1.0
	v_rcp_f32_e32 v100, v100
	v_rcp_f32_e32 v101, v101
	s_nop 0
	v_pk_fma_f32 v[102:103], v[100:101], s[60:61], v[128:129] op_sel_hi:[1,0,0]
	v_pk_fma_f32 v[102:103], v[100:101], v[102:103], s[62:63] op_sel_hi:[1,1,0]
	v_pk_fma_f32 v[102:103], v[100:101], v[102:103], s[64:65] op_sel_hi:[1,1,0]
; #define PG8_LAS __attribute__((address_space(3)))
; __device__ __forceinline__ u32x4 pack8(f32x4 v0, f32x4 v1) { u32x4 w; w.x = cvt_pk_bf16(v0[0], v0[1]); w.y = cvt_pk_bf16(v0[2], v0[3]); w.z = cvt_pk_bf16(v1[0], v1[1]); w.w = cvt_pk_bf16(v1[2], v1[3]); return w; }
; __device__ __forceinline__ f32x4 gelu4(f32x4 v) { f32x2 a = gelu_pk((f32x2){v[0], v[1]}), b = gelu_pk((f32x2){v[2], v[3]}); return (f32x4){a.x, a.y, b.x, b.y}; }
; __device__ __forceinline__ f32x2 gelu_pk(f32x2 v) {
;     const f32x2 av = __builtin_elementwise_abs(v), d = av * 0.2316418882f + 1.0f;
;     f32x2 t; t.x = __builtin_amdgcn_rcpf(d.x); t.y = __builtin_amdgcn_rcpf(d.y);
;     f32x2 q = t * 0.5307027145f + (-0.7265760135f); q = q * t + 0.7107068705f; q = q * t + (-0.142248368f); q = q * t + 0.127414796f; q = q * t;
;     const f32x2 s = (v * v) * (-0.72134752044f);
;     f32x2 e; e.x = __builtin_amdgcn_exp2f(s.x); e.y = __builtin_amdgcn_exp2f(s.y);
;     const f32x2 m = v * (q * e), r = v - m;
;     f32x2 o; o.x = v.x < 0.f ? m.x : r.x; o.y = v.y < 0.f ? m.y : r.y; return o;
;     __device__ __forceinline__ void operator()(f32x4 (&acc)[2][2][4][2], const Unit& u, int wr, int wc, int fr_, int fq_) const {
;     ...
;                     const int cidx = bj * 5632 + jcol + 4 * n;
;                     const f32x4 w0 = *(const f32x4*)(cw + cidx), w1 = *(const f32x4*)(cw + 11264 + cidx), w2 = *(const f32x4*)(cw + 22528 + cidx), b4 = *(const f32x4*)(cb + cidx);
;                     f32x4 pR1 = (f32x4){0.f, 0.f, 0.f, 0.f}, pR2 = pR1;
;                     if (blk) { const f32x4 h14 = *(const PG8_LAS f32x4*)(hal + ((blk - 1) * 2 + 0) * 256 + ct) * rs14, h15 = *(const PG8_LAS f32x4*)(hal + ((blk - 1) * 2 + 1) * 256 + ct) * rs15;
;     ...
;             for (int m = 0; m < 4; ++m) { const int row = u.pm * BM + blk * 64 + m * 16 + fr;
;                 const f32x4 g0 = gelu4(acc[ai][0][m][0]), g1 = gelu4(acc[ai][0][m][1]);
;                 *(u32x4*)(ACT + (size_t)row * 5632 + jcol) = pack8(g0 * acc[ai][1][m][0], g1 * acc[ai][1][m][1]); asm volatile("" ::: "memory"); __builtin_amdgcn_sched_barrier(0); }
	v_pk_fma_f32 v[102:103], v[100:101], v[102:103], s[66:67] op_sel_hi:[1,1,0]
	v_pk_mul_f32 v[100:101], v[100:101], v[102:103]
	v_pk_mul_f32 v[98:99], v[98:99], v[100:101]
	v_max_f32_e32 v100, 0, v110
	v_max_f32_e32 v101, 0, v111
	v_fma_f32 v98, -|v110|, v98, v100
	v_fma_f32 v99, -|v111|, v99, v101
	s_nop 1
	v_pk_mul_f32 v[88:89], v[98:99], v[70:71]
	v_pk_mul_f32 v[70:71], v[96:97], v[68:69]
	v_cvt_pk_bf16_f32 v68, v72, v73
	v_mad_i64_i32 v[72:73], s[0:1], v112, s93, v[76:77]
	v_cvt_pk_bf16_f32 v69, v74, v75
	v_cvt_pk_bf16_f32 v70, v70, v71
	v_cvt_pk_bf16_f32 v71, v88, v89
	v_lshl_add_u64 v[72:73], v[72:73], 0, v[78:79]
	global_store_dwordx4 v[72:73], v[68:71], off
	s_nop 1
	v_fma_f32 v68, |v80|, s58, 1.0
	v_fma_f32 v69, |v81|, s58, 1.0
	v_pk_mul_f32 v[72:73], v[80:81], v[80:81]
	v_rcp_f32_e32 v68, v68
	v_rcp_f32_e32 v69, v69
	v_pk_mul_f32 v[72:73], v[72:73], s[50:51] op_sel_hi:[1,0]
	v_exp_f32_e32 v72, v72
	v_pk_fma_f32 v[70:71], v[68:69], s[60:61], v[128:129] op_sel_hi:[1,0,0]
	v_exp_f32_e32 v73, v73
	v_pk_fma_f32 v[70:71], v[68:69], v[70:71], s[62:63] op_sel_hi:[1,1,0]
	v_add_u32_e32 v88, 48, v179
	v_pk_fma_f32 v[70:71], v[68:69], v[70:71], s[64:65] op_sel_hi:[1,1,0]
	v_pk_fma_f32 v[70:71], v[68:69], v[70:71], s[66:67] op_sel_hi:[1,1,0]
	v_pk_mul_f32 v[68:69], v[68:69], v[70:71]
	v_pk_mul_f32 v[70:71], v[82:83], v[82:83]
	v_pk_mul_f32 v[68:69], v[72:73], v[68:69]
	v_pk_mul_f32 v[70:71], v[70:71], s[50:51] op_sel_hi:[1,0]
	v_max_f32_e32 v72, 0, v80
	v_max_f32_e32 v73, 0, v81
	v_exp_f32_e32 v70, v70
	v_fma_f32 v68, -|v80|, v68, v72
	v_fma_f32 v69, -|v81|, v69, v73
	v_exp_f32_e32 v71, v71
	v_fma_f32 v72, |v82|, s58, 1.0
	v_fma_f32 v73, |v83|, s58, 1.0
	v_rcp_f32_e32 v72, v72
	v_rcp_f32_e32 v73, v73
	v_pk_mul_f32 v[80:81], v[92:93], v[92:93]
	v_pk_mul_f32 v[68:69], v[68:69], v[84:85]
	v_pk_mul_f32 v[80:81], v[80:81], s[50:51] op_sel_hi:[1,0]
	v_pk_fma_f32 v[74:75], v[72:73], s[60:61], v[128:129] op_sel_hi:[1,0,0]
	v_exp_f32_e32 v80, v80
	v_pk_fma_f32 v[74:75], v[72:73], v[74:75], s[62:63] op_sel_hi:[1,1,0]
	v_exp_f32_e32 v81, v81
	v_pk_fma_f32 v[74:75], v[72:73], v[74:75], s[64:65] op_sel_hi:[1,1,0]
	v_pk_fma_f32 v[74:75], v[72:73], v[74:75], s[66:67] op_sel_hi:[1,1,0]
	v_pk_mul_f32 v[72:73], v[72:73], v[74:75]
	v_pk_mul_f32 v[70:71], v[70:71], v[72:73]
	v_max_f32_e32 v72, 0, v82
	v_max_f32_e32 v73, 0, v83
	v_fma_f32 v70, -|v82|, v70, v72
	v_fma_f32 v71, -|v83|, v71, v73
	s_nop 0
	v_fma_f32 v72, |v92|, s58, 1.0
	v_fma_f32 v73, |v93|, s58, 1.0
	v_rcp_f32_e32 v72, v72
	v_rcp_f32_e32 v73, v73
	v_pk_mul_f32 v[70:71], v[70:71], v[86:87]
	v_pk_fma_f32 v[74:75], v[72:73], s[60:61], v[128:129] op_sel_hi:[1,0,0]
	v_pk_fma_f32 v[74:75], v[72:73], v[74:75], s[62:63] op_sel_hi:[1,1,0]
	v_pk_fma_f32 v[74:75], v[72:73], v[74:75], s[64:65] op_sel_hi:[1,1,0]
	v_pk_fma_f32 v[74:75], v[72:73], v[74:75], s[66:67] op_sel_hi:[1,1,0]
	v_pk_mul_f32 v[72:73], v[72:73], v[74:75]
	v_pk_mul_f32 v[74:75], v[94:95], v[94:95]
	v_pk_mul_f32 v[72:73], v[80:81], v[72:73]
	v_pk_mul_f32 v[74:75], v[74:75], s[50:51] op_sel_hi:[1,0]
	v_max_f32_e32 v80, 0, v92
	v_max_f32_e32 v81, 0, v93
	v_exp_f32_e32 v74, v74
	v_fma_f32 v72, -|v92|, v72, v80
	v_fma_f32 v73, -|v93|, v73, v81
	v_exp_f32_e32 v75, v75
	v_fma_f32 v80, |v94|, s58, 1.0
	v_fma_f32 v81, |v95|, s58, 1.0
	v_rcp_f32_e32 v80, v80
	v_rcp_f32_e32 v81, v81
	s_nop 0
	v_pk_fma_f32 v[82:83], v[80:81], s[60:61], v[128:129] op_sel_hi:[1,0,0]
	v_pk_fma_f32 v[82:83], v[80:81], v[82:83], s[62:63] op_sel_hi:[1,1,0]
	v_pk_fma_f32 v[82:83], v[80:81], v[82:83], s[64:65] op_sel_hi:[1,1,0]
	v_pk_fma_f32 v[82:83], v[80:81], v[82:83], s[66:67] op_sel_hi:[1,1,0]
	v_pk_mul_f32 v[80:81], v[80:81], v[82:83]
	v_pk_mul_f32 v[74:75], v[74:75], v[80:81]
	v_max_f32_e32 v80, 0, v94
	v_max_f32_e32 v81, 0, v95
	v_fma_f32 v74, -|v94|, v74, v80
	v_fma_f32 v75, -|v95|, v75, v81
	s_nop 1
	v_pk_mul_f32 v[74:75], v[74:75], v[66:67]
	v_pk_mul_f32 v[66:67], v[72:73], v[64:65]
	v_cvt_pk_bf16_f32 v64, v68, v69
	v_mad_i64_i32 v[68:69], s[0:1], v88, s93, v[76:77]
	v_cvt_pk_bf16_f32 v65, v70, v71
	v_cvt_pk_bf16_f32 v66, v66, v67
	v_cvt_pk_bf16_f32 v67, v74, v75
	v_lshl_add_u64 v[68:69], v[68:69], 0, v[78:79]
	global_store_dwordx4 v[68:69], v[64:67], off
	global_load_dwordx4 v[80:83], v[166:167], off
	global_load_dwordx4 v[84:87], v[164:165], off
	global_load_dwordx4 v[88:91], v[168:169], off
	global_load_dwordx4 v[92:95], v[170:171], off
	v_mov_b32_e32 v65, s96
	v_add_u32_e32 v71, s97, v154
	ds_read_b64 v[66:67], v65
	ds_read_b128 v[96:99], v71
	v_add_u32_e32 v64, s89, v225
	v_add_u32_e32 v73, s14, v154
	ds_read_b128 v[100:103], v73
	ds_read2_b32 v[68:69], v64 offset1:16
	ds_read2_b32 v[64:65], v64 offset0:32 offset1:48
	s_waitcnt lgkmcnt(3)
	v_pk_mul_f32 v[74:75], v[66:67], v[98:99] op_sel_hi:[0,1]
	v_pk_mul_f32 v[96:97], v[66:67], v[96:97] op_sel_hi:[0,1]
	s_waitcnt lgkmcnt(2)
	v_pk_mul_f32 v[98:99], v[66:67], v[102:103] op_sel:[1,0]
	v_pk_mul_f32 v[100:101], v[66:67], v[100:101] op_sel:[1,0]
	v_cndmask_b32_e64 v70, v99, v75, s[10:11]
	v_cndmask_b32_e64 v72, v98, v74, s[10:11]
	v_cndmask_b32_e64 v102, v101, v97, s[10:11]
	v_cndmask_b32_e64 v103, v100, v96, s[10:11]
	s_waitcnt lgkmcnt(1)
; #define PG8_LAS __attribute__((address_space(3)))
; __device__ __forceinline__ float dpp_ror1(float x) { float r; asm volatile("s_nop 1\n\tv_mov_b32_dpp %0, %1 row_ror:1 row_mask:0xf bank_mask:0xf" : "=&v"(r) : "v"(x)); return r; }
; __device__ __forceinline__ float dpp_ror2(float x) { float r; asm volatile("s_nop 1\n\tv_mov_b32_dpp %0, %1 row_ror:2 row_mask:0xf bank_mask:0xf" : "=&v"(r) : "v"(x)); return r; }
;     __device__ __forceinline__ void operator()(f32x4 (&acc)[2][2][4][2], const Unit& u, int wr, int wc, int fr_, int fq_) const {
;     ...
;                     const f32x4 w0 = *(const f32x4*)(cw + cidx), w1 = *(const f32x4*)(cw + 11264 + cidx), w2 = *(const f32x4*)(cw + 22528 + cidx), b4 = *(const f32x4*)(cb + cidx);
;                     f32x4 pR1 = (f32x4){0.f, 0.f, 0.f, 0.f}, pR2 = pR1;
;                     if (blk) { const f32x4 h14 = *(const PG8_LAS f32x4*)(hal + ((blk - 1) * 2 + 0) * 256 + ct) * rs14, h15 = *(const PG8_LAS f32x4*)(hal + ((blk - 1) * 2 + 1) * 256 + ct) * rs15;
;                         pR1 = h15; pR2 = (fr == 0) ? h14 : h15; }
; #pragma unroll
;                     for (int m = 0; m < 4; ++m) {
;                         const f32x4 U = acc[ai][bj][m][n] * rsr[m];
;                         f32x4 R1, R2;
; #pragma unroll
;                         for (int i = 0; i < 4; ++i) { R1[i] = dpp_ror1(U[i]); R2[i] = dpp_ror2(U[i]); }
;                         const f32x4 U1 = (fr >= 1) ? R1 : pR1, U2 = (fr >= 2) ? R2 : pR2;
;                         const f32x4 C = b4 + w0 * U2 + w1 * U1 + w2 * U;
;                         acc[ai][bj][m][n] = C; pR1 = R1; pR2 = R2;
	v_pk_mul_f32 v[62:63], v[62:63], v[68:69] op_sel_hi:[1,0]
	v_pk_mul_f32 v[60:61], v[60:61], v[68:69] op_sel_hi:[1,0]
	s_nop 0
	s_nop 1
	v_mov_b32_dpp v104, v60 row_ror:1 row_mask:0xf bank_mask:0xf
	v_mov_b32_dpp v105, v60 row_ror:2 row_mask:0xf bank_mask:0xf
	v_mov_b32_dpp v106, v61 row_ror:1 row_mask:0xf bank_mask:0xf
	v_mov_b32_dpp v107, v61 row_ror:2 row_mask:0xf bank_mask:0xf
	v_mov_b32_dpp v108, v62 row_ror:1 row_mask:0xf bank_mask:0xf
	v_mov_b32_dpp v109, v62 row_ror:2 row_mask:0xf bank_mask:0xf
	v_mov_b32_dpp v110, v63 row_ror:1 row_mask:0xf bank_mask:0xf
	v_mov_b32_dpp v111, v63 row_ror:2 row_mask:0xf bank_mask:0xf
	v_cndmask_b32_e64 v96, v100, v104, s[6:7]
	v_cndmask_b32_e64 v74, v98, v108, s[6:7]
	v_cndmask_b32_e64 v75, v99, v110, s[6:7]
	v_cndmask_b32_e64 v97, v101, v106, s[6:7]
	v_cndmask_b32_e64 v98, v72, v109, s[8:9]
	v_cndmask_b32_e64 v99, v70, v111, s[8:9]
	v_cndmask_b32_e64 v100, v103, v105, s[8:9]
	v_cndmask_b32_e64 v101, v102, v107, s[8:9]
	s_waitcnt vmcnt(2)
	v_pk_fma_f32 v[98:99], v[86:87], v[98:99], v[82:83]
	v_pk_fma_f32 v[100:101], v[84:85], v[100:101], v[80:81]
	s_waitcnt vmcnt(1)
	v_pk_fma_f32 v[74:75], v[90:91], v[74:75], v[98:99]
	v_pk_fma_f32 v[96:97], v[88:89], v[96:97], v[100:101]
	s_waitcnt vmcnt(0)
	v_pk_fma_f32 v[62:63], v[62:63], v[94:95], v[74:75]
	v_pk_fma_f32 v[60:61], v[60:61], v[92:93], v[96:97]
	v_mov_b32_e32 v70, v69
	v_pk_mul_f32 v[58:59], v[58:59], v[70:71] op_sel_hi:[1,0]
	v_pk_mul_f32 v[56:57], v[56:57], v[70:71] op_sel_hi:[1,0]
	s_nop 1
	v_mov_b32_dpp v69, v56 row_ror:1 row_mask:0xf bank_mask:0xf
	v_mov_b32_dpp v72, v56 row_ror:2 row_mask:0xf bank_mask:0xf
	v_mov_b32_dpp v102, v57 row_ror:1 row_mask:0xf bank_mask:0xf
	v_mov_b32_dpp v103, v57 row_ror:2 row_mask:0xf bank_mask:0xf
	v_mov_b32_dpp v112, v58 row_ror:1 row_mask:0xf bank_mask:0xf
	v_mov_b32_dpp v113, v58 row_ror:2 row_mask:0xf bank_mask:0xf
	v_mov_b32_dpp v114, v59 row_ror:1 row_mask:0xf bank_mask:0xf
	v_mov_b32_dpp v115, v59 row_ror:2 row_mask:0xf bank_mask:0xf
	v_cndmask_b32_e64 v100, v105, v72, s[8:9]
	v_cndmask_b32_e64 v98, v109, v113, s[8:9]
	v_cndmask_b32_e64 v99, v111, v115, s[8:9]
	v_cndmask_b32_e64 v101, v107, v103, s[8:9]
	v_cndmask_b32_e64 v74, v108, v112, s[6:7]
	v_cndmask_b32_e64 v75, v110, v114, s[6:7]
	v_cndmask_b32_e64 v96, v104, v69, s[6:7]
	v_cndmask_b32_e64 v97, v106, v102, s[6:7]
	v_pk_fma_f32 v[98:99], v[86:87], v[98:99], v[82:83]
	v_pk_fma_f32 v[100:101], v[84:85], v[100:101], v[80:81]
	v_pk_fma_f32 v[74:75], v[90:91], v[74:75], v[98:99]
	v_pk_fma_f32 v[96:97], v[88:89], v[96:97], v[100:101]
	v_pk_fma_f32 v[58:59], v[58:59], v[94:95], v[74:75]
	v_pk_fma_f32 v[56:57], v[56:57], v[92:93], v[96:97]
	s_nop 0
	s_waitcnt lgkmcnt(0)
	v_pk_mul_f32 v[54:55], v[54:55], v[64:65] op_sel_hi:[1,0]
	v_pk_mul_f32 v[52:53], v[52:53], v[64:65] op_sel_hi:[1,0]
	s_nop 0
	s_nop 1
	v_mov_b32_dpp v104, v52 row_ror:1 row_mask:0xf bank_mask:0xf
	v_mov_b32_dpp v105, v52 row_ror:2 row_mask:0xf bank_mask:0xf
	v_mov_b32_dpp v106, v53 row_ror:1 row_mask:0xf bank_mask:0xf
	v_mov_b32_dpp v107, v53 row_ror:2 row_mask:0xf bank_mask:0xf
	v_mov_b32_dpp v108, v54 row_ror:1 row_mask:0xf bank_mask:0xf
	v_mov_b32_dpp v109, v54 row_ror:2 row_mask:0xf bank_mask:0xf
	v_mov_b32_dpp v110, v55 row_ror:1 row_mask:0xf bank_mask:0xf
	v_mov_b32_dpp v111, v55 row_ror:2 row_mask:0xf bank_mask:0xf
	v_cndmask_b32_e64 v100, v72, v105, s[8:9]
	v_cndmask_b32_e64 v98, v113, v109, s[8:9]
	v_cndmask_b32_e64 v99, v115, v111, s[8:9]
	v_cndmask_b32_e64 v101, v103, v107, s[8:9]
	v_cndmask_b32_e64 v74, v112, v108, s[6:7]
	v_cndmask_b32_e64 v75, v114, v110, s[6:7]
	v_cndmask_b32_e64 v96, v69, v104, s[6:7]
	v_cndmask_b32_e64 v97, v102, v106, s[6:7]
	v_pk_fma_f32 v[98:99], v[86:87], v[98:99], v[82:83]
	v_pk_fma_f32 v[100:101], v[84:85], v[100:101], v[80:81]
	v_pk_fma_f32 v[74:75], v[90:91], v[74:75], v[98:99]
	v_pk_fma_f32 v[96:97], v[88:89], v[96:97], v[100:101]
	v_pk_fma_f32 v[54:55], v[54:55], v[94:95], v[74:75]
	v_pk_fma_f32 v[52:53], v[52:53], v[92:93], v[96:97]
	v_mov_b32_e32 v72, v65
	v_pk_mul_f32 v[50:51], v[50:51], v[72:73] op_sel_hi:[1,0]
	v_pk_mul_f32 v[48:49], v[48:49], v[72:73] op_sel_hi:[1,0]
	s_nop 1
	v_mov_b32_dpp v65, v48 row_ror:1 row_mask:0xf bank_mask:0xf
	v_mov_b32_dpp v69, v48 row_ror:2 row_mask:0xf bank_mask:0xf
	v_mov_b32_dpp v97, v49 row_ror:1 row_mask:0xf bank_mask:0xf
	v_mov_b32_dpp v101, v49 row_ror:2 row_mask:0xf bank_mask:0xf
	v_mov_b32_dpp v74, v50 row_ror:1 row_mask:0xf bank_mask:0xf
	v_mov_b32_dpp v98, v50 row_ror:2 row_mask:0xf bank_mask:0xf
	v_mov_b32_dpp v75, v51 row_ror:1 row_mask:0xf bank_mask:0xf
	v_mov_b32_dpp v99, v51 row_ror:2 row_mask:0xf bank_mask:0xf
	v_cndmask_b32_e64 v100, v105, v69, s[8:9]
	v_cndmask_b32_e64 v98, v109, v98, s[8:9]
	v_cndmask_b32_e64 v99, v111, v99, s[8:9]
	v_cndmask_b32_e64 v101, v107, v101, s[8:9]
	v_cndmask_b32_e64 v74, v108, v74, s[6:7]
	v_cndmask_b32_e64 v75, v110, v75, s[6:7]
	v_cndmask_b32_e64 v96, v104, v65, s[6:7]
	v_cndmask_b32_e64 v97, v106, v97, s[6:7]
	v_pk_fma_f32 v[82:83], v[86:87], v[98:99], v[82:83]
	v_pk_fma_f32 v[80:81], v[84:85], v[100:101], v[80:81]
	v_pk_fma_f32 v[74:75], v[90:91], v[74:75], v[82:83]
	v_pk_fma_f32 v[80:81], v[88:89], v[96:97], v[80:81]
	v_pk_fma_f32 v[50:51], v[50:51], v[94:95], v[74:75]
	v_pk_fma_f32 v[48:49], v[48:49], v[92:93], v[80:81]
	s_nop 0
	global_load_dwordx4 v[80:83], v[164:165], off offset:16
	global_load_dwordx4 v[84:87], v[166:167], off offset:16
	global_load_dwordx4 v[88:91], v[172:173], off
	global_load_dwordx4 v[92:95], v[174:175], off
	v_pk_mul_f32 v[74:75], v[46:47], v[68:69] op_sel_hi:[1,0]
	v_pk_mul_f32 v[100:101], v[44:45], v[68:69] op_sel_hi:[1,0]
	ds_read_b128 v[44:47], v71 offset:16
	ds_read_b128 v[96:99], v73 offset:16
	s_nop 1
	v_mov_b32_dpp v65, v100 row_ror:1 row_mask:0xf bank_mask:0xf
	v_mov_b32_dpp v69, v100 row_ror:2 row_mask:0xf bank_mask:0xf
	v_mov_b32_dpp v102, v101 row_ror:1 row_mask:0xf bank_mask:0xf
	s_waitcnt lgkmcnt(1)
; #define PG8_LAS __attribute__((address_space(3)))
; __device__ __forceinline__ float dpp_ror1(float x) { float r; asm volatile("s_nop 1\n\tv_mov_b32_dpp %0, %1 row_ror:1 row_mask:0xf bank_mask:0xf" : "=&v"(r) : "v"(x)); return r; }
; __device__ __forceinline__ float dpp_ror2(float x) { float r; asm volatile("s_nop 1\n\tv_mov_b32_dpp %0, %1 row_ror:2 row_mask:0xf bank_mask:0xf" : "=&v"(r) : "v"(x)); return r; }
;     __device__ __forceinline__ void operator()(f32x4 (&acc)[2][2][4][2], const Unit& u, int wr, int wc, int fr_, int fq_) const {
;     ...
;                     const f32x4 w0 = *(const f32x4*)(cw + cidx), w1 = *(const f32x4*)(cw + 11264 + cidx), w2 = *(const f32x4*)(cw + 22528 + cidx), b4 = *(const f32x4*)(cb + cidx);
;                     f32x4 pR1 = (f32x4){0.f, 0.f, 0.f, 0.f}, pR2 = pR1;
;                     if (blk) { const f32x4 h14 = *(const PG8_LAS f32x4*)(hal + ((blk - 1) * 2 + 0) * 256 + ct) * rs14, h15 = *(const PG8_LAS f32x4*)(hal + ((blk - 1) * 2 + 1) * 256 + ct) * rs15;
;                         pR1 = h15; pR2 = (fr == 0) ? h14 : h15; }
; #pragma unroll
;                     for (int m = 0; m < 4; ++m) {
;                         const f32x4 U = acc[ai][bj][m][n] * rsr[m];
;                         f32x4 R1, R2;
; #pragma unroll
;                         for (int i = 0; i < 4; ++i) { R1[i] = dpp_ror1(U[i]); R2[i] = dpp_ror2(U[i]); }
;                         const f32x4 U1 = (fr >= 1) ? R1 : pR1, U2 = (fr >= 2) ? R2 : pR2;
;                         const f32x4 C = b4 + w0 * U2 + w1 * U1 + w2 * U;
;                         acc[ai][bj][m][n] = C; pR1 = R1; pR2 = R2;
	v_pk_mul_f32 v[46:47], v[66:67], v[46:47] op_sel_hi:[0,1]
	v_pk_mul_f32 v[44:45], v[66:67], v[44:45] op_sel_hi:[0,1]
	s_waitcnt lgkmcnt(0)
	v_pk_mul_f32 v[98:99], v[66:67], v[98:99] op_sel:[1,0]
	v_pk_mul_f32 v[96:97], v[66:67], v[96:97] op_sel:[1,0]
	v_cndmask_b32_e64 v108, v99, v47, s[10:11]
	v_cndmask_b32_e64 v109, v98, v46, s[10:11]
	v_cndmask_b32_e64 v110, v96, v44, s[10:11]
	v_cndmask_b32_e64 v111, v97, v45, s[10:11]
	s_nop 1
	v_mov_b32_dpp v103, v101 row_ror:2 row_mask:0xf bank_mask:0xf
	v_mov_b32_dpp v104, v74 row_ror:1 row_mask:0xf bank_mask:0xf
	v_mov_b32_dpp v105, v74 row_ror:2 row_mask:0xf bank_mask:0xf
	v_mov_b32_dpp v106, v75 row_ror:1 row_mask:0xf bank_mask:0xf
	v_mov_b32_dpp v107, v75 row_ror:2 row_mask:0xf bank_mask:0xf
	v_cndmask_b32_e64 v47, v97, v102, s[6:7]
	v_cndmask_b32_e64 v44, v98, v104, s[6:7]
	v_cndmask_b32_e64 v45, v99, v106, s[6:7]
	v_cndmask_b32_e64 v46, v96, v65, s[6:7]
	v_cndmask_b32_e64 v96, v109, v105, s[8:9]
	v_cndmask_b32_e64 v97, v108, v107, s[8:9]
	v_cndmask_b32_e64 v99, v111, v103, s[8:9]
	v_cndmask_b32_e64 v98, v110, v69, s[8:9]
	s_waitcnt vmcnt(2)
	v_pk_fma_f32 v[96:97], v[82:83], v[96:97], v[86:87]
	v_pk_fma_f32 v[98:99], v[80:81], v[98:99], v[84:85]
	s_waitcnt vmcnt(1)
	v_pk_fma_f32 v[44:45], v[90:91], v[44:45], v[96:97]
	v_pk_fma_f32 v[96:97], v[88:89], v[46:47], v[98:99]
	s_waitcnt vmcnt(0)
	v_pk_fma_f32 v[46:47], v[74:75], v[94:95], v[44:45]
	v_pk_fma_f32 v[44:45], v[100:101], v[92:93], v[96:97]
	v_pk_mul_f32 v[42:43], v[42:43], v[70:71] op_sel_hi:[1,0]
	v_pk_mul_f32 v[40:41], v[40:41], v[70:71] op_sel_hi:[1,0]
	s_nop 1
	v_mov_b32_dpp v108, v40 row_ror:1 row_mask:0xf bank_mask:0xf
	v_mov_b32_dpp v109, v40 row_ror:2 row_mask:0xf bank_mask:0xf
	v_mov_b32_dpp v110, v41 row_ror:1 row_mask:0xf bank_mask:0xf
	v_mov_b32_dpp v111, v41 row_ror:2 row_mask:0xf bank_mask:0xf
	v_mov_b32_dpp v112, v42 row_ror:1 row_mask:0xf bank_mask:0xf
	v_mov_b32_dpp v113, v42 row_ror:2 row_mask:0xf bank_mask:0xf
	v_mov_b32_dpp v114, v43 row_ror:1 row_mask:0xf bank_mask:0xf
	v_mov_b32_dpp v115, v43 row_ror:2 row_mask:0xf bank_mask:0xf
	v_cndmask_b32_e64 v100, v69, v109, s[8:9]
	v_cndmask_b32_e64 v98, v105, v113, s[8:9]
	v_cndmask_b32_e64 v99, v107, v115, s[8:9]
	v_cndmask_b32_e64 v101, v103, v111, s[8:9]
	v_cndmask_b32_e64 v74, v104, v112, s[6:7]
	v_cndmask_b32_e64 v75, v106, v114, s[6:7]
	v_cndmask_b32_e64 v96, v65, v108, s[6:7]
	v_cndmask_b32_e64 v97, v102, v110, s[6:7]
	v_pk_fma_f32 v[98:99], v[82:83], v[98:99], v[86:87]
	v_pk_fma_f32 v[100:101], v[80:81], v[100:101], v[84:85]
	v_pk_fma_f32 v[74:75], v[90:91], v[74:75], v[98:99]
	v_pk_fma_f32 v[96:97], v[88:89], v[96:97], v[100:101]
	v_pk_fma_f32 v[42:43], v[42:43], v[94:95], v[74:75]
	v_pk_fma_f32 v[40:41], v[40:41], v[92:93], v[96:97]
	v_pk_mul_f32 v[38:39], v[38:39], v[64:65] op_sel_hi:[1,0]
	v_pk_mul_f32 v[36:37], v[36:37], v[64:65] op_sel_hi:[1,0]
	s_nop 1
	v_mov_b32_dpp v65, v36 row_ror:1 row_mask:0xf bank_mask:0xf
	v_mov_b32_dpp v69, v36 row_ror:2 row_mask:0xf bank_mask:0xf
	v_mov_b32_dpp v102, v37 row_ror:1 row_mask:0xf bank_mask:0xf
	v_mov_b32_dpp v103, v37 row_ror:2 row_mask:0xf bank_mask:0xf
	v_mov_b32_dpp v104, v38 row_ror:1 row_mask:0xf bank_mask:0xf
	v_mov_b32_dpp v105, v38 row_ror:2 row_mask:0xf bank_mask:0xf
	v_mov_b32_dpp v106, v39 row_ror:1 row_mask:0xf bank_mask:0xf
	v_mov_b32_dpp v107, v39 row_ror:2 row_mask:0xf bank_mask:0xf
	v_cndmask_b32_e64 v100, v109, v69, s[8:9]
	v_cndmask_b32_e64 v98, v113, v105, s[8:9]
	v_cndmask_b32_e64 v99, v115, v107, s[8:9]
	v_cndmask_b32_e64 v101, v111, v103, s[8:9]
	v_cndmask_b32_e64 v74, v112, v104, s[6:7]
	v_cndmask_b32_e64 v75, v114, v106, s[6:7]
	v_cndmask_b32_e64 v96, v108, v65, s[6:7]
	v_cndmask_b32_e64 v97, v110, v102, s[6:7]
	v_pk_fma_f32 v[98:99], v[82:83], v[98:99], v[86:87]
	v_pk_fma_f32 v[100:101], v[80:81], v[100:101], v[84:85]
	v_pk_fma_f32 v[74:75], v[90:91], v[74:75], v[98:99]
	v_pk_fma_f32 v[96:97], v[88:89], v[96:97], v[100:101]
	v_pk_fma_f32 v[38:39], v[38:39], v[94:95], v[74:75]
	v_pk_fma_f32 v[36:37], v[36:37], v[92:93], v[96:97]
	v_pk_mul_f32 v[34:35], v[34:35], v[72:73] op_sel_hi:[1,0]
	v_pk_mul_f32 v[32:33], v[32:33], v[72:73] op_sel_hi:[1,0]
	s_nop 1
	v_mov_b32_dpp v96, v32 row_ror:1 row_mask:0xf bank_mask:0xf
	v_mov_b32_dpp v100, v32 row_ror:2 row_mask:0xf bank_mask:0xf
	v_mov_b32_dpp v97, v33 row_ror:1 row_mask:0xf bank_mask:0xf
	v_mov_b32_dpp v101, v33 row_ror:2 row_mask:0xf bank_mask:0xf
	v_mov_b32_dpp v74, v34 row_ror:1 row_mask:0xf bank_mask:0xf
	v_mov_b32_dpp v98, v34 row_ror:2 row_mask:0xf bank_mask:0xf
	v_mov_b32_dpp v75, v35 row_ror:1 row_mask:0xf bank_mask:0xf
	v_mov_b32_dpp v99, v35 row_ror:2 row_mask:0xf bank_mask:0xf
	v_cndmask_b32_e64 v100, v69, v100, s[8:9]
	v_cndmask_b32_e64 v98, v105, v98, s[8:9]
	v_cndmask_b32_e64 v99, v107, v99, s[8:9]
	v_cndmask_b32_e64 v101, v103, v101, s[8:9]
	v_cndmask_b32_e64 v74, v104, v74, s[6:7]
	v_cndmask_b32_e64 v75, v106, v75, s[6:7]
	v_cndmask_b32_e64 v96, v65, v96, s[6:7]
	v_cndmask_b32_e64 v97, v102, v97, s[6:7]
	v_pk_fma_f32 v[82:83], v[82:83], v[98:99], v[86:87]
	v_pk_fma_f32 v[80:81], v[80:81], v[100:101], v[84:85]
	v_pk_fma_f32 v[74:75], v[90:91], v[74:75], v[82:83]
	v_pk_fma_f32 v[80:81], v[88:89], v[96:97], v[80:81]
	v_pk_fma_f32 v[34:35], v[34:35], v[94:95], v[74:75]
	v_pk_fma_f32 v[32:33], v[32:33], v[92:93], v[80:81]
	s_nop 0
	global_load_dwordx4 v[80:83], v[176:177], off
	global_load_dwordx4 v[84:87], v[138:139], off
	global_load_dwordx4 v[88:91], v[140:141], off
	global_load_dwordx4 v[92:95], v[142:143], off
	v_pk_mul_f32 v[74:75], v[30:31], v[68:69] op_sel_hi:[1,0]
	v_pk_mul_f32 v[100:101], v[28:29], v[68:69] op_sel_hi:[1,0]
	ds_read_b128 v[28:31], v71 offset:512
	ds_read_b128 v[96:99], v73 offset:512
	s_nop 1
	v_mov_b32_dpp v65, v100 row_ror:1 row_mask:0xf bank_mask:0xf
	v_mov_b32_dpp v69, v100 row_ror:2 row_mask:0xf bank_mask:0xf
	v_mov_b32_dpp v102, v101 row_ror:1 row_mask:0xf bank_mask:0xf
	s_waitcnt lgkmcnt(1)
; #define PG8_LAS __attribute__((address_space(3)))
; __device__ __forceinline__ float dpp_ror1(float x) { float r; asm volatile("s_nop 1\n\tv_mov_b32_dpp %0, %1 row_ror:1 row_mask:0xf bank_mask:0xf" : "=&v"(r) : "v"(x)); return r; }
; __device__ __forceinline__ float dpp_ror2(float x) { float r; asm volatile("s_nop 1\n\tv_mov_b32_dpp %0, %1 row_ror:2 row_mask:0xf bank_mask:0xf" : "=&v"(r) : "v"(x)); return r; }
;     __device__ __forceinline__ void operator()(f32x4 (&acc)[2][2][4][2], const Unit& u, int wr, int wc, int fr_, int fq_) const {
;     ...
;                     const f32x4 w0 = *(const f32x4*)(cw + cidx), w1 = *(const f32x4*)(cw + 11264 + cidx), w2 = *(const f32x4*)(cw + 22528 + cidx), b4 = *(const f32x4*)(cb + cidx);
;                     f32x4 pR1 = (f32x4){0.f, 0.f, 0.f, 0.f}, pR2 = pR1;
;                     if (blk) { const f32x4 h14 = *(const PG8_LAS f32x4*)(hal + ((blk - 1) * 2 + 0) * 256 + ct) * rs14, h15 = *(const PG8_LAS f32x4*)(hal + ((blk - 1) * 2 + 1) * 256 + ct) * rs15;
;                         pR1 = h15; pR2 = (fr == 0) ? h14 : h15; }
; #pragma unroll
;                     for (int m = 0; m < 4; ++m) {
;                         const f32x4 U = acc[ai][bj][m][n] * rsr[m];
;                         f32x4 R1, R2;
; #pragma unroll
;                         for (int i = 0; i < 4; ++i) { R1[i] = dpp_ror1(U[i]); R2[i] = dpp_ror2(U[i]); }
;                         const f32x4 U1 = (fr >= 1) ? R1 : pR1, U2 = (fr >= 2) ? R2 : pR2;
;                         const f32x4 C = b4 + w0 * U2 + w1 * U1 + w2 * U;
;                         acc[ai][bj][m][n] = C; pR1 = R1; pR2 = R2;
	v_pk_mul_f32 v[30:31], v[66:67], v[30:31] op_sel_hi:[0,1]
	v_pk_mul_f32 v[28:29], v[66:67], v[28:29] op_sel_hi:[0,1]
	s_waitcnt lgkmcnt(0)
	v_pk_mul_f32 v[98:99], v[66:67], v[98:99] op_sel:[1,0]
	v_pk_mul_f32 v[96:97], v[66:67], v[96:97] op_sel:[1,0]
	v_cndmask_b32_e64 v108, v99, v31, s[10:11]
	v_cndmask_b32_e64 v109, v98, v30, s[10:11]
	v_cndmask_b32_e64 v110, v96, v28, s[10:11]
	v_cndmask_b32_e64 v111, v97, v29, s[10:11]
	s_nop 1
	v_mov_b32_dpp v103, v101 row_ror:2 row_mask:0xf bank_mask:0xf
	v_mov_b32_dpp v104, v74 row_ror:1 row_mask:0xf bank_mask:0xf
	v_mov_b32_dpp v105, v74 row_ror:2 row_mask:0xf bank_mask:0xf
	v_mov_b32_dpp v106, v75 row_ror:1 row_mask:0xf bank_mask:0xf
	v_mov_b32_dpp v107, v75 row_ror:2 row_mask:0xf bank_mask:0xf
	v_cndmask_b32_e64 v31, v97, v102, s[6:7]
	v_cndmask_b32_e64 v28, v98, v104, s[6:7]
	v_cndmask_b32_e64 v29, v99, v106, s[6:7]
	v_cndmask_b32_e64 v30, v96, v65, s[6:7]
	v_cndmask_b32_e64 v96, v109, v105, s[8:9]
	v_cndmask_b32_e64 v97, v108, v107, s[8:9]
	v_cndmask_b32_e64 v99, v111, v103, s[8:9]
	v_cndmask_b32_e64 v98, v110, v69, s[8:9]
	s_waitcnt vmcnt(2)
	v_pk_fma_f32 v[96:97], v[86:87], v[96:97], v[82:83]
	v_pk_fma_f32 v[98:99], v[84:85], v[98:99], v[80:81]
	s_waitcnt vmcnt(1)
	v_pk_fma_f32 v[28:29], v[90:91], v[28:29], v[96:97]
	v_pk_fma_f32 v[96:97], v[88:89], v[30:31], v[98:99]
	s_waitcnt vmcnt(0)
	v_pk_fma_f32 v[30:31], v[74:75], v[94:95], v[28:29]
	v_pk_fma_f32 v[28:29], v[100:101], v[92:93], v[96:97]
	v_pk_mul_f32 v[26:27], v[26:27], v[70:71] op_sel_hi:[1,0]
	v_pk_mul_f32 v[24:25], v[24:25], v[70:71] op_sel_hi:[1,0]
	s_nop 1
	v_mov_b32_dpp v108, v24 row_ror:1 row_mask:0xf bank_mask:0xf
	v_mov_b32_dpp v109, v24 row_ror:2 row_mask:0xf bank_mask:0xf
	v_mov_b32_dpp v110, v25 row_ror:1 row_mask:0xf bank_mask:0xf
	v_mov_b32_dpp v111, v25 row_ror:2 row_mask:0xf bank_mask:0xf
	v_mov_b32_dpp v112, v26 row_ror:1 row_mask:0xf bank_mask:0xf
	v_mov_b32_dpp v113, v26 row_ror:2 row_mask:0xf bank_mask:0xf
	v_mov_b32_dpp v114, v27 row_ror:1 row_mask:0xf bank_mask:0xf
	v_mov_b32_dpp v115, v27 row_ror:2 row_mask:0xf bank_mask:0xf
	v_cndmask_b32_e64 v100, v69, v109, s[8:9]
	v_cndmask_b32_e64 v98, v105, v113, s[8:9]
	v_cndmask_b32_e64 v99, v107, v115, s[8:9]
	v_cndmask_b32_e64 v101, v103, v111, s[8:9]
	v_cndmask_b32_e64 v74, v104, v112, s[6:7]
	v_cndmask_b32_e64 v75, v106, v114, s[6:7]
	v_cndmask_b32_e64 v96, v65, v108, s[6:7]
	v_cndmask_b32_e64 v97, v102, v110, s[6:7]
	v_pk_fma_f32 v[98:99], v[86:87], v[98:99], v[82:83]
	v_pk_fma_f32 v[100:101], v[84:85], v[100:101], v[80:81]
	v_pk_fma_f32 v[74:75], v[90:91], v[74:75], v[98:99]
	v_pk_fma_f32 v[96:97], v[88:89], v[96:97], v[100:101]
	v_pk_fma_f32 v[26:27], v[26:27], v[94:95], v[74:75]
	v_pk_fma_f32 v[24:25], v[24:25], v[92:93], v[96:97]
	v_pk_mul_f32 v[22:23], v[22:23], v[64:65] op_sel_hi:[1,0]
	v_pk_mul_f32 v[20:21], v[20:21], v[64:65] op_sel_hi:[1,0]
	s_nop 1
	v_mov_b32_dpp v65, v20 row_ror:1 row_mask:0xf bank_mask:0xf
	v_mov_b32_dpp v69, v20 row_ror:2 row_mask:0xf bank_mask:0xf
	v_mov_b32_dpp v102, v21 row_ror:1 row_mask:0xf bank_mask:0xf
	v_mov_b32_dpp v103, v21 row_ror:2 row_mask:0xf bank_mask:0xf
	v_mov_b32_dpp v104, v22 row_ror:1 row_mask:0xf bank_mask:0xf
	v_mov_b32_dpp v105, v22 row_ror:2 row_mask:0xf bank_mask:0xf
	v_mov_b32_dpp v106, v23 row_ror:1 row_mask:0xf bank_mask:0xf
	v_mov_b32_dpp v107, v23 row_ror:2 row_mask:0xf bank_mask:0xf
	v_cndmask_b32_e64 v100, v109, v69, s[8:9]
	v_cndmask_b32_e64 v98, v113, v105, s[8:9]
	v_cndmask_b32_e64 v99, v115, v107, s[8:9]
	v_cndmask_b32_e64 v101, v111, v103, s[8:9]
	v_cndmask_b32_e64 v74, v112, v104, s[6:7]
	v_cndmask_b32_e64 v75, v114, v106, s[6:7]
	v_cndmask_b32_e64 v96, v108, v65, s[6:7]
	v_cndmask_b32_e64 v97, v110, v102, s[6:7]
	v_pk_fma_f32 v[98:99], v[86:87], v[98:99], v[82:83]
	v_pk_fma_f32 v[100:101], v[84:85], v[100:101], v[80:81]
	v_pk_fma_f32 v[74:75], v[90:91], v[74:75], v[98:99]
	v_pk_fma_f32 v[96:97], v[88:89], v[96:97], v[100:101]
	v_pk_fma_f32 v[22:23], v[22:23], v[94:95], v[74:75]
	v_pk_fma_f32 v[20:21], v[20:21], v[92:93], v[96:97]
	v_pk_mul_f32 v[18:19], v[18:19], v[72:73] op_sel_hi:[1,0]
	v_pk_mul_f32 v[16:17], v[16:17], v[72:73] op_sel_hi:[1,0]
	s_nop 1
	v_mov_b32_dpp v96, v16 row_ror:1 row_mask:0xf bank_mask:0xf
	v_mov_b32_dpp v100, v16 row_ror:2 row_mask:0xf bank_mask:0xf
	v_mov_b32_dpp v97, v17 row_ror:1 row_mask:0xf bank_mask:0xf
	v_mov_b32_dpp v101, v17 row_ror:2 row_mask:0xf bank_mask:0xf
	v_mov_b32_dpp v74, v18 row_ror:1 row_mask:0xf bank_mask:0xf
	v_mov_b32_dpp v98, v18 row_ror:2 row_mask:0xf bank_mask:0xf
	v_mov_b32_dpp v75, v19 row_ror:1 row_mask:0xf bank_mask:0xf
	v_mov_b32_dpp v99, v19 row_ror:2 row_mask:0xf bank_mask:0xf
	v_cndmask_b32_e64 v100, v69, v100, s[8:9]
	v_cndmask_b32_e64 v98, v105, v98, s[8:9]
	v_cndmask_b32_e64 v99, v107, v99, s[8:9]
	v_cndmask_b32_e64 v101, v103, v101, s[8:9]
	v_cndmask_b32_e64 v74, v104, v74, s[6:7]
	v_cndmask_b32_e64 v75, v106, v75, s[6:7]
	v_cndmask_b32_e64 v96, v65, v96, s[6:7]
	v_cndmask_b32_e64 v97, v102, v97, s[6:7]
	v_pk_fma_f32 v[82:83], v[86:87], v[98:99], v[82:83]
	v_pk_fma_f32 v[80:81], v[84:85], v[100:101], v[80:81]
	v_pk_fma_f32 v[74:75], v[90:91], v[74:75], v[82:83]
	v_pk_fma_f32 v[80:81], v[88:89], v[96:97], v[80:81]
	v_pk_fma_f32 v[18:19], v[18:19], v[94:95], v[74:75]
	v_pk_fma_f32 v[16:17], v[16:17], v[92:93], v[80:81]
	s_nop 0
	global_load_dwordx4 v[80:83], v[136:137], off
	global_load_dwordx4 v[84:87], v[130:131], off
	global_load_dwordx4 v[88:91], v[132:133], off
	global_load_dwordx4 v[92:95], v[134:135], off
	v_pk_mul_f32 v[74:75], v[14:15], v[68:69] op_sel_hi:[1,0]
	v_pk_mul_f32 v[68:69], v[12:13], v[68:69] op_sel_hi:[1,0]
	ds_read_b128 v[12:15], v71 offset:528
	ds_read_b128 v[96:99], v73 offset:528
	s_nop 1
	v_mov_b32_dpp v65, v68 row_ror:1 row_mask:0xf bank_mask:0xf
	v_mov_b32_dpp v73, v68 row_ror:2 row_mask:0xf bank_mask:0xf
	v_mov_b32_dpp v71, v69 row_ror:1 row_mask:0xf bank_mask:0xf
	s_waitcnt lgkmcnt(1)
; #define PG8_LAS __attribute__((address_space(3)))
; __device__ __forceinline__ float dpp_ror1(float x) { float r; asm volatile("s_nop 1\n\tv_mov_b32_dpp %0, %1 row_ror:1 row_mask:0xf bank_mask:0xf" : "=&v"(r) : "v"(x)); return r; }
; __device__ __forceinline__ float dpp_ror2(float x) { float r; asm volatile("s_nop 1\n\tv_mov_b32_dpp %0, %1 row_ror:2 row_mask:0xf bank_mask:0xf" : "=&v"(r) : "v"(x)); return r; }
; __device__ __forceinline__ f32x2 gelu_pk(f32x2 v) {
;     const f32x2 av = __builtin_elementwise_abs(v), d = av * 0.2316418882f + 1.0f;
;     f32x2 t; t.x = __builtin_amdgcn_rcpf(d.x); t.y = __builtin_amdgcn_rcpf(d.y);
;     f32x2 q = t * 0.5307027145f + (-0.7265760135f); q = q * t + 0.7107068705f; q = q * t + (-0.142248368f); q = q * t + 0.127414796f; q = q * t;
;     const f32x2 s = (v * v) * (-0.72134752044f);
;     f32x2 e; e.x = __builtin_amdgcn_exp2f(s.x); e.y = __builtin_amdgcn_exp2f(s.y);
;     const f32x2 m = v * (q * e), r = v - m;
;     f32x2 o; o.x = v.x < 0.f ? m.x : r.x; o.y = v.y < 0.f ? m.y : r.y; return o;
;     __device__ __forceinline__ void operator()(f32x4 (&acc)[2][2][4][2], const Unit& u, int wr, int wc, int fr_, int fq_) const {
;     ...
;                     const f32x4 w0 = *(const f32x4*)(cw + cidx), w1 = *(const f32x4*)(cw + 11264 + cidx), w2 = *(const f32x4*)(cw + 22528 + cidx), b4 = *(const f32x4*)(cb + cidx);
;                     f32x4 pR1 = (f32x4){0.f, 0.f, 0.f, 0.f}, pR2 = pR1;
;                     if (blk) { const f32x4 h14 = *(const PG8_LAS f32x4*)(hal + ((blk - 1) * 2 + 0) * 256 + ct) * rs14, h15 = *(const PG8_LAS f32x4*)(hal + ((blk - 1) * 2 + 1) * 256 + ct) * rs15;
;                         pR1 = h15; pR2 = (fr == 0) ? h14 : h15; }
; #pragma unroll
;                     for (int m = 0; m < 4; ++m) {
;                         const f32x4 U = acc[ai][bj][m][n] * rsr[m];
;                         f32x4 R1, R2;
; #pragma unroll
;                         for (int i = 0; i < 4; ++i) { R1[i] = dpp_ror1(U[i]); R2[i] = dpp_ror2(U[i]); }
;                         const f32x4 U1 = (fr >= 1) ? R1 : pR1, U2 = (fr >= 2) ? R2 : pR2;
;                         const f32x4 C = b4 + w0 * U2 + w1 * U1 + w2 * U;
;                         acc[ai][bj][m][n] = C; pR1 = R1; pR2 = R2;
	v_pk_mul_f32 v[14:15], v[66:67], v[14:15] op_sel_hi:[0,1]
	v_pk_mul_f32 v[12:13], v[66:67], v[12:13] op_sel_hi:[0,1]
	s_waitcnt lgkmcnt(0)
	v_pk_mul_f32 v[98:99], v[66:67], v[98:99] op_sel:[1,0]
	v_pk_mul_f32 v[66:67], v[66:67], v[96:97] op_sel:[1,0]
	v_cndmask_b32_e64 v96, v99, v15, s[10:11]
	v_cndmask_b32_e64 v97, v98, v14, s[10:11]
	v_cndmask_b32_e64 v105, v66, v12, s[10:11]
	v_cndmask_b32_e64 v106, v67, v13, s[10:11]
	s_nop 1
	v_mov_b32_dpp v100, v69 row_ror:2 row_mask:0xf bank_mask:0xf
	v_mov_b32_dpp v101, v74 row_ror:1 row_mask:0xf bank_mask:0xf
	v_mov_b32_dpp v102, v74 row_ror:2 row_mask:0xf bank_mask:0xf
	v_mov_b32_dpp v103, v75 row_ror:1 row_mask:0xf bank_mask:0xf
	v_mov_b32_dpp v104, v75 row_ror:2 row_mask:0xf bank_mask:0xf
	v_cndmask_b32_e64 v15, v67, v71, s[6:7]
	v_cndmask_b32_e64 v14, v66, v65, s[6:7]
	v_cndmask_b32_e64 v66, v97, v102, s[8:9]
	v_cndmask_b32_e64 v67, v96, v104, s[8:9]
	v_cndmask_b32_e64 v97, v106, v100, s[8:9]
	v_cndmask_b32_e64 v96, v105, v73, s[8:9]
	v_cndmask_b32_e64 v12, v98, v101, s[6:7]
	v_cndmask_b32_e64 v13, v99, v103, s[6:7]
	s_waitcnt vmcnt(2)
	v_pk_fma_f32 v[66:67], v[86:87], v[66:67], v[82:83]
	v_pk_fma_f32 v[96:97], v[84:85], v[96:97], v[80:81]
	s_waitcnt vmcnt(1)
	v_pk_fma_f32 v[12:13], v[90:91], v[12:13], v[66:67]
	v_pk_fma_f32 v[66:67], v[88:89], v[14:15], v[96:97]
	s_waitcnt vmcnt(0)
	v_pk_fma_f32 v[14:15], v[74:75], v[94:95], v[12:13]
	v_pk_fma_f32 v[12:13], v[68:69], v[92:93], v[66:67]
	v_pk_mul_f32 v[10:11], v[10:11], v[70:71] op_sel_hi:[1,0]
	v_pk_mul_f32 v[8:9], v[8:9], v[70:71] op_sel_hi:[1,0]
	s_nop 1
	v_mov_b32_dpp v96, v8 row_ror:1 row_mask:0xf bank_mask:0xf
	v_mov_b32_dpp v97, v8 row_ror:2 row_mask:0xf bank_mask:0xf
	v_mov_b32_dpp v98, v9 row_ror:1 row_mask:0xf bank_mask:0xf
	v_mov_b32_dpp v99, v9 row_ror:2 row_mask:0xf bank_mask:0xf
	v_mov_b32_dpp v105, v10 row_ror:1 row_mask:0xf bank_mask:0xf
	v_mov_b32_dpp v106, v10 row_ror:2 row_mask:0xf bank_mask:0xf
	v_mov_b32_dpp v107, v11 row_ror:1 row_mask:0xf bank_mask:0xf
	v_mov_b32_dpp v108, v11 row_ror:2 row_mask:0xf bank_mask:0xf
	v_cndmask_b32_e64 v69, v71, v98, s[6:7]
	v_cndmask_b32_e64 v70, v102, v106, s[8:9]
	v_cndmask_b32_e64 v71, v104, v108, s[8:9]
	v_cndmask_b32_e64 v74, v73, v97, s[8:9]
	v_cndmask_b32_e64 v75, v100, v99, s[8:9]
	v_cndmask_b32_e64 v66, v101, v105, s[6:7]
	v_cndmask_b32_e64 v67, v103, v107, s[6:7]
	v_cndmask_b32_e64 v68, v65, v96, s[6:7]
	v_pk_fma_f32 v[70:71], v[86:87], v[70:71], v[82:83]
	v_pk_fma_f32 v[74:75], v[84:85], v[74:75], v[80:81]
	v_pk_fma_f32 v[66:67], v[90:91], v[66:67], v[70:71]
	v_pk_fma_f32 v[68:69], v[88:89], v[68:69], v[74:75]
	v_pk_fma_f32 v[10:11], v[10:11], v[94:95], v[66:67]
	v_pk_fma_f32 v[8:9], v[8:9], v[92:93], v[68:69]
	v_pk_mul_f32 v[6:7], v[6:7], v[64:65] op_sel_hi:[1,0]
	v_pk_mul_f32 v[4:5], v[4:5], v[64:65] op_sel_hi:[1,0]
	s_nop 1
	v_mov_b32_dpp v73, v4 row_ror:1 row_mask:0xf bank_mask:0xf
	v_mov_b32_dpp v74, v4 row_ror:2 row_mask:0xf bank_mask:0xf
	v_mov_b32_dpp v75, v5 row_ror:1 row_mask:0xf bank_mask:0xf
	v_mov_b32_dpp v100, v5 row_ror:2 row_mask:0xf bank_mask:0xf
	v_mov_b32_dpp v101, v6 row_ror:1 row_mask:0xf bank_mask:0xf
	v_mov_b32_dpp v102, v6 row_ror:2 row_mask:0xf bank_mask:0xf
	v_mov_b32_dpp v103, v7 row_ror:1 row_mask:0xf bank_mask:0xf
	v_mov_b32_dpp v104, v7 row_ror:2 row_mask:0xf bank_mask:0xf
	v_cndmask_b32_e64 v70, v97, v74, s[8:9]
	v_cndmask_b32_e64 v68, v106, v102, s[8:9]
	v_cndmask_b32_e64 v69, v108, v104, s[8:9]
	v_cndmask_b32_e64 v71, v99, v100, s[8:9]
	v_cndmask_b32_e64 v64, v105, v101, s[6:7]
	v_cndmask_b32_e64 v65, v107, v103, s[6:7]
	v_cndmask_b32_e64 v66, v96, v73, s[6:7]
	v_cndmask_b32_e64 v67, v98, v75, s[6:7]
	v_pk_fma_f32 v[68:69], v[86:87], v[68:69], v[82:83]
	v_pk_fma_f32 v[70:71], v[84:85], v[70:71], v[80:81]
	v_pk_fma_f32 v[64:65], v[90:91], v[64:65], v[68:69]
	v_pk_fma_f32 v[66:67], v[88:89], v[66:67], v[70:71]
	v_pk_fma_f32 v[6:7], v[6:7], v[94:95], v[64:65]
	v_pk_fma_f32 v[4:5], v[4:5], v[92:93], v[66:67]
	v_pk_mul_f32 v[2:3], v[2:3], v[72:73] op_sel_hi:[1,0]
	v_pk_mul_f32 v[0:1], v[0:1], v[72:73] op_sel_hi:[1,0]
	s_nop 1
	v_mov_b32_dpp v66, v0 row_ror:1 row_mask:0xf bank_mask:0xf
	v_mov_b32_dpp v70, v0 row_ror:2 row_mask:0xf bank_mask:0xf
	v_mov_b32_dpp v67, v1 row_ror:1 row_mask:0xf bank_mask:0xf
	v_mov_b32_dpp v71, v1 row_ror:2 row_mask:0xf bank_mask:0xf
	v_mov_b32_dpp v64, v2 row_ror:1 row_mask:0xf bank_mask:0xf
	v_mov_b32_dpp v68, v2 row_ror:2 row_mask:0xf bank_mask:0xf
	v_mov_b32_dpp v65, v3 row_ror:1 row_mask:0xf bank_mask:0xf
	v_mov_b32_dpp v69, v3 row_ror:2 row_mask:0xf bank_mask:0xf
	v_cndmask_b32_e64 v70, v74, v70, s[8:9]
	v_cndmask_b32_e64 v68, v102, v68, s[8:9]
	v_cndmask_b32_e64 v69, v104, v69, s[8:9]
	v_cndmask_b32_e64 v71, v100, v71, s[8:9]
	v_cndmask_b32_e64 v64, v101, v64, s[6:7]
	v_cndmask_b32_e64 v65, v103, v65, s[6:7]
	v_cndmask_b32_e64 v66, v73, v66, s[6:7]
	v_cndmask_b32_e64 v67, v75, v67, s[6:7]
	v_pk_fma_f32 v[68:69], v[86:87], v[68:69], v[82:83]
	v_pk_fma_f32 v[70:71], v[84:85], v[70:71], v[80:81]
	v_pk_fma_f32 v[64:65], v[90:91], v[64:65], v[68:69]
	v_pk_fma_f32 v[66:67], v[88:89], v[66:67], v[70:71]
	v_pk_fma_f32 v[2:3], v[2:3], v[94:95], v[64:65]
	v_pk_fma_f32 v[0:1], v[0:1], v[92:93], v[66:67]
	v_fma_f32 v66, |v60|, s58, 1.0
	v_fma_f32 v67, |v61|, s58, 1.0
	v_pk_mul_f32 v[70:71], v[60:61], v[60:61]
	v_rcp_f32_e32 v66, v66
	v_rcp_f32_e32 v67, v67
	v_pk_mul_f32 v[70:71], v[70:71], s[50:51] op_sel_hi:[1,0]
	v_exp_f32_e32 v70, v70
	v_pk_fma_f32 v[68:69], v[66:67], s[60:61], v[128:129] op_sel_hi:[1,0,0]
	v_exp_f32_e32 v71, v71
	v_pk_fma_f32 v[68:69], v[66:67], v[68:69], s[62:63] op_sel_hi:[1,1,0]
	v_readlane_b32 s0, v244, 59
; __device__ __forceinline__ u32x4 pack8(f32x4 v0, f32x4 v1) { u32x4 w; w.x = cvt_pk_bf16(v0[0], v0[1]); w.y = cvt_pk_bf16(v0[2], v0[3]); w.z = cvt_pk_bf16(v1[0], v1[1]); w.w = cvt_pk_bf16(v1[2], v1[3]); return w; }
; __device__ __forceinline__ f32x4 gelu4(f32x4 v) { f32x2 a = gelu_pk((f32x2){v[0], v[1]}), b = gelu_pk((f32x2){v[2], v[3]}); return (f32x4){a.x, a.y, b.x, b.y}; }
; __device__ __forceinline__ f32x2 gelu_pk(f32x2 v) {
;     const f32x2 av = __builtin_elementwise_abs(v), d = av * 0.2316418882f + 1.0f;
;     f32x2 t; t.x = __builtin_amdgcn_rcpf(d.x); t.y = __builtin_amdgcn_rcpf(d.y);
;     f32x2 q = t * 0.5307027145f + (-0.7265760135f); q = q * t + 0.7107068705f; q = q * t + (-0.142248368f); q = q * t + 0.127414796f; q = q * t;
;     const f32x2 s = (v * v) * (-0.72134752044f);
;     f32x2 e; e.x = __builtin_amdgcn_exp2f(s.x); e.y = __builtin_amdgcn_exp2f(s.y);
;     const f32x2 m = v * (q * e), r = v - m;
;     f32x2 o; o.x = v.x < 0.f ? m.x : r.x; o.y = v.y < 0.f ? m.y : r.y; return o;
;     __device__ __forceinline__ void operator()(f32x4 (&acc)[2][2][4][2], const Unit& u, int wr, int wc, int fr_, int fq_) const {
;     ...
;             for (int m = 0; m < 4; ++m) { const int row = u.pm * BM + blk * 64 + m * 16 + fr;
;                 const f32x4 g0 = gelu4(acc[ai][0][m][0]), g1 = gelu4(acc[ai][0][m][1]);
;                 *(u32x4*)(ACT + (size_t)row * 5632 + jcol) = pack8(g0 * acc[ai][1][m][0], g1 * acc[ai][1][m][1]); asm volatile("" ::: "memory"); __builtin_amdgcn_sched_barrier(0); }
	v_pk_fma_f32 v[68:69], v[66:67], v[68:69], s[64:65] op_sel_hi:[1,1,0]
	s_nop 0
	v_pk_fma_f32 v[68:69], v[66:67], v[68:69], s[66:67] op_sel_hi:[1,1,0]
	v_add_u32_e32 v64, s0, v178
	v_pk_mul_f32 v[66:67], v[66:67], v[68:69]
	v_pk_mul_f32 v[68:69], v[62:63], v[62:63]
	v_pk_mul_f32 v[66:67], v[70:71], v[66:67]
	v_pk_mul_f32 v[68:69], v[68:69], s[50:51] op_sel_hi:[1,0]
	v_max_f32_e32 v70, 0, v60
	v_max_f32_e32 v71, 0, v61
	v_exp_f32_e32 v68, v68
	v_fma_f32 v60, -|v60|, v66, v70
	v_fma_f32 v61, -|v61|, v67, v71
	v_exp_f32_e32 v69, v69
	v_fma_f32 v66, |v62|, s58, 1.0
	v_fma_f32 v67, |v63|, s58, 1.0
	v_rcp_f32_e32 v66, v66
	v_rcp_f32_e32 v67, v67
	v_pk_mul_f32 v[28:29], v[60:61], v[28:29]
	v_pk_fma_f32 v[70:71], v[66:67], s[60:61], v[128:129] op_sel_hi:[1,0,0]
	v_pk_fma_f32 v[70:71], v[66:67], v[70:71], s[62:63] op_sel_hi:[1,1,0]
	v_pk_fma_f32 v[70:71], v[66:67], v[70:71], s[64:65] op_sel_hi:[1,1,0]
	v_pk_fma_f32 v[70:71], v[66:67], v[70:71], s[66:67] op_sel_hi:[1,1,0]
	v_pk_mul_f32 v[66:67], v[66:67], v[70:71]
	v_pk_mul_f32 v[70:71], v[44:45], v[44:45]
	v_pk_mul_f32 v[66:67], v[68:69], v[66:67]
	v_pk_mul_f32 v[70:71], v[70:71], s[50:51] op_sel_hi:[1,0]
	v_max_f32_e32 v68, 0, v62
	v_max_f32_e32 v69, 0, v63
	v_exp_f32_e32 v70, v70
	v_fma_f32 v62, -|v62|, v66, v68
	v_fma_f32 v63, -|v63|, v67, v69
	v_exp_f32_e32 v71, v71
	v_fma_f32 v66, |v44|, s58, 1.0
	v_fma_f32 v67, |v45|, s58, 1.0
	v_rcp_f32_e32 v66, v66
	v_rcp_f32_e32 v67, v67
	v_pk_mul_f32 v[30:31], v[62:63], v[30:31]
	v_pk_fma_f32 v[68:69], v[66:67], s[60:61], v[128:129] op_sel_hi:[1,0,0]
	v_pk_fma_f32 v[68:69], v[66:67], v[68:69], s[62:63] op_sel_hi:[1,1,0]
	v_pk_fma_f32 v[68:69], v[66:67], v[68:69], s[64:65] op_sel_hi:[1,1,0]
	v_pk_fma_f32 v[68:69], v[66:67], v[68:69], s[66:67] op_sel_hi:[1,1,0]
	v_pk_mul_f32 v[66:67], v[66:67], v[68:69]
	v_pk_mul_f32 v[68:69], v[46:47], v[46:47]
	v_pk_mul_f32 v[66:67], v[70:71], v[66:67]
	v_pk_mul_f32 v[68:69], v[68:69], s[50:51] op_sel_hi:[1,0]
	v_max_f32_e32 v70, 0, v44
	v_max_f32_e32 v71, 0, v45
	v_exp_f32_e32 v68, v68
	v_fma_f32 v44, -|v44|, v66, v70
	v_fma_f32 v45, -|v45|, v67, v71
	v_exp_f32_e32 v69, v69
	v_fma_f32 v66, |v46|, s58, 1.0
	v_fma_f32 v67, |v47|, s58, 1.0
	v_rcp_f32_e32 v66, v66
	v_rcp_f32_e32 v67, v67
	s_nop 0
	v_pk_fma_f32 v[70:71], v[66:67], s[60:61], v[128:129] op_sel_hi:[1,0,0]
	v_pk_fma_f32 v[70:71], v[66:67], v[70:71], s[62:63] op_sel_hi:[1,1,0]
	v_pk_fma_f32 v[70:71], v[66:67], v[70:71], s[64:65] op_sel_hi:[1,1,0]
	v_pk_fma_f32 v[70:71], v[66:67], v[70:71], s[66:67] op_sel_hi:[1,1,0]
	v_pk_mul_f32 v[66:67], v[66:67], v[70:71]
	v_pk_mul_f32 v[66:67], v[68:69], v[66:67]
	v_max_f32_e32 v68, 0, v46
	v_max_f32_e32 v69, 0, v47
	v_fma_f32 v46, -|v46|, v66, v68
	v_fma_f32 v47, -|v47|, v67, v69
	s_nop 1
	v_pk_mul_f32 v[46:47], v[46:47], v[14:15]
	v_pk_mul_f32 v[14:15], v[44:45], v[12:13]
	v_cvt_pk_bf16_f32 v12, v28, v29
	v_mad_i64_i32 v[28:29], s[0:1], v64, s93, v[76:77]
	v_cvt_pk_bf16_f32 v13, v30, v31
	v_cvt_pk_bf16_f32 v14, v14, v15
	v_cvt_pk_bf16_f32 v15, v46, v47
	v_lshl_add_u64 v[28:29], v[28:29], 0, v[78:79]
	global_store_dwordx4 v[28:29], v[12:15], off
	s_nop 1
	v_fma_f32 v12, |v56|, s58, 1.0
	v_fma_f32 v13, |v57|, s58, 1.0
	v_pk_mul_f32 v[28:29], v[56:57], v[56:57]
	v_rcp_f32_e32 v12, v12
	v_rcp_f32_e32 v13, v13
	v_pk_mul_f32 v[28:29], v[28:29], s[50:51] op_sel_hi:[1,0]
	v_exp_f32_e32 v28, v28
	v_pk_fma_f32 v[14:15], v[12:13], s[60:61], v[128:129] op_sel_hi:[1,0,0]
	v_exp_f32_e32 v29, v29
	v_pk_fma_f32 v[14:15], v[12:13], v[14:15], s[62:63] op_sel_hi:[1,1,0]
	v_pk_mul_f32 v[44:45], v[40:41], v[40:41]
	v_pk_fma_f32 v[14:15], v[12:13], v[14:15], s[64:65] op_sel_hi:[1,1,0]
	v_pk_mul_f32 v[44:45], v[44:45], s[50:51] op_sel_hi:[1,0]
	v_pk_fma_f32 v[14:15], v[12:13], v[14:15], s[66:67] op_sel_hi:[1,1,0]
	v_exp_f32_e32 v44, v44
	v_pk_mul_f32 v[12:13], v[12:13], v[14:15]
	v_pk_mul_f32 v[14:15], v[58:59], v[58:59]
	v_pk_mul_f32 v[12:13], v[28:29], v[12:13]
	v_pk_mul_f32 v[14:15], v[14:15], s[50:51] op_sel_hi:[1,0]
	v_max_f32_e32 v28, 0, v56
	v_max_f32_e32 v29, 0, v57
	v_exp_f32_e32 v14, v14
	v_fma_f32 v12, -|v56|, v12, v28
	v_fma_f32 v13, -|v57|, v13, v29
	v_exp_f32_e32 v15, v15
	v_fma_f32 v28, |v58|, s58, 1.0
	v_fma_f32 v29, |v59|, s58, 1.0
	v_rcp_f32_e32 v28, v28
	v_rcp_f32_e32 v29, v29
	v_exp_f32_e32 v45, v45
	v_add_u32_e32 v46, 16, v64
	v_pk_mul_f32 v[12:13], v[12:13], v[24:25]
	v_pk_fma_f32 v[30:31], v[28:29], s[60:61], v[128:129] op_sel_hi:[1,0,0]
	v_pk_fma_f32 v[30:31], v[28:29], v[30:31], s[62:63] op_sel_hi:[1,1,0]
	v_pk_fma_f32 v[30:31], v[28:29], v[30:31], s[64:65] op_sel_hi:[1,1,0]
	v_pk_fma_f32 v[30:31], v[28:29], v[30:31], s[66:67] op_sel_hi:[1,1,0]
	v_pk_mul_f32 v[28:29], v[28:29], v[30:31]
	v_pk_mul_f32 v[14:15], v[14:15], v[28:29]
	v_max_f32_e32 v28, 0, v58
	v_max_f32_e32 v29, 0, v59
	v_fma_f32 v14, -|v58|, v14, v28
	v_fma_f32 v15, -|v59|, v15, v29
	s_nop 0
	v_fma_f32 v28, |v40|, s58, 1.0
	v_fma_f32 v29, |v41|, s58, 1.0
	v_rcp_f32_e32 v28, v28
	v_rcp_f32_e32 v29, v29
	v_pk_mul_f32 v[14:15], v[14:15], v[26:27]
	v_pk_fma_f32 v[30:31], v[28:29], s[60:61], v[128:129] op_sel_hi:[1,0,0]
	v_pk_fma_f32 v[30:31], v[28:29], v[30:31], s[62:63] op_sel_hi:[1,1,0]
	v_pk_fma_f32 v[30:31], v[28:29], v[30:31], s[64:65] op_sel_hi:[1,1,0]
	v_pk_fma_f32 v[30:31], v[28:29], v[30:31], s[66:67] op_sel_hi:[1,1,0]
	v_pk_mul_f32 v[28:29], v[28:29], v[30:31]
	v_pk_mul_f32 v[30:31], v[42:43], v[42:43]
	v_pk_mul_f32 v[28:29], v[44:45], v[28:29]
	v_pk_mul_f32 v[30:31], v[30:31], s[50:51] op_sel_hi:[1,0]
	v_max_f32_e32 v44, 0, v40
	v_max_f32_e32 v45, 0, v41
	v_fma_f32 v28, -|v40|, v28, v44
	v_fma_f32 v29, -|v41|, v29, v45
	v_fma_f32 v40, |v42|, s58, 1.0
; __device__ __forceinline__ u32x4 pack8(f32x4 v0, f32x4 v1) { u32x4 w; w.x = cvt_pk_bf16(v0[0], v0[1]); w.y = cvt_pk_bf16(v0[2], v0[3]); w.z = cvt_pk_bf16(v1[0], v1[1]); w.w = cvt_pk_bf16(v1[2], v1[3]); return w; }
; __device__ __forceinline__ f32x4 gelu4(f32x4 v) { f32x2 a = gelu_pk((f32x2){v[0], v[1]}), b = gelu_pk((f32x2){v[2], v[3]}); return (f32x4){a.x, a.y, b.x, b.y}; }
; __device__ __forceinline__ f32x2 gelu_pk(f32x2 v) {
;     const f32x2 av = __builtin_elementwise_abs(v), d = av * 0.2316418882f + 1.0f;
;     f32x2 t; t.x = __builtin_amdgcn_rcpf(d.x); t.y = __builtin_amdgcn_rcpf(d.y);
;     f32x2 q = t * 0.5307027145f + (-0.7265760135f); q = q * t + 0.7107068705f; q = q * t + (-0.142248368f); q = q * t + 0.127414796f; q = q * t;
;     const f32x2 s = (v * v) * (-0.72134752044f);
;     f32x2 e; e.x = __builtin_amdgcn_exp2f(s.x); e.y = __builtin_amdgcn_exp2f(s.y);
;     const f32x2 m = v * (q * e), r = v - m;
;     f32x2 o; o.x = v.x < 0.f ? m.x : r.x; o.y = v.y < 0.f ? m.y : r.y; return o;
;     __device__ __forceinline__ void operator()(f32x4 (&acc)[2][2][4][2], const Unit& u, int wr, int wc, int fr_, int fq_) const {
;     ...
;             for (int m = 0; m < 4; ++m) { const int row = u.pm * BM + blk * 64 + m * 16 + fr;
;                 const f32x4 g0 = gelu4(acc[ai][0][m][0]), g1 = gelu4(acc[ai][0][m][1]);
;                 *(u32x4*)(ACT + (size_t)row * 5632 + jcol) = pack8(g0 * acc[ai][1][m][0], g1 * acc[ai][1][m][1]); asm volatile("" ::: "memory"); __builtin_amdgcn_sched_barrier(0); }
	v_fma_f32 v41, |v43|, s58, 1.0
	v_rcp_f32_e32 v40, v40
	v_rcp_f32_e32 v41, v41
	v_exp_f32_e32 v30, v30
	v_exp_f32_e32 v31, v31
	v_pk_fma_f32 v[44:45], v[40:41], s[60:61], v[128:129] op_sel_hi:[1,0,0]
	s_nop 0
	v_pk_fma_f32 v[44:45], v[40:41], v[44:45], s[62:63] op_sel_hi:[1,1,0]
	s_nop 0
	v_pk_fma_f32 v[44:45], v[40:41], v[44:45], s[64:65] op_sel_hi:[1,1,0]
	v_pk_fma_f32 v[44:45], v[40:41], v[44:45], s[66:67] op_sel_hi:[1,1,0]
	v_pk_mul_f32 v[40:41], v[40:41], v[44:45]
	v_pk_mul_f32 v[30:31], v[30:31], v[40:41]
	v_max_f32_e32 v40, 0, v42
	v_max_f32_e32 v41, 0, v43
	v_fma_f32 v30, -|v42|, v30, v40
	v_fma_f32 v31, -|v43|, v31, v41
	s_nop 1
	v_pk_mul_f32 v[24:25], v[30:31], v[10:11]
	v_pk_mul_f32 v[10:11], v[28:29], v[8:9]
	v_cvt_pk_bf16_f32 v8, v12, v13
	v_mad_i64_i32 v[12:13], s[0:1], v46, s93, v[76:77]
	v_cvt_pk_bf16_f32 v9, v14, v15
	v_cvt_pk_bf16_f32 v10, v10, v11
	v_cvt_pk_bf16_f32 v11, v24, v25
	v_lshl_add_u64 v[12:13], v[12:13], 0, v[78:79]
	global_store_dwordx4 v[12:13], v[8:11], off
	s_nop 1
	v_fma_f32 v8, |v52|, s58, 1.0
	v_fma_f32 v9, |v53|, s58, 1.0
	v_pk_mul_f32 v[12:13], v[52:53], v[52:53]
	v_rcp_f32_e32 v8, v8
	v_rcp_f32_e32 v9, v9
	v_pk_mul_f32 v[12:13], v[12:13], s[50:51] op_sel_hi:[1,0]
	v_exp_f32_e32 v12, v12
	v_pk_fma_f32 v[10:11], v[8:9], s[60:61], v[128:129] op_sel_hi:[1,0,0]
	v_exp_f32_e32 v13, v13
	v_pk_fma_f32 v[10:11], v[8:9], v[10:11], s[62:63] op_sel_hi:[1,1,0]
	v_pk_mul_f32 v[24:25], v[36:37], v[36:37]
	v_pk_fma_f32 v[10:11], v[8:9], v[10:11], s[64:65] op_sel_hi:[1,1,0]
	v_pk_mul_f32 v[24:25], v[24:25], s[50:51] op_sel_hi:[1,0]
	v_pk_fma_f32 v[10:11], v[8:9], v[10:11], s[66:67] op_sel_hi:[1,1,0]
	v_exp_f32_e32 v24, v24
	v_pk_mul_f32 v[8:9], v[8:9], v[10:11]
	v_pk_mul_f32 v[10:11], v[54:55], v[54:55]
	v_pk_mul_f32 v[8:9], v[12:13], v[8:9]
	v_pk_mul_f32 v[10:11], v[10:11], s[50:51] op_sel_hi:[1,0]
	v_max_f32_e32 v12, 0, v52
	v_max_f32_e32 v13, 0, v53
	v_exp_f32_e32 v10, v10
	v_fma_f32 v8, -|v52|, v8, v12
	v_fma_f32 v9, -|v53|, v9, v13
	v_exp_f32_e32 v11, v11
	v_fma_f32 v12, |v54|, s58, 1.0
	v_fma_f32 v13, |v55|, s58, 1.0
	v_rcp_f32_e32 v12, v12
	v_rcp_f32_e32 v13, v13
	v_exp_f32_e32 v25, v25
	v_add_u32_e32 v28, 32, v64
	v_pk_mul_f32 v[8:9], v[8:9], v[20:21]
	v_pk_fma_f32 v[14:15], v[12:13], s[60:61], v[128:129] op_sel_hi:[1,0,0]
	v_pk_fma_f32 v[14:15], v[12:13], v[14:15], s[62:63] op_sel_hi:[1,1,0]
	v_pk_fma_f32 v[14:15], v[12:13], v[14:15], s[64:65] op_sel_hi:[1,1,0]
	v_pk_fma_f32 v[14:15], v[12:13], v[14:15], s[66:67] op_sel_hi:[1,1,0]
	v_pk_mul_f32 v[12:13], v[12:13], v[14:15]
	v_pk_mul_f32 v[10:11], v[10:11], v[12:13]
	v_max_f32_e32 v12, 0, v54
	v_max_f32_e32 v13, 0, v55
	v_fma_f32 v10, -|v54|, v10, v12
	v_fma_f32 v11, -|v55|, v11, v13
	s_nop 0
	v_fma_f32 v12, |v36|, s58, 1.0
	v_fma_f32 v13, |v37|, s58, 1.0
	v_rcp_f32_e32 v12, v12
	v_rcp_f32_e32 v13, v13
	v_pk_mul_f32 v[10:11], v[10:11], v[22:23]
	v_pk_fma_f32 v[14:15], v[12:13], s[60:61], v[128:129] op_sel_hi:[1,0,0]
	v_pk_fma_f32 v[14:15], v[12:13], v[14:15], s[62:63] op_sel_hi:[1,1,0]
	v_pk_fma_f32 v[14:15], v[12:13], v[14:15], s[64:65] op_sel_hi:[1,1,0]
	v_pk_fma_f32 v[14:15], v[12:13], v[14:15], s[66:67] op_sel_hi:[1,1,0]
	v_pk_mul_f32 v[12:13], v[12:13], v[14:15]
	v_pk_mul_f32 v[14:15], v[38:39], v[38:39]
	v_pk_mul_f32 v[12:13], v[24:25], v[12:13]
	v_pk_mul_f32 v[14:15], v[14:15], s[50:51] op_sel_hi:[1,0]
	v_max_f32_e32 v24, 0, v36
	v_max_f32_e32 v25, 0, v37
	v_exp_f32_e32 v14, v14
	v_fma_f32 v12, -|v36|, v12, v24
	v_fma_f32 v13, -|v37|, v13, v25
	v_exp_f32_e32 v15, v15
	v_fma_f32 v24, |v38|, s58, 1.0
	v_fma_f32 v25, |v39|, s58, 1.0
	v_rcp_f32_e32 v24, v24
	v_rcp_f32_e32 v25, v25
	s_nop 0
	v_pk_fma_f32 v[26:27], v[24:25], s[60:61], v[128:129] op_sel_hi:[1,0,0]
	v_pk_fma_f32 v[26:27], v[24:25], v[26:27], s[62:63] op_sel_hi:[1,1,0]
	v_pk_fma_f32 v[26:27], v[24:25], v[26:27], s[64:65] op_sel_hi:[1,1,0]
	v_pk_fma_f32 v[26:27], v[24:25], v[26:27], s[66:67] op_sel_hi:[1,1,0]
	v_pk_mul_f32 v[24:25], v[24:25], v[26:27]
	v_pk_mul_f32 v[14:15], v[14:15], v[24:25]
; __device__ __forceinline__ u32x4 pack8(f32x4 v0, f32x4 v1) { u32x4 w; w.x = cvt_pk_bf16(v0[0], v0[1]); w.y = cvt_pk_bf16(v0[2], v0[3]); w.z = cvt_pk_bf16(v1[0], v1[1]); w.w = cvt_pk_bf16(v1[2], v1[3]); return w; }
; __device__ __forceinline__ f32x4 gelu4(f32x4 v) { f32x2 a = gelu_pk((f32x2){v[0], v[1]}), b = gelu_pk((f32x2){v[2], v[3]}); return (f32x4){a.x, a.y, b.x, b.y}; }
; __device__ __forceinline__ f32x2 gelu_pk(f32x2 v) {
;     const f32x2 av = __builtin_elementwise_abs(v), d = av * 0.2316418882f + 1.0f;
;     f32x2 t; t.x = __builtin_amdgcn_rcpf(d.x); t.y = __builtin_amdgcn_rcpf(d.y);
;     f32x2 q = t * 0.5307027145f + (-0.7265760135f); q = q * t + 0.7107068705f; q = q * t + (-0.142248368f); q = q * t + 0.127414796f; q = q * t;
;     const f32x2 s = (v * v) * (-0.72134752044f);
;     f32x2 e; e.x = __builtin_amdgcn_exp2f(s.x); e.y = __builtin_amdgcn_exp2f(s.y);
;     const f32x2 m = v * (q * e), r = v - m;
;     f32x2 o; o.x = v.x < 0.f ? m.x : r.x; o.y = v.y < 0.f ? m.y : r.y; return o;
;     __device__ __forceinline__ void operator()(f32x4 (&acc)[2][2][4][2], const Unit& u, int wr, int wc, int fr_, int fq_) const {
;     ...
;             for (int m = 0; m < 4; ++m) { const int row = u.pm * BM + blk * 64 + m * 16 + fr;
;                 const f32x4 g0 = gelu4(acc[ai][0][m][0]), g1 = gelu4(acc[ai][0][m][1]);
;                 *(u32x4*)(ACT + (size_t)row * 5632 + jcol) = pack8(g0 * acc[ai][1][m][0], g1 * acc[ai][1][m][1]); asm volatile("" ::: "memory"); __builtin_amdgcn_sched_barrier(0); }
	v_max_f32_e32 v24, 0, v38
	v_max_f32_e32 v25, 0, v39
	v_fma_f32 v14, -|v38|, v14, v24
	v_fma_f32 v15, -|v39|, v15, v25
	s_nop 1
	v_pk_mul_f32 v[14:15], v[14:15], v[6:7]
	v_pk_mul_f32 v[6:7], v[12:13], v[4:5]
	v_cvt_pk_bf16_f32 v4, v8, v9
	v_mad_i64_i32 v[8:9], s[0:1], v28, s93, v[76:77]
	v_cvt_pk_bf16_f32 v5, v10, v11
	v_cvt_pk_bf16_f32 v6, v6, v7
	v_cvt_pk_bf16_f32 v7, v14, v15
	v_lshl_add_u64 v[8:9], v[8:9], 0, v[78:79]
	global_store_dwordx4 v[8:9], v[4:7], off
	s_nop 1
	v_fma_f32 v4, |v48|, s58, 1.0
	v_fma_f32 v5, |v49|, s58, 1.0
	v_pk_mul_f32 v[8:9], v[48:49], v[48:49]
	v_rcp_f32_e32 v4, v4
	v_rcp_f32_e32 v5, v5
	v_pk_mul_f32 v[8:9], v[8:9], s[50:51] op_sel_hi:[1,0]
	v_exp_f32_e32 v8, v8
	v_pk_fma_f32 v[6:7], v[4:5], s[60:61], v[128:129] op_sel_hi:[1,0,0]
	v_exp_f32_e32 v9, v9
	v_pk_fma_f32 v[6:7], v[4:5], v[6:7], s[62:63] op_sel_hi:[1,1,0]
	v_pk_mul_f32 v[12:13], v[32:33], v[32:33]
	v_pk_fma_f32 v[6:7], v[4:5], v[6:7], s[64:65] op_sel_hi:[1,1,0]
	v_pk_mul_f32 v[12:13], v[12:13], s[50:51] op_sel_hi:[1,0]
	v_pk_fma_f32 v[6:7], v[4:5], v[6:7], s[66:67] op_sel_hi:[1,1,0]
	v_exp_f32_e32 v12, v12
	v_pk_mul_f32 v[4:5], v[4:5], v[6:7]
	v_pk_mul_f32 v[6:7], v[50:51], v[50:51]
	v_pk_mul_f32 v[4:5], v[8:9], v[4:5]
	v_pk_mul_f32 v[6:7], v[6:7], s[50:51] op_sel_hi:[1,0]
	v_max_f32_e32 v8, 0, v48
	v_max_f32_e32 v9, 0, v49
	v_exp_f32_e32 v6, v6
	v_fma_f32 v4, -|v48|, v4, v8
	v_fma_f32 v5, -|v49|, v5, v9
	v_exp_f32_e32 v7, v7
	v_fma_f32 v8, |v50|, s58, 1.0
	v_fma_f32 v9, |v51|, s58, 1.0
	v_rcp_f32_e32 v8, v8
	v_rcp_f32_e32 v9, v9
	v_exp_f32_e32 v13, v13
	v_add_u32_e32 v20, 48, v64
	v_pk_mul_f32 v[4:5], v[4:5], v[16:17]
	v_pk_fma_f32 v[10:11], v[8:9], s[60:61], v[128:129] op_sel_hi:[1,0,0]
	v_pk_fma_f32 v[10:11], v[8:9], v[10:11], s[62:63] op_sel_hi:[1,1,0]
	v_pk_fma_f32 v[10:11], v[8:9], v[10:11], s[64:65] op_sel_hi:[1,1,0]
	v_pk_fma_f32 v[10:11], v[8:9], v[10:11], s[66:67] op_sel_hi:[1,1,0]
	v_pk_mul_f32 v[8:9], v[8:9], v[10:11]
	v_pk_mul_f32 v[6:7], v[6:7], v[8:9]
	v_max_f32_e32 v8, 0, v50
	v_max_f32_e32 v9, 0, v51
	v_fma_f32 v6, -|v50|, v6, v8
	v_fma_f32 v7, -|v51|, v7, v9
	s_nop 0
	v_fma_f32 v8, |v32|, s58, 1.0
	v_fma_f32 v9, |v33|, s58, 1.0
	v_rcp_f32_e32 v8, v8
	v_rcp_f32_e32 v9, v9
	v_pk_mul_f32 v[6:7], v[6:7], v[18:19]
	v_pk_fma_f32 v[10:11], v[8:9], s[60:61], v[128:129] op_sel_hi:[1,0,0]
	v_pk_fma_f32 v[10:11], v[8:9], v[10:11], s[62:63] op_sel_hi:[1,1,0]
	v_pk_fma_f32 v[10:11], v[8:9], v[10:11], s[64:65] op_sel_hi:[1,1,0]
	v_pk_fma_f32 v[10:11], v[8:9], v[10:11], s[66:67] op_sel_hi:[1,1,0]
	v_pk_mul_f32 v[8:9], v[8:9], v[10:11]
	v_pk_mul_f32 v[10:11], v[34:35], v[34:35]
	v_pk_mul_f32 v[8:9], v[12:13], v[8:9]
	v_pk_mul_f32 v[10:11], v[10:11], s[50:51] op_sel_hi:[1,0]
	v_max_f32_e32 v12, 0, v32
	v_max_f32_e32 v13, 0, v33
	v_exp_f32_e32 v10, v10
	v_fma_f32 v8, -|v32|, v8, v12
	v_fma_f32 v9, -|v33|, v9, v13
	v_exp_f32_e32 v11, v11
	v_fma_f32 v12, |v34|, s58, 1.0
	v_fma_f32 v13, |v35|, s58, 1.0
	v_rcp_f32_e32 v12, v12
	v_rcp_f32_e32 v13, v13
	s_nop 0
	v_pk_fma_f32 v[14:15], v[12:13], s[60:61], v[128:129] op_sel_hi:[1,0,0]
	v_pk_fma_f32 v[14:15], v[12:13], v[14:15], s[62:63] op_sel_hi:[1,1,0]
	v_pk_fma_f32 v[14:15], v[12:13], v[14:15], s[64:65] op_sel_hi:[1,1,0]
	v_pk_fma_f32 v[14:15], v[12:13], v[14:15], s[66:67] op_sel_hi:[1,1,0]
	v_pk_mul_f32 v[12:13], v[12:13], v[14:15]
	v_pk_mul_f32 v[10:11], v[10:11], v[12:13]
	v_max_f32_e32 v12, 0, v34
	v_max_f32_e32 v13, 0, v35
	v_fma_f32 v10, -|v34|, v10, v12
	v_fma_f32 v11, -|v35|, v11, v13
	s_nop 1
	v_pk_mul_f32 v[10:11], v[10:11], v[2:3]
	v_pk_mul_f32 v[2:3], v[8:9], v[0:1]
	v_cvt_pk_bf16_f32 v0, v4, v5
	v_mad_i64_i32 v[4:5], s[0:1], v20, s93, v[76:77]
	v_cvt_pk_bf16_f32 v1, v6, v7
	v_cvt_pk_bf16_f32 v2, v2, v3
	v_cvt_pk_bf16_f32 v3, v10, v11
	v_lshl_add_u64 v[4:5], v[4:5], 0, v[78:79]
	global_store_dwordx4 v[4:5], v[0:3], off
	s_andn2_b64 vcc, exec, s[4:5]
	s_mov_b64 s[0:1], -1
	s_cbranch_vccnz .LBB0_1697
	s_andn2_b64 vcc, exec, s[18:19]
	s_cbranch_vccnz .LBB0_1696
	s_barrier
	s_branch .LBB0_1696
